# all nine GEMM K-loop heads placed at address = 128 mod 256 (as the GU loop already was), downstream code phases preserved
# baseline (speedup 1.0000x reference)
; template <class Epi>
; __device__ __forceinline__ void gemm_phase(LAS unsigned char* lds, const Gemm g, const Epi& E) {
;     ...
;         if (!has_next) break;
; #pragma unroll
;         for (int a = 0; a < 2; ++a)
; #pragma unroll
;             for (int b = 0; b < 2; ++b)
; #pragma unroll
;                 for (int m = 0; m < 4; ++m)
; #pragma unroll
;                     for (int n = 0; n < 2; ++n) acc[a][b][m][n] = (f32x4){0.f, 0.f, 0.f, 0.f};
;         cur = nxt; cA = nA; cB = nB; ++ui;
.LBB0_158:
	v_mov_b32_e32 v129, 0
	s_andn2_b64 vcc, exec, s[44:45]
	v_mov_b32_e32 v128, 0
	v_mov_b32_e32 v127, 0
	v_mov_b32_e32 v126, 0
	v_mov_b32_e32 v125, 0
	v_mov_b32_e32 v124, 0
	v_mov_b32_e32 v123, 0
	v_mov_b32_e32 v122, 0
	v_mov_b32_e32 v103, 0
	v_mov_b32_e32 v102, 0
	v_mov_b32_e32 v105, 0
	v_mov_b32_e32 v104, 0
	v_mov_b32_e32 v111, 0
	v_mov_b32_e32 v110, 0
	v_mov_b32_e32 v113, 0
	v_mov_b32_e32 v112, 0
	v_mov_b32_e32 v87, 0
	v_mov_b32_e32 v86, 0
	v_mov_b32_e32 v89, 0
	v_mov_b32_e32 v88, 0
	v_mov_b32_e32 v95, 0
	v_mov_b32_e32 v94, 0
	v_mov_b32_e32 v97, 0
	v_mov_b32_e32 v96, 0
	v_mov_b32_e32 v75, 0
	v_mov_b32_e32 v74, 0
	v_mov_b32_e32 v77, 0
	v_mov_b32_e32 v76, 0
	v_mov_b32_e32 v79, 0
	v_mov_b32_e32 v78, 0
	v_mov_b32_e32 v81, 0
	v_mov_b32_e32 v80, 0
	v_mov_b32_e32 v143, 0
	v_mov_b32_e32 v142, 0
	v_mov_b32_e32 v145, 0
	v_mov_b32_e32 v144, 0
	v_mov_b32_e32 v147, 0
	v_mov_b32_e32 v146, 0
	v_mov_b32_e32 v149, 0
	v_mov_b32_e32 v148, 0
	v_mov_b32_e32 v115, 0
	v_mov_b32_e32 v114, 0
	v_mov_b32_e32 v117, 0
	v_mov_b32_e32 v116, 0
	v_mov_b32_e32 v119, 0
	v_mov_b32_e32 v118, 0
	v_mov_b32_e32 v121, 0
	v_mov_b32_e32 v120, 0
	v_mov_b32_e32 v99, 0
	v_mov_b32_e32 v98, 0
	v_mov_b32_e32 v101, 0
	v_mov_b32_e32 v100, 0
	v_mov_b32_e32 v107, 0
	v_mov_b32_e32 v106, 0
	v_mov_b32_e32 v109, 0
	v_mov_b32_e32 v108, 0
	v_mov_b32_e32 v73, 0
	v_mov_b32_e32 v72, 0
	v_mov_b32_e32 v71, 0
	v_mov_b32_e32 v70, 0
	v_mov_b32_e32 v69, 0
	v_mov_b32_e32 v68, 0
	v_mov_b32_e32 v67, 0
	v_mov_b32_e32 v66, 0
	v_mov_b32_e32 v65, 0
	v_mov_b32_e32 v64, 0
	v_mov_b32_e32 v63, 0
	v_mov_b32_e32 v62, 0
	v_mov_b32_e32 v61, 0
	v_mov_b32_e32 v60, 0
	v_mov_b32_e32 v59, 0
	v_mov_b32_e32 v58, 0
	v_mov_b32_e32 v39, 0
	v_mov_b32_e32 v38, 0
	v_mov_b32_e32 v41, 0
	v_mov_b32_e32 v40, 0
	v_mov_b32_e32 v47, 0
	v_mov_b32_e32 v46, 0
	v_mov_b32_e32 v49, 0
	v_mov_b32_e32 v48, 0
	v_mov_b32_e32 v23, 0
	v_mov_b32_e32 v22, 0
	v_mov_b32_e32 v25, 0
	v_mov_b32_e32 v24, 0
	v_mov_b32_e32 v31, 0
	v_mov_b32_e32 v30, 0
	v_mov_b32_e32 v33, 0
	v_mov_b32_e32 v32, 0
	v_mov_b32_e32 v9, 0
	v_mov_b32_e32 v8, 0
	v_mov_b32_e32 v11, 0
	v_mov_b32_e32 v10, 0
	v_mov_b32_e32 v15, 0
	v_mov_b32_e32 v14, 0
	v_mov_b32_e32 v17, 0
	v_mov_b32_e32 v16, 0
	v_mov_b32_e32 v83, 0
	v_mov_b32_e32 v82, 0
	v_mov_b32_e32 v85, 0
	v_mov_b32_e32 v84, 0
	v_mov_b32_e32 v91, 0
	v_mov_b32_e32 v90, 0
	v_mov_b32_e32 v93, 0
	v_mov_b32_e32 v92, 0
	v_mov_b32_e32 v51, 0
	v_mov_b32_e32 v50, 0
	v_mov_b32_e32 v53, 0
	v_mov_b32_e32 v52, 0
	v_mov_b32_e32 v55, 0
	v_mov_b32_e32 v54, 0
	v_mov_b32_e32 v57, 0
	v_mov_b32_e32 v56, 0
	v_mov_b32_e32 v35, 0
	v_mov_b32_e32 v34, 0
	v_mov_b32_e32 v37, 0
	v_mov_b32_e32 v36, 0
	v_mov_b32_e32 v43, 0
	v_mov_b32_e32 v42, 0
	v_mov_b32_e32 v45, 0
	v_mov_b32_e32 v44, 0
	v_mov_b32_e32 v7, 0
	v_mov_b32_e32 v6, 0
	v_mov_b32_e32 v5, 0
	v_mov_b32_e32 v4, 0
	v_mov_b32_e32 v3, 0
	v_mov_b32_e32 v2, 0
	v_mov_b32_e32 v1, 0
	v_mov_b32_e32 v0, 0
	s_cbranch_vccnz .LBB0_147
	s_add_u32 s46, s46, 0x80
	s_addc_u32 s47, s47, 0
	s_add_u32 s87, s48, 0x100
	v_mov_b32_e32 v0, 0
	s_addc_u32 s88, s49, 0
	s_mov_b32 s48, 0
	v_mov_b32_e32 v1, v0
	v_mov_b32_e32 v2, v0
	v_mov_b32_e32 v3, v0
	v_mov_b32_e32 v4, v0
	v_mov_b32_e32 v5, v0
	v_mov_b32_e32 v6, v0
	v_mov_b32_e32 v7, v0
	v_mov_b32_e32 v8, v0
	v_mov_b32_e32 v9, v0
	v_mov_b32_e32 v10, v0
	v_mov_b32_e32 v11, v0
	v_mov_b32_e32 v14, v0
	v_mov_b32_e32 v15, v0
	v_mov_b32_e32 v16, v0
	v_mov_b32_e32 v17, v0
	v_mov_b32_e32 v22, v0
	v_mov_b32_e32 v23, v0
	v_mov_b32_e32 v24, v0
	v_mov_b32_e32 v25, v0
	v_mov_b32_e32 v30, v0
	v_mov_b32_e32 v31, v0
	v_mov_b32_e32 v32, v0
	v_mov_b32_e32 v33, v0
	v_mov_b32_e32 v38, v0
	v_mov_b32_e32 v39, v0
	v_mov_b32_e32 v40, v0
	v_mov_b32_e32 v41, v0
	v_mov_b32_e32 v46, v0
	v_mov_b32_e32 v47, v0
	v_mov_b32_e32 v48, v0
	v_mov_b32_e32 v49, v0
	v_mov_b32_e32 v18, v0
	v_mov_b32_e32 v19, v0
	v_mov_b32_e32 v20, v0
	v_mov_b32_e32 v21, v0
	v_mov_b32_e32 v26, v0
	v_mov_b32_e32 v27, v0
	v_mov_b32_e32 v28, v0
	v_mov_b32_e32 v29, v0
	v_mov_b32_e32 v34, v0
	v_mov_b32_e32 v35, v0
	v_mov_b32_e32 v36, v0
	v_mov_b32_e32 v37, v0
	v_mov_b32_e32 v42, v0
	v_mov_b32_e32 v43, v0
	v_mov_b32_e32 v44, v0
	v_mov_b32_e32 v45, v0
	v_mov_b32_e32 v50, v0
	v_mov_b32_e32 v51, v0
	v_mov_b32_e32 v52, v0
	v_mov_b32_e32 v53, v0
	v_mov_b32_e32 v54, v0
	v_mov_b32_e32 v55, v0
	v_mov_b32_e32 v56, v0
	v_mov_b32_e32 v57, v0
	v_mov_b32_e32 v58, v0
	v_mov_b32_e32 v59, v0
	v_mov_b32_e32 v60, v0
	v_mov_b32_e32 v61, v0
	v_mov_b32_e32 v62, v0
	v_mov_b32_e32 v63, v0
	v_mov_b32_e32 v64, v0
	v_mov_b32_e32 v65, v0
	v_mov_b32_e32 v66, v0
	v_mov_b32_e32 v67, v0
	v_mov_b32_e32 v68, v0
	v_mov_b32_e32 v69, v0
	v_mov_b32_e32 v70, v0
	v_mov_b32_e32 v71, v0
	v_mov_b32_e32 v72, v0
	v_mov_b32_e32 v73, v0
	v_mov_b32_e32 v74, v0
	v_mov_b32_e32 v75, v0
	v_mov_b32_e32 v76, v0
	v_mov_b32_e32 v77, v0
	v_mov_b32_e32 v78, v0
	v_mov_b32_e32 v79, v0
	v_mov_b32_e32 v80, v0
	v_mov_b32_e32 v81, v0
	v_mov_b32_e32 v86, v0
	v_mov_b32_e32 v87, v0
	v_mov_b32_e32 v88, v0
	v_mov_b32_e32 v89, v0
	v_mov_b32_e32 v94, v0
	v_mov_b32_e32 v95, v0
	v_mov_b32_e32 v96, v0
	v_mov_b32_e32 v97, v0
	v_mov_b32_e32 v102, v0
	v_mov_b32_e32 v103, v0
	v_mov_b32_e32 v104, v0
	v_mov_b32_e32 v105, v0
	v_mov_b32_e32 v110, v0
	v_mov_b32_e32 v111, v0
	v_mov_b32_e32 v112, v0
	v_mov_b32_e32 v113, v0
	v_mov_b32_e32 v82, v0
	v_mov_b32_e32 v83, v0
	v_mov_b32_e32 v84, v0
	v_mov_b32_e32 v85, v0
	v_mov_b32_e32 v90, v0
	v_mov_b32_e32 v91, v0
	v_mov_b32_e32 v92, v0
	v_mov_b32_e32 v93, v0
	v_mov_b32_e32 v98, v0
	v_mov_b32_e32 v99, v0
	v_mov_b32_e32 v100, v0
	v_mov_b32_e32 v101, v0
	v_mov_b32_e32 v106, v0
	v_mov_b32_e32 v107, v0
	v_mov_b32_e32 v108, v0
	v_mov_b32_e32 v109, v0
	v_mov_b32_e32 v114, v0
	v_mov_b32_e32 v115, v0
	v_mov_b32_e32 v116, v0
	v_mov_b32_e32 v117, v0
	v_mov_b32_e32 v118, v0
	v_mov_b32_e32 v119, v0
	v_mov_b32_e32 v120, v0
	v_mov_b32_e32 v121, v0
	v_mov_b32_e32 v122, v0
	v_mov_b32_e32 v123, v0
	v_mov_b32_e32 v124, v0
	v_mov_b32_e32 v125, v0
	v_mov_b32_e32 v126, v0
	v_mov_b32_e32 v127, v0
	v_mov_b32_e32 v128, v0
	v_mov_b32_e32 v129, v0
	s_nop 0
	s_nop 0
	s_nop 0
; #define PG8_STAGE(bufoff, gbase, voff) do { _Pragma("unroll") for (int _i = 0; _i < 2; ++_i) \
;         __builtin_amdgcn_global_load_lds((const unsigned*)((const char*)(gbase) + (voff)[_i]), (LAS unsigned*)(lds + (bufoff) + ldsw + _i * 8192), 16, 0, 0); } while (0)
; #define PG8_LDA(dst, b, h) do { _Pragma("unroll") for (int m = 0; m < 4; ++m) _Pragma("unroll") for (int k = 0; k < 2; ++k) dst[m][k] = *(const LAS bf16x8*)(lds + PG8_SA(b, h) + aoff + m * 2048 + k * 1024); } while (0)
; #define PG8_LDB(dst, b, h) do { _Pragma("unroll") for (int n = 0; n < 2; ++n) _Pragma("unroll") for (int k = 0; k < 2; ++k) dst[n][k] = *(const LAS bf16x8*)(lds + PG8_SB(b, h) + boff + n * 2048 + k * 1024); } while (0)
; #define PG8_MMA(ai, bj, At, Bt) do { __builtin_amdgcn_s_setprio(1); _Pragma("unroll") for (int m = 0; m < 4; ++m) _Pragma("unroll") for (int n = 0; n < 2; ++n) _Pragma("unroll") for (int k = 0; k < 2; ++k) \
;         acc[ai][bj][m][n] = __builtin_amdgcn_mfma_f32_16x16x32_bf16(Bt[n][k], At[m][k], acc[ai][bj][m][n], 0, 0, 0); __builtin_amdgcn_s_setprio(0); } while (0)
; #define PG8_WAIT_V(n) asm volatile("s_waitcnt vmcnt(" #n ")" ::: "memory")
; #define PG8_WAIT_L(n) asm volatile("s_waitcnt lgkmcnt(" #n ")" ::: "memory")
; #define PG8_BAR __builtin_amdgcn_s_barrier()
; template <class Epi>
; __device__ __forceinline__ void gemm_phase(LAS unsigned char* lds, const Gemm g, const Epi& E) {
;     ...
;         for (int t = 0; t < nt; t += 2) {
;             const bool last = (t == nt - 2);
;             const char* a1 = cA + (size_t)(t + 1) * kstep;
;             const char* a2 = last ? nA : cA + (size_t)(t + 2) * kstep; const char* b2 = last ? nB : cB + (size_t)(t + 2) * kstep;
;             const char* a3 = a2 + kstep; const char* b3 = b2 + kstep;
;             PG8_LDB(B0, 0, 0); PG8_SCHED; PG8_LDA(At, 0, 0); PG8_STAGE(PG8_SA(1, 1), a1 + hstep, voffA);
;             PG8_WAIT_L(8); PG8_BAR; PG8_WAIT_L(0); PG8_MMA(0, 0, At, B0); PG8_BAR; PG8_SCHED;
;             PG8_LDB(B1, 0, 1); PG8_STAGE(PG8_SB(0, 0), b2, voffB);
;             PG8_BAR; PG8_WAIT_L(0); PG8_MMA(0, 1, At, B1); PG8_BAR;
;             PG8_LDA(At, 0, 1); PG8_STAGE(PG8_SA(0, 0), a2, voffA);
;             PG8_BAR; PG8_WAIT_L(0); PG8_MMA(1, 0, At, B0); PG8_BAR; PG8_SCHED;
;             PG8_STAGE(PG8_SB(0, 1), b2 + hstep, voffB);
;             PG8_WAIT_V(6); PG8_BAR; PG8_MMA(1, 1, At, B1); PG8_BAR;
.LBB0_160:
	s_add_i32 s89, s48, 2
	s_add_u32 s50, s46, 0x80
	s_addc_u32 s49, s47, 0
	s_add_i32 s90, 0, 0x10000
	v_add_u32_e32 v153, s90, v151
	ds_read_b128 v[142:145], v153
	ds_read_b128 v[146:149], v153 offset:1024
	ds_read_b128 v[154:157], v153 offset:2048
	ds_read_b128 v[158:161], v153 offset:3072
	s_cmp_eq_u32 s81, s48
	s_cselect_b32 s48, s0, s50
	s_cselect_b32 s49, s1, s49
	s_cselect_b32 s51, s39, s88
	s_cselect_b32 s50, s38, s87
	v_lshl_add_u64 v[186:187], s[46:47], 0, v[138:139]
	s_add_i32 m0, s55, 0xc000
	ds_read_b128 v[162:165], v152
	ds_read_b128 v[166:169], v152 offset:1024
	ds_read_b128 v[170:173], v152 offset:2048
	ds_read_b128 v[174:177], v152 offset:3072
	ds_read_b128 v[194:197], v152 offset:4096
	ds_read_b128 v[198:201], v152 offset:5120
	ds_read_b128 v[202:205], v152 offset:6144
	ds_read_b128 v[206:209], v152 offset:7168
	global_load_lds_dwordx4 v[186:187], off
	v_lshl_add_u64 v[186:187], s[46:47], 0, v[140:141]
	s_add_i32 m0, s55, 0xe000
	s_nop 0
	global_load_lds_dwordx4 v[186:187], off
	s_waitcnt lgkmcnt(8)
	s_barrier
	s_waitcnt lgkmcnt(0)
	s_setprio 1
	s_waitcnt lgkmcnt(0)
	v_mfma_f32_16x16x32_bf16 v[126:129], v[142:145], v[162:165], v[126:129]
	v_mfma_f32_16x16x32_bf16 v[122:125], v[154:157], v[162:165], v[122:125]
	v_mfma_f32_16x16x32_bf16 v[118:121], v[142:145], v[170:173], v[118:121]
	v_mfma_f32_16x16x32_bf16 v[114:117], v[154:157], v[170:173], v[114:117]
	v_mfma_f32_16x16x32_bf16 v[106:109], v[142:145], v[194:197], v[106:109]
	v_mfma_f32_16x16x32_bf16 v[98:101], v[154:157], v[194:197], v[98:101]
	v_mfma_f32_16x16x32_bf16 v[90:93], v[142:145], v[202:205], v[90:93]
	v_mfma_f32_16x16x32_bf16 v[82:85], v[154:157], v[202:205], v[82:85]
	v_mfma_f32_16x16x32_bf16 v[126:129], v[146:149], v[166:169], v[126:129]
	v_mfma_f32_16x16x32_bf16 v[122:125], v[158:161], v[166:169], v[122:125]
	v_mfma_f32_16x16x32_bf16 v[118:121], v[146:149], v[174:177], v[118:121]
	v_mfma_f32_16x16x32_bf16 v[114:117], v[158:161], v[174:177], v[114:117]
	v_mfma_f32_16x16x32_bf16 v[106:109], v[146:149], v[198:201], v[106:109]
	v_mfma_f32_16x16x32_bf16 v[98:101], v[158:161], v[198:201], v[98:101]
	v_mfma_f32_16x16x32_bf16 v[90:93], v[146:149], v[206:209], v[90:93]
	v_mfma_f32_16x16x32_bf16 v[82:85], v[158:161], v[206:209], v[82:85]
	s_setprio 0
	s_barrier
	s_add_i32 s91, 0, 0x14000
	s_add_i32 s90, s90, s54
	v_add_u32_e32 v153, s91, v151
	v_lshl_add_u64 v[186:187], s[50:51], 0, v[132:133]
	s_mov_b32 m0, s90
	ds_read_b128 v[210:213], v153
	ds_read_b128 v[220:223], v153 offset:1024
	ds_read_b128 v[224:227], v153 offset:2048
	ds_read_b128 v[228:231], v153 offset:3072
	global_load_lds_dwordx4 v[186:187], off
	v_lshl_add_u64 v[188:189], s[50:51], 0, v[136:137]
	s_add_i32 m0, s90, 0x2000
	s_nop 0
	global_load_lds_dwordx4 v[188:189], off
	s_barrier
	s_waitcnt lgkmcnt(0)
	s_setprio 1
	s_waitcnt lgkmcnt(0)
	v_mfma_f32_16x16x32_bf16 v[110:113], v[210:213], v[162:165], v[110:113]
	v_mfma_f32_16x16x32_bf16 v[102:105], v[224:227], v[162:165], v[102:105]
	v_mfma_f32_16x16x32_bf16 v[94:97], v[210:213], v[170:173], v[94:97]
	v_mfma_f32_16x16x32_bf16 v[86:89], v[224:227], v[170:173], v[86:89]
	v_mfma_f32_16x16x32_bf16 v[78:81], v[210:213], v[194:197], v[78:81]
	v_mfma_f32_16x16x32_bf16 v[74:77], v[224:227], v[194:197], v[74:77]
	v_mfma_f32_16x16x32_bf16 v[70:73], v[210:213], v[202:205], v[70:73]
	v_mfma_f32_16x16x32_bf16 v[66:69], v[224:227], v[202:205], v[66:69]
	v_mfma_f32_16x16x32_bf16 v[110:113], v[220:223], v[166:169], v[110:113]
	v_mfma_f32_16x16x32_bf16 v[102:105], v[228:231], v[166:169], v[102:105]
	v_mfma_f32_16x16x32_bf16 v[94:97], v[220:223], v[174:177], v[94:97]
	v_mfma_f32_16x16x32_bf16 v[86:89], v[228:231], v[174:177], v[86:89]
	v_mfma_f32_16x16x32_bf16 v[78:81], v[220:223], v[198:201], v[78:81]
	v_mfma_f32_16x16x32_bf16 v[74:77], v[228:231], v[198:201], v[74:77]
	v_mfma_f32_16x16x32_bf16 v[70:73], v[220:223], v[206:209], v[70:73]
	v_mfma_f32_16x16x32_bf16 v[66:69], v[228:231], v[206:209], v[66:69]
	s_setprio 0
	s_mov_b32 m0, s55
	v_lshl_add_u64 v[232:233], s[48:49], 0, v[130:131]
	s_barrier
	ds_read_b128 v[162:165], v152 offset:16384
	ds_read_b128 v[166:169], v152 offset:17408
	ds_read_b128 v[170:173], v152 offset:18432
	ds_read_b128 v[174:177], v152 offset:19456
	ds_read_b128 v[194:197], v152 offset:20480
	ds_read_b128 v[198:201], v152 offset:21504
	ds_read_b128 v[202:205], v152 offset:22528
	ds_read_b128 v[206:209], v152 offset:23552
	global_load_lds_dwordx4 v[232:233], off
	v_lshl_add_u64 v[234:235], s[48:49], 0, v[134:135]
	s_mov_b32 m0, s56
	s_nop 0
	global_load_lds_dwordx4 v[234:235], off
	s_barrier
	s_waitcnt lgkmcnt(0)
	s_setprio 1
	s_waitcnt lgkmcnt(0)
	v_mfma_f32_16x16x32_bf16 v[62:65], v[142:145], v[162:165], v[62:65]
	v_mfma_f32_16x16x32_bf16 v[58:61], v[154:157], v[162:165], v[58:61]
	v_mfma_f32_16x16x32_bf16 v[54:57], v[142:145], v[170:173], v[54:57]
	v_mfma_f32_16x16x32_bf16 v[50:53], v[154:157], v[170:173], v[50:53]
	v_mfma_f32_16x16x32_bf16 v[42:45], v[142:145], v[194:197], v[42:45]
	v_mfma_f32_16x16x32_bf16 v[34:37], v[154:157], v[194:197], v[34:37]
	v_mfma_f32_16x16x32_bf16 v[26:29], v[142:145], v[202:205], v[26:29]
	v_mfma_f32_16x16x32_bf16 v[18:21], v[154:157], v[202:205], v[18:21]
	v_mfma_f32_16x16x32_bf16 v[62:65], v[146:149], v[166:169], v[62:65]
	v_mfma_f32_16x16x32_bf16 v[58:61], v[158:161], v[166:169], v[58:61]
	v_mfma_f32_16x16x32_bf16 v[54:57], v[146:149], v[174:177], v[54:57]
	v_mfma_f32_16x16x32_bf16 v[50:53], v[158:161], v[174:177], v[50:53]
	v_mfma_f32_16x16x32_bf16 v[42:45], v[146:149], v[198:201], v[42:45]
	v_mfma_f32_16x16x32_bf16 v[34:37], v[158:161], v[198:201], v[34:37]
	v_mfma_f32_16x16x32_bf16 v[26:29], v[146:149], v[206:209], v[26:29]
	v_mfma_f32_16x16x32_bf16 v[18:21], v[158:161], v[206:209], v[18:21]
	s_setprio 0
	s_barrier
; #define PG8_STAGE(bufoff, gbase, voff) do { _Pragma("unroll") for (int _i = 0; _i < 2; ++_i) \
;         __builtin_amdgcn_global_load_lds((const unsigned*)((const char*)(gbase) + (voff)[_i]), (LAS unsigned*)(lds + (bufoff) + ldsw + _i * 8192), 16, 0, 0); } while (0)
; #define PG8_LDA(dst, b, h) do { _Pragma("unroll") for (int m = 0; m < 4; ++m) _Pragma("unroll") for (int k = 0; k < 2; ++k) dst[m][k] = *(const LAS bf16x8*)(lds + PG8_SA(b, h) + aoff + m * 2048 + k * 1024); } while (0)
; #define PG8_LDB(dst, b, h) do { _Pragma("unroll") for (int n = 0; n < 2; ++n) _Pragma("unroll") for (int k = 0; k < 2; ++k) dst[n][k] = *(const LAS bf16x8*)(lds + PG8_SB(b, h) + boff + n * 2048 + k * 1024); } while (0)
; #define PG8_WAIT_V(n) asm volatile("s_waitcnt vmcnt(" #n ")" ::: "memory")
; #define PG8_WAIT_L(n) asm volatile("s_waitcnt lgkmcnt(" #n ")" ::: "memory")
; #define PG8_BAR __builtin_amdgcn_s_barrier()
; #define PG8_SCHED __builtin_amdgcn_sched_barrier(0)
; template <class Epi>
; __device__ __forceinline__ void gemm_phase(LAS unsigned char* lds, const Gemm g, const Epi& E) {
;     ...
;             PG8_LDB(B0, 0, 0); PG8_SCHED; PG8_LDA(At, 0, 0); PG8_STAGE(PG8_SA(1, 1), a1 + hstep, voffA);
;             PG8_WAIT_L(8); PG8_BAR; PG8_WAIT_L(0); PG8_MMA(0, 0, At, B0); PG8_BAR; PG8_SCHED;
;             PG8_LDB(B1, 0, 1); PG8_STAGE(PG8_SB(0, 0), b2, voffB);
;             PG8_BAR; PG8_WAIT_L(0); PG8_MMA(0, 1, At, B1); PG8_BAR;
;             PG8_LDA(At, 0, 1); PG8_STAGE(PG8_SA(0, 0), a2, voffA);
;             PG8_BAR; PG8_WAIT_L(0); PG8_MMA(1, 0, At, B0); PG8_BAR; PG8_SCHED;
;             PG8_STAGE(PG8_SB(0, 1), b2 + hstep, voffB);
;             PG8_WAIT_V(6); PG8_BAR; PG8_MMA(1, 1, At, B1); PG8_BAR;
;             PG8_LDB(B0, 1, 0); PG8_SCHED; PG8_LDA(At, 1, 0); PG8_STAGE(PG8_SA(0, 1), a2 + hstep, voffA);
;             PG8_WAIT_L(8); PG8_BAR; PG8_WAIT_L(0); PG8_MMA(0, 0, At, B0); PG8_BAR; PG8_SCHED;
;             PG8_LDB(B1, 1, 1); PG8_STAGE(PG8_SB(1, 0), b3, voffB);
;             PG8_BAR; PG8_WAIT_L(0); PG8_MMA(0, 1, At, B1); PG8_BAR;
;             PG8_LDA(At, 1, 1); PG8_STAGE(PG8_SA(1, 0), a3, voffA);
;             PG8_BAR; PG8_WAIT_L(0); PG8_MMA(1, 0, At, B0); PG8_BAR; PG8_SCHED;
;             PG8_STAGE(PG8_SB(1, 1), b3 + hstep, voffB);
;             PG8_WAIT_V(6); PG8_BAR; PG8_MMA(1, 1, At, B1); PG8_BAR;
	s_add_u32 s50, s50, s40
	s_addc_u32 s51, s51, s41
	s_add_i32 s90, s91, s54
	v_lshl_add_u64 v[236:237], s[50:51], 0, v[132:133]
	s_mov_b32 m0, s90
	v_lshl_add_u64 v[238:239], s[50:51], 0, v[136:137]
	global_load_lds_dwordx4 v[236:237], off
	s_add_i32 m0, s90, 0x2000
	s_nop 0
	global_load_lds_dwordx4 v[238:239], off
	s_waitcnt vmcnt(6)
	s_barrier
	s_setprio 1
	v_mfma_f32_16x16x32_bf16 v[46:49], v[210:213], v[162:165], v[46:49]
	v_mfma_f32_16x16x32_bf16 v[38:41], v[224:227], v[162:165], v[38:41]
	v_mfma_f32_16x16x32_bf16 v[30:33], v[210:213], v[170:173], v[30:33]
	v_mfma_f32_16x16x32_bf16 v[22:25], v[224:227], v[170:173], v[22:25]
	v_mfma_f32_16x16x32_bf16 v[14:17], v[210:213], v[194:197], v[14:17]
	v_mfma_f32_16x16x32_bf16 v[8:11], v[224:227], v[194:197], v[8:11]
	v_mfma_f32_16x16x32_bf16 v[4:7], v[210:213], v[202:205], v[4:7]
	v_mfma_f32_16x16x32_bf16 v[0:3], v[224:227], v[202:205], v[0:3]
	v_mfma_f32_16x16x32_bf16 v[46:49], v[220:223], v[166:169], v[46:49]
	v_mfma_f32_16x16x32_bf16 v[38:41], v[228:231], v[166:169], v[38:41]
	v_mfma_f32_16x16x32_bf16 v[30:33], v[220:223], v[174:177], v[30:33]
	v_mfma_f32_16x16x32_bf16 v[22:25], v[228:231], v[174:177], v[22:25]
	v_mfma_f32_16x16x32_bf16 v[14:17], v[220:223], v[198:201], v[14:17]
	v_mfma_f32_16x16x32_bf16 v[8:11], v[228:231], v[198:201], v[8:11]
	v_mfma_f32_16x16x32_bf16 v[4:7], v[220:223], v[206:209], v[4:7]
	v_mfma_f32_16x16x32_bf16 v[0:3], v[228:231], v[206:209], v[0:3]
	s_setprio 0
	s_add_i32 s50, 0, 0x18000
	v_add_u32_e32 v153, s50, v151
	s_barrier
	ds_read_b128 v[142:145], v153
	ds_read_b128 v[146:149], v153 offset:1024
	ds_read_b128 v[154:157], v153 offset:2048
	ds_read_b128 v[158:161], v153 offset:3072
	s_add_u32 s48, s48, s40
	s_addc_u32 s49, s49, s41
	s_mov_b32 m0, s57
	v_lshl_add_u64 v[210:211], s[48:49], 0, v[130:131]
	ds_read_b128 v[162:165], v152 offset:32768
	ds_read_b128 v[166:169], v152 offset:33792
	ds_read_b128 v[170:173], v152 offset:34816
	ds_read_b128 v[174:177], v152 offset:35840
	ds_read_b128 v[194:197], v152 offset:36864
	ds_read_b128 v[198:201], v152 offset:37888
	ds_read_b128 v[202:205], v152 offset:38912
	ds_read_b128 v[206:209], v152 offset:39936
	global_load_lds_dwordx4 v[210:211], off
	v_lshl_add_u64 v[210:211], s[48:49], 0, v[134:135]
	s_mov_b32 m0, s58
	s_nop 0
	global_load_lds_dwordx4 v[210:211], off
	s_waitcnt lgkmcnt(8)
	s_barrier
	s_waitcnt lgkmcnt(0)
	s_setprio 1
	s_waitcnt lgkmcnt(0)
	v_mfma_f32_16x16x32_bf16 v[126:129], v[142:145], v[162:165], v[126:129]
	v_mfma_f32_16x16x32_bf16 v[122:125], v[154:157], v[162:165], v[122:125]
	v_mfma_f32_16x16x32_bf16 v[118:121], v[142:145], v[170:173], v[118:121]
	v_mfma_f32_16x16x32_bf16 v[114:117], v[154:157], v[170:173], v[114:117]
	v_mfma_f32_16x16x32_bf16 v[106:109], v[142:145], v[194:197], v[106:109]
	v_mfma_f32_16x16x32_bf16 v[98:101], v[154:157], v[194:197], v[98:101]
	v_mfma_f32_16x16x32_bf16 v[90:93], v[142:145], v[202:205], v[90:93]
	v_mfma_f32_16x16x32_bf16 v[82:85], v[154:157], v[202:205], v[82:85]
	v_mfma_f32_16x16x32_bf16 v[126:129], v[146:149], v[166:169], v[126:129]
	v_mfma_f32_16x16x32_bf16 v[122:125], v[158:161], v[166:169], v[122:125]
	v_mfma_f32_16x16x32_bf16 v[118:121], v[146:149], v[174:177], v[118:121]
	v_mfma_f32_16x16x32_bf16 v[114:117], v[158:161], v[174:177], v[114:117]
	v_mfma_f32_16x16x32_bf16 v[106:109], v[146:149], v[198:201], v[106:109]
	v_mfma_f32_16x16x32_bf16 v[98:101], v[158:161], v[198:201], v[98:101]
	v_mfma_f32_16x16x32_bf16 v[90:93], v[146:149], v[206:209], v[90:93]
	v_mfma_f32_16x16x32_bf16 v[82:85], v[158:161], v[206:209], v[82:85]
	s_setprio 0
	s_barrier
	s_add_i32 s48, 0, 0x1c000
	s_add_i32 s49, s50, s54
	v_add_u32_e32 v153, s48, v151
	v_lshl_add_u64 v[186:187], v[186:187], 0, s[20:21]
	s_mov_b32 m0, s49
	ds_read_b128 v[210:213], v153
	ds_read_b128 v[220:223], v153 offset:1024
	ds_read_b128 v[224:227], v153 offset:2048
	ds_read_b128 v[228:231], v153 offset:3072
	global_load_lds_dwordx4 v[186:187], off
	v_lshl_add_u64 v[186:187], v[188:189], 0, s[20:21]
	s_add_i32 m0, s49, 0x2000
	s_nop 0
	global_load_lds_dwordx4 v[186:187], off
	s_barrier
	s_waitcnt lgkmcnt(0)
	s_setprio 1
	s_waitcnt lgkmcnt(0)
	v_mfma_f32_16x16x32_bf16 v[110:113], v[210:213], v[162:165], v[110:113]
	v_mfma_f32_16x16x32_bf16 v[102:105], v[224:227], v[162:165], v[102:105]
	v_mfma_f32_16x16x32_bf16 v[94:97], v[210:213], v[170:173], v[94:97]
	v_mfma_f32_16x16x32_bf16 v[86:89], v[224:227], v[170:173], v[86:89]
	v_mfma_f32_16x16x32_bf16 v[78:81], v[210:213], v[194:197], v[78:81]
	v_mfma_f32_16x16x32_bf16 v[74:77], v[224:227], v[194:197], v[74:77]
	v_mfma_f32_16x16x32_bf16 v[70:73], v[210:213], v[202:205], v[70:73]
	v_mfma_f32_16x16x32_bf16 v[66:69], v[224:227], v[202:205], v[66:69]
	v_mfma_f32_16x16x32_bf16 v[110:113], v[220:223], v[166:169], v[110:113]
	v_mfma_f32_16x16x32_bf16 v[102:105], v[228:231], v[166:169], v[102:105]
	v_mfma_f32_16x16x32_bf16 v[94:97], v[220:223], v[174:177], v[94:97]
	v_mfma_f32_16x16x32_bf16 v[86:89], v[228:231], v[174:177], v[86:89]
	v_mfma_f32_16x16x32_bf16 v[78:81], v[220:223], v[198:201], v[78:81]
	v_mfma_f32_16x16x32_bf16 v[74:77], v[228:231], v[198:201], v[74:77]
	v_mfma_f32_16x16x32_bf16 v[70:73], v[220:223], v[206:209], v[70:73]
	v_mfma_f32_16x16x32_bf16 v[66:69], v[228:231], v[206:209], v[66:69]
	s_setprio 0
	s_mov_b32 m0, s59
	v_lshl_add_u64 v[186:187], v[232:233], 0, s[20:21]
	s_barrier
	ds_read_b128 v[162:165], v152 offset:49152
	ds_read_b128 v[166:169], v152 offset:50176
	ds_read_b128 v[170:173], v152 offset:51200
	ds_read_b128 v[174:177], v152 offset:52224
	ds_read_b128 v[194:197], v152 offset:53248
	ds_read_b128 v[198:201], v152 offset:54272
	ds_read_b128 v[202:205], v152 offset:55296
	ds_read_b128 v[206:209], v152 offset:56320
	global_load_lds_dwordx4 v[186:187], off
	v_lshl_add_u64 v[186:187], v[234:235], 0, s[20:21]
	s_mov_b32 m0, s60
	s_nop 0
	global_load_lds_dwordx4 v[186:187], off
	s_barrier
; #define PG8_STAGE(bufoff, gbase, voff) do { _Pragma("unroll") for (int _i = 0; _i < 2; ++_i) \
;         __builtin_amdgcn_global_load_lds((const unsigned*)((const char*)(gbase) + (voff)[_i]), (LAS unsigned*)(lds + (bufoff) + ldsw + _i * 8192), 16, 0, 0); } while (0)
; #define PG8_MMA(ai, bj, At, Bt) do { __builtin_amdgcn_s_setprio(1); _Pragma("unroll") for (int m = 0; m < 4; ++m) _Pragma("unroll") for (int n = 0; n < 2; ++n) _Pragma("unroll") for (int k = 0; k < 2; ++k) \
;         acc[ai][bj][m][n] = __builtin_amdgcn_mfma_f32_16x16x32_bf16(Bt[n][k], At[m][k], acc[ai][bj][m][n], 0, 0, 0); __builtin_amdgcn_s_setprio(0); } while (0)
; #define PG8_WAIT_V(n) asm volatile("s_waitcnt vmcnt(" #n ")" ::: "memory")
; #define PG8_WAIT_L(n) asm volatile("s_waitcnt lgkmcnt(" #n ")" ::: "memory")
; #define PG8_BAR __builtin_amdgcn_s_barrier()
; #define PG8_SCHED __builtin_amdgcn_sched_barrier(0)
; __device__ __forceinline__ u32x4 pack8(const f32x4 a, const f32x4 b) { u32x4 w; w.x = pk_bf16(a[0], a[1]); w.y = pk_bf16(a[2], a[3]); w.z = pk_bf16(b[0], b[1]); w.w = pk_bf16(b[2], b[3]); return w; }
; template <class Epi>
; __device__ __forceinline__ void gemm_phase(LAS unsigned char* lds, const Gemm g, const Epi& E) {
;     ...
;             PG8_BAR; PG8_WAIT_L(0); PG8_MMA(1, 0, At, B0); PG8_BAR; PG8_SCHED;
;             PG8_STAGE(PG8_SB(1, 1), b3 + hstep, voffB);
;             PG8_WAIT_V(6); PG8_BAR; PG8_MMA(1, 1, At, B1); PG8_BAR;
;     __device__ __forceinline__ void fin(int row, int cb, f32x4 v0, f32x4 v1, int, const Col&, const Pos&) const {
;         *(u32x4*)(D + (size_t)row * 1024 + cb) = pack8(v0 * beta, v1 * beta);
;     }
	s_waitcnt lgkmcnt(0)
	s_setprio 1
	s_waitcnt lgkmcnt(0)
	v_mfma_f32_16x16x32_bf16 v[62:65], v[142:145], v[162:165], v[62:65]
	v_mfma_f32_16x16x32_bf16 v[58:61], v[154:157], v[162:165], v[58:61]
	v_mfma_f32_16x16x32_bf16 v[54:57], v[142:145], v[170:173], v[54:57]
	v_mfma_f32_16x16x32_bf16 v[50:53], v[154:157], v[170:173], v[50:53]
	v_mfma_f32_16x16x32_bf16 v[42:45], v[142:145], v[194:197], v[42:45]
	v_mfma_f32_16x16x32_bf16 v[34:37], v[154:157], v[194:197], v[34:37]
	v_mfma_f32_16x16x32_bf16 v[26:29], v[142:145], v[202:205], v[26:29]
	v_mfma_f32_16x16x32_bf16 v[18:21], v[154:157], v[202:205], v[18:21]
	v_mfma_f32_16x16x32_bf16 v[62:65], v[146:149], v[166:169], v[62:65]
	v_mfma_f32_16x16x32_bf16 v[58:61], v[158:161], v[166:169], v[58:61]
	v_mfma_f32_16x16x32_bf16 v[54:57], v[146:149], v[174:177], v[54:57]
	v_mfma_f32_16x16x32_bf16 v[50:53], v[158:161], v[174:177], v[50:53]
	v_mfma_f32_16x16x32_bf16 v[42:45], v[146:149], v[198:201], v[42:45]
	v_mfma_f32_16x16x32_bf16 v[34:37], v[158:161], v[198:201], v[34:37]
	v_mfma_f32_16x16x32_bf16 v[26:29], v[146:149], v[206:209], v[26:29]
	v_mfma_f32_16x16x32_bf16 v[18:21], v[158:161], v[206:209], v[18:21]
	s_setprio 0
	s_barrier
	s_add_i32 s48, s48, s54
	v_lshl_add_u64 v[142:143], v[236:237], 0, s[20:21]
	s_mov_b32 m0, s48
	s_nop 0
	global_load_lds_dwordx4 v[142:143], off
	v_lshl_add_u64 v[142:143], v[238:239], 0, s[20:21]
	s_add_i32 m0, s48, 0x2000
	s_nop 0
	global_load_lds_dwordx4 v[142:143], off
	s_waitcnt vmcnt(6)
	s_barrier
	s_setprio 1
	v_mfma_f32_16x16x32_bf16 v[46:49], v[210:213], v[162:165], v[46:49]
	v_mfma_f32_16x16x32_bf16 v[38:41], v[224:227], v[162:165], v[38:41]
	v_mfma_f32_16x16x32_bf16 v[30:33], v[210:213], v[170:173], v[30:33]
	v_mfma_f32_16x16x32_bf16 v[22:25], v[224:227], v[170:173], v[22:25]
	v_mfma_f32_16x16x32_bf16 v[14:17], v[210:213], v[194:197], v[14:17]
	v_mfma_f32_16x16x32_bf16 v[8:11], v[224:227], v[194:197], v[8:11]
	v_mfma_f32_16x16x32_bf16 v[4:7], v[210:213], v[202:205], v[4:7]
	v_mfma_f32_16x16x32_bf16 v[0:3], v[224:227], v[202:205], v[0:3]
	v_mfma_f32_16x16x32_bf16 v[46:49], v[220:223], v[166:169], v[46:49]
	v_mfma_f32_16x16x32_bf16 v[38:41], v[228:231], v[166:169], v[38:41]
	v_mfma_f32_16x16x32_bf16 v[30:33], v[220:223], v[174:177], v[30:33]
	v_mfma_f32_16x16x32_bf16 v[22:25], v[228:231], v[174:177], v[22:25]
	v_mfma_f32_16x16x32_bf16 v[14:17], v[220:223], v[198:201], v[14:17]
	v_mfma_f32_16x16x32_bf16 v[8:11], v[228:231], v[198:201], v[8:11]
	v_mfma_f32_16x16x32_bf16 v[4:7], v[220:223], v[206:209], v[4:7]
	v_mfma_f32_16x16x32_bf16 v[0:3], v[228:231], v[206:209], v[0:3]
	s_setprio 0
	s_add_u32 s46, s46, 0x100
	s_addc_u32 s47, s47, 0
	s_add_u32 s87, s87, 0x100
	s_addc_u32 s88, s88, 0
	s_cmp_ge_i32 s89, s2
	s_mov_b32 s48, s89
	s_barrier
	s_cbranch_scc0 .LBB0_160
	s_nop 0
	s_nop 0
	s_nop 0
	s_nop 0
	s_nop 0
	s_nop 0
	s_nop 0
	s_nop 0
	s_nop 0
	s_nop 0
	s_nop 0
	s_nop 0
	s_nop 0
	s_nop 0
	s_nop 0
	s_nop 0
	s_nop 0
	s_nop 0
	s_nop 0
	s_nop 0
	s_nop 0
	s_nop 0
	s_nop 0
	s_nop 0
	s_nop 0
	s_nop 0
	s_nop 0
	s_nop 0
	s_nop 0
	s_nop 0
	s_nop 0
	s_nop 0
	s_nop 0
	s_nop 0
	s_nop 0
	s_nop 0
	s_nop 0
	s_nop 0
	s_nop 0
	s_nop 0
	s_nop 0
	s_nop 0
	s_nop 0
	s_nop 0
	s_nop 0
	s_nop 0
	s_nop 0
	s_nop 0
	s_nop 0
	s_nop 0
	s_nop 0
	s_nop 0
	s_nop 0
	s_nop 0
	s_nop 0
	s_nop 0
	s_nop 0
	s_nop 0
	s_nop 0
	s_nop 0
	s_nop 0
	v_pk_mul_f32 v[128:129], v[128:129], 0.5 op_sel_hi:[1,0]
	v_pk_mul_f32 v[126:127], v[126:127], 0.5 op_sel_hi:[1,0]
	v_pk_mul_f32 v[124:125], v[124:125], 0.5 op_sel_hi:[1,0]
	v_pk_mul_f32 v[122:123], v[122:123], 0.5 op_sel_hi:[1,0]
	v_pk_mul_f32 v[142:143], v[112:113], 0.5 op_sel_hi:[1,0]
	v_pk_mul_f32 v[144:145], v[110:111], 0.5 op_sel_hi:[1,0]
	v_pk_mul_f32 v[146:147], v[104:105], 0.5 op_sel_hi:[1,0]
	v_pk_mul_f32 v[148:149], v[102:103], 0.5 op_sel_hi:[1,0]
	v_pk_mul_f32 v[102:103], v[120:121], 0.5 op_sel_hi:[1,0]
	v_pk_mul_f32 v[104:105], v[118:119], 0.5 op_sel_hi:[1,0]
	v_pk_mul_f32 v[110:111], v[116:117], 0.5 op_sel_hi:[1,0]
	v_pk_mul_f32 v[112:113], v[114:115], 0.5 op_sel_hi:[1,0]
	v_pk_mul_f32 v[114:115], v[96:97], 0.5 op_sel_hi:[1,0]
	v_pk_mul_f32 v[116:117], v[94:95], 0.5 op_sel_hi:[1,0]
	v_pk_mul_f32 v[118:119], v[88:89], 0.5 op_sel_hi:[1,0]
	v_pk_mul_f32 v[120:121], v[86:87], 0.5 op_sel_hi:[1,0]
	v_pk_mul_f32 v[86:87], v[108:109], 0.5 op_sel_hi:[1,0]
	v_pk_mul_f32 v[88:89], v[106:107], 0.5 op_sel_hi:[1,0]
	v_pk_mul_f32 v[94:95], v[100:101], 0.5 op_sel_hi:[1,0]
	v_pk_mul_f32 v[96:97], v[98:99], 0.5 op_sel_hi:[1,0]
	v_pk_mul_f32 v[98:99], v[80:81], 0.5 op_sel_hi:[1,0]
	v_pk_mul_f32 v[100:101], v[78:79], 0.5 op_sel_hi:[1,0]
	v_pk_mul_f32 v[106:107], v[76:77], 0.5 op_sel_hi:[1,0]
	v_pk_mul_f32 v[108:109], v[74:75], 0.5 op_sel_hi:[1,0]
	v_pk_mul_f32 v[74:75], v[92:93], 0.5 op_sel_hi:[1,0]
	v_pk_mul_f32 v[76:77], v[90:91], 0.5 op_sel_hi:[1,0]
	v_pk_mul_f32 v[78:79], v[84:85], 0.5 op_sel_hi:[1,0]
	v_pk_mul_f32 v[80:81], v[82:83], 0.5 op_sel_hi:[1,0]
	v_pk_mul_f32 v[72:73], v[72:73], 0.5 op_sel_hi:[1,0]
	v_pk_mul_f32 v[70:71], v[70:71], 0.5 op_sel_hi:[1,0]
	v_pk_mul_f32 v[68:69], v[68:69], 0.5 op_sel_hi:[1,0]
	v_pk_mul_f32 v[66:67], v[66:67], 0.5 op_sel_hi:[1,0]
	v_pk_mul_f32 v[64:65], v[64:65], 0.5 op_sel_hi:[1,0]
	v_pk_mul_f32 v[62:63], v[62:63], 0.5 op_sel_hi:[1,0]
	v_pk_mul_f32 v[60:61], v[60:61], 0.5 op_sel_hi:[1,0]
	v_pk_mul_f32 v[58:59], v[58:59], 0.5 op_sel_hi:[1,0]
	v_pk_mul_f32 v[82:83], v[48:49], 0.5 op_sel_hi:[1,0]
	v_pk_mul_f32 v[84:85], v[46:47], 0.5 op_sel_hi:[1,0]
	v_pk_mul_f32 v[90:91], v[40:41], 0.5 op_sel_hi:[1,0]
	v_pk_mul_f32 v[92:93], v[38:39], 0.5 op_sel_hi:[1,0]
	v_pk_mul_f32 v[38:39], v[56:57], 0.5 op_sel_hi:[1,0]
	v_pk_mul_f32 v[40:41], v[54:55], 0.5 op_sel_hi:[1,0]
	v_pk_mul_f32 v[46:47], v[52:53], 0.5 op_sel_hi:[1,0]
	v_pk_mul_f32 v[48:49], v[50:51], 0.5 op_sel_hi:[1,0]
	v_pk_mul_f32 v[50:51], v[32:33], 0.5 op_sel_hi:[1,0]
	v_pk_mul_f32 v[52:53], v[30:31], 0.5 op_sel_hi:[1,0]
	v_pk_mul_f32 v[54:55], v[24:25], 0.5 op_sel_hi:[1,0]
	v_pk_mul_f32 v[56:57], v[22:23], 0.5 op_sel_hi:[1,0]
	v_pk_mul_f32 v[22:23], v[44:45], 0.5 op_sel_hi:[1,0]
	v_pk_mul_f32 v[24:25], v[42:43], 0.5 op_sel_hi:[1,0]
	v_pk_mul_f32 v[30:31], v[36:37], 0.5 op_sel_hi:[1,0]
	v_pk_mul_f32 v[32:33], v[34:35], 0.5 op_sel_hi:[1,0]
	v_pk_mul_f32 v[34:35], v[16:17], 0.5 op_sel_hi:[1,0]
	v_pk_mul_f32 v[36:37], v[14:15], 0.5 op_sel_hi:[1,0]
	v_pk_mul_f32 v[42:43], v[10:11], 0.5 op_sel_hi:[1,0]
	v_pk_mul_f32 v[44:45], v[8:9], 0.5 op_sel_hi:[1,0]
	v_pk_mul_f32 v[8:9], v[28:29], 0.5 op_sel_hi:[1,0]
	v_pk_mul_f32 v[10:11], v[26:27], 0.5 op_sel_hi:[1,0]
	v_pk_mul_f32 v[14:15], v[20:21], 0.5 op_sel_hi:[1,0]
	v_pk_mul_f32 v[16:17], v[18:19], 0.5 op_sel_hi:[1,0]
	v_pk_mul_f32 v[6:7], v[6:7], 0.5 op_sel_hi:[1,0]
	v_pk_mul_f32 v[4:5], v[4:5], 0.5 op_sel_hi:[1,0]
	v_pk_mul_f32 v[2:3], v[2:3], 0.5 op_sel_hi:[1,0]
	v_pk_mul_f32 v[0:1], v[0:1], 0.5 op_sel_hi:[1,0]
	s_mov_b32 s50, 0x3a800000
	s_branch .LBB0_147

; template <class Epi>
; __device__ __forceinline__ void gemm_phase(LAS unsigned char* lds, const Gemm g, const Epi& E) {
;     ...
;         if (!has_next) break;
; #pragma unroll
;         for (int a = 0; a < 2; ++a)
; #pragma unroll
;             for (int b = 0; b < 2; ++b)
; #pragma unroll
;                 for (int m = 0; m < 4; ++m)
; #pragma unroll
;                     for (int n = 0; n < 2; ++n) acc[a][b][m][n] = (f32x4){0.f, 0.f, 0.f, 0.f};
;         cur = nxt; cA = nA; cB = nB; ++ui;
.LBB0_349:
	v_mov_b32_e32 v125, 0
	s_andn2_b64 vcc, exec, s[44:45]
	v_mov_b32_e32 v124, v125
	v_mov_b32_e32 v123, v125
	v_mov_b32_e32 v122, v125
	v_mov_b32_e32 v129, v125
	v_mov_b32_e32 v128, v125
	v_mov_b32_e32 v127, v125
	v_mov_b32_e32 v126, v125
	v_mov_b32_e32 v113, v125
	v_mov_b32_e32 v112, v125
	v_mov_b32_e32 v111, v125
	v_mov_b32_e32 v110, v125
	v_mov_b32_e32 v109, v125
	v_mov_b32_e32 v108, v125
	v_mov_b32_e32 v107, v125
	v_mov_b32_e32 v106, v125
	v_mov_b32_e32 v97, v125
	v_mov_b32_e32 v96, v125
	v_mov_b32_e32 v95, v125
	v_mov_b32_e32 v94, v125
	v_mov_b32_e32 v93, v125
	v_mov_b32_e32 v92, v125
	v_mov_b32_e32 v91, v125
	v_mov_b32_e32 v90, v125
	v_mov_b32_e32 v81, v125
	v_mov_b32_e32 v80, v125
	v_mov_b32_e32 v79, v125
	v_mov_b32_e32 v78, v125
	v_mov_b32_e32 v77, v125
	v_mov_b32_e32 v76, v125
	v_mov_b32_e32 v75, v125
	v_mov_b32_e32 v74, v125
	v_mov_b32_e32 v121, v125
	v_mov_b32_e32 v120, v125
	v_mov_b32_e32 v119, v125
	v_mov_b32_e32 v118, v125
	v_mov_b32_e32 v117, v125
	v_mov_b32_e32 v116, v125
	v_mov_b32_e32 v115, v125
	v_mov_b32_e32 v114, v125
	v_mov_b32_e32 v105, v125
	v_mov_b32_e32 v104, v125
	v_mov_b32_e32 v103, v125
	v_mov_b32_e32 v102, v125
	v_mov_b32_e32 v101, v125
	v_mov_b32_e32 v100, v125
	v_mov_b32_e32 v99, v125
	v_mov_b32_e32 v98, v125
	v_mov_b32_e32 v89, v125
	v_mov_b32_e32 v88, v125
	v_mov_b32_e32 v87, v125
	v_mov_b32_e32 v86, v125
	v_mov_b32_e32 v85, v125
	v_mov_b32_e32 v84, v125
	v_mov_b32_e32 v83, v125
	v_mov_b32_e32 v82, v125
	v_mov_b32_e32 v73, v125
	v_mov_b32_e32 v72, v125
	v_mov_b32_e32 v71, v125
	v_mov_b32_e32 v70, v125
	v_mov_b32_e32 v69, v125
	v_mov_b32_e32 v68, v125
	v_mov_b32_e32 v67, v125
	v_mov_b32_e32 v66, v125
	v_mov_b32_e32 v65, v125
	v_mov_b32_e32 v64, v125
	v_mov_b32_e32 v63, v125
	v_mov_b32_e32 v62, v125
	v_mov_b32_e32 v61, v125
	v_mov_b32_e32 v60, v125
	v_mov_b32_e32 v59, v125
	v_mov_b32_e32 v58, v125
	v_mov_b32_e32 v49, v125
	v_mov_b32_e32 v48, v125
	v_mov_b32_e32 v47, v125
	v_mov_b32_e32 v46, v125
	v_mov_b32_e32 v45, v125
	v_mov_b32_e32 v44, v125
	v_mov_b32_e32 v43, v125
	v_mov_b32_e32 v42, v125
	v_mov_b32_e32 v33, v125
	v_mov_b32_e32 v32, v125
	v_mov_b32_e32 v31, v125
	v_mov_b32_e32 v30, v125
	v_mov_b32_e32 v29, v125
	v_mov_b32_e32 v28, v125
	v_mov_b32_e32 v27, v125
	v_mov_b32_e32 v26, v125
	v_mov_b32_e32 v17, v125
	v_mov_b32_e32 v16, v125
	v_mov_b32_e32 v15, v125
	v_mov_b32_e32 v14, v125
	v_mov_b32_e32 v11, v125
	v_mov_b32_e32 v10, v125
	v_mov_b32_e32 v9, v125
	v_mov_b32_e32 v8, v125
	v_mov_b32_e32 v57, v125
	v_mov_b32_e32 v56, v125
	v_mov_b32_e32 v55, v125
	v_mov_b32_e32 v54, v125
	v_mov_b32_e32 v53, v125
	v_mov_b32_e32 v52, v125
	v_mov_b32_e32 v51, v125
	v_mov_b32_e32 v50, v125
	v_mov_b32_e32 v41, v125
	v_mov_b32_e32 v40, v125
	v_mov_b32_e32 v39, v125
	v_mov_b32_e32 v38, v125
	v_mov_b32_e32 v37, v125
	v_mov_b32_e32 v36, v125
	v_mov_b32_e32 v35, v125
	v_mov_b32_e32 v34, v125
	v_mov_b32_e32 v25, v125
	v_mov_b32_e32 v24, v125
	v_mov_b32_e32 v23, v125
	v_mov_b32_e32 v22, v125
	v_mov_b32_e32 v21, v125
	v_mov_b32_e32 v20, v125
	v_mov_b32_e32 v19, v125
	v_mov_b32_e32 v18, v125
	v_mov_b32_e32 v7, v125
	v_mov_b32_e32 v6, v125
	v_mov_b32_e32 v5, v125
	v_mov_b32_e32 v4, v125
	v_mov_b32_e32 v3, v125
	v_mov_b32_e32 v2, v125
	v_mov_b32_e32 v1, v125
	v_mov_b32_e32 v0, v125
	s_cbranch_vccnz .LBB0_342
	s_add_u32 s46, s46, 0x80
	s_addc_u32 s47, s47, 0
	s_add_u32 s84, s48, 0x100
	v_mov_b32_e32 v0, 0
	s_addc_u32 s85, s49, 0
	s_mov_b32 s48, 0
	v_mov_b32_e32 v1, v0
	v_mov_b32_e32 v2, v0
	v_mov_b32_e32 v3, v0
	v_mov_b32_e32 v4, v0
	v_mov_b32_e32 v5, v0
	v_mov_b32_e32 v6, v0
	v_mov_b32_e32 v7, v0
	v_mov_b32_e32 v18, v0
	v_mov_b32_e32 v19, v0
	v_mov_b32_e32 v20, v0
	v_mov_b32_e32 v21, v0
	v_mov_b32_e32 v22, v0
	v_mov_b32_e32 v23, v0
	v_mov_b32_e32 v24, v0
	v_mov_b32_e32 v25, v0
	v_mov_b32_e32 v34, v0
	v_mov_b32_e32 v35, v0
	v_mov_b32_e32 v36, v0
	v_mov_b32_e32 v37, v0
	v_mov_b32_e32 v38, v0
	v_mov_b32_e32 v39, v0
	v_mov_b32_e32 v40, v0
	v_mov_b32_e32 v41, v0
	v_mov_b32_e32 v50, v0
	v_mov_b32_e32 v51, v0
	v_mov_b32_e32 v52, v0
	v_mov_b32_e32 v53, v0
	v_mov_b32_e32 v54, v0
	v_mov_b32_e32 v55, v0
	v_mov_b32_e32 v56, v0
	v_mov_b32_e32 v57, v0
	v_mov_b32_e32 v8, v0
	v_mov_b32_e32 v9, v0
	v_mov_b32_e32 v10, v0
	v_mov_b32_e32 v11, v0
	v_mov_b32_e32 v14, v0
	v_mov_b32_e32 v15, v0
	v_mov_b32_e32 v16, v0
	v_mov_b32_e32 v17, v0
	v_mov_b32_e32 v26, v0
	v_mov_b32_e32 v27, v0
	v_mov_b32_e32 v28, v0
	v_mov_b32_e32 v29, v0
	v_mov_b32_e32 v30, v0
	v_mov_b32_e32 v31, v0
	v_mov_b32_e32 v32, v0
	v_mov_b32_e32 v33, v0
	v_mov_b32_e32 v42, v0
	v_mov_b32_e32 v43, v0
	v_mov_b32_e32 v44, v0
	v_mov_b32_e32 v45, v0
	v_mov_b32_e32 v46, v0
	v_mov_b32_e32 v47, v0
	v_mov_b32_e32 v48, v0
	v_mov_b32_e32 v49, v0
	v_mov_b32_e32 v58, v0
	v_mov_b32_e32 v59, v0
	v_mov_b32_e32 v60, v0
	v_mov_b32_e32 v61, v0
	v_mov_b32_e32 v62, v0
	v_mov_b32_e32 v63, v0
	v_mov_b32_e32 v64, v0
	v_mov_b32_e32 v65, v0
	v_mov_b32_e32 v66, v0
	v_mov_b32_e32 v67, v0
	v_mov_b32_e32 v68, v0
	v_mov_b32_e32 v69, v0
	v_mov_b32_e32 v70, v0
	v_mov_b32_e32 v71, v0
	v_mov_b32_e32 v72, v0
	v_mov_b32_e32 v73, v0
	v_mov_b32_e32 v82, v0
	v_mov_b32_e32 v83, v0
	v_mov_b32_e32 v84, v0
	v_mov_b32_e32 v85, v0
	v_mov_b32_e32 v86, v0
	v_mov_b32_e32 v87, v0
	v_mov_b32_e32 v88, v0
	v_mov_b32_e32 v89, v0
	v_mov_b32_e32 v98, v0
	v_mov_b32_e32 v99, v0
	v_mov_b32_e32 v100, v0
	v_mov_b32_e32 v101, v0
	v_mov_b32_e32 v102, v0
	v_mov_b32_e32 v103, v0
	v_mov_b32_e32 v104, v0
	v_mov_b32_e32 v105, v0
	v_mov_b32_e32 v114, v0
	v_mov_b32_e32 v115, v0
	v_mov_b32_e32 v116, v0
	v_mov_b32_e32 v117, v0
	v_mov_b32_e32 v118, v0
	v_mov_b32_e32 v119, v0
	v_mov_b32_e32 v120, v0
	v_mov_b32_e32 v121, v0
	v_mov_b32_e32 v74, v0
	v_mov_b32_e32 v75, v0
	v_mov_b32_e32 v76, v0
	v_mov_b32_e32 v77, v0
	v_mov_b32_e32 v78, v0
	v_mov_b32_e32 v79, v0
	v_mov_b32_e32 v80, v0
	v_mov_b32_e32 v81, v0
	v_mov_b32_e32 v90, v0
	v_mov_b32_e32 v91, v0
	v_mov_b32_e32 v92, v0
	v_mov_b32_e32 v93, v0
	v_mov_b32_e32 v94, v0
	v_mov_b32_e32 v95, v0
	v_mov_b32_e32 v96, v0
	v_mov_b32_e32 v97, v0
	v_mov_b32_e32 v106, v0
	v_mov_b32_e32 v107, v0
	v_mov_b32_e32 v108, v0
	v_mov_b32_e32 v109, v0
	v_mov_b32_e32 v110, v0
	v_mov_b32_e32 v111, v0
	v_mov_b32_e32 v112, v0
	v_mov_b32_e32 v113, v0
	v_mov_b32_e32 v126, v0
	v_mov_b32_e32 v127, v0
	v_mov_b32_e32 v128, v0
	v_mov_b32_e32 v129, v0
	v_mov_b32_e32 v122, v0
	v_mov_b32_e32 v123, v0
	v_mov_b32_e32 v124, v0
	v_mov_b32_e32 v125, v0
	s_nop 0
	s_nop 0
	s_nop 0
	s_nop 0
	s_nop 0
	s_nop 0
	s_nop 0
	s_nop 0
	s_nop 0
	s_nop 0
	s_nop 0
	s_nop 0
	s_nop 0
	s_nop 0
	s_nop 0
	s_nop 0
	s_nop 0
	s_nop 0
	s_nop 0
	s_nop 0
	s_nop 0
	s_nop 0
	s_nop 0
	s_nop 0
	s_nop 0
	s_nop 0
	s_nop 0
	s_nop 0
	s_nop 0
	s_nop 0
	s_nop 0
	s_nop 0
	s_nop 0
	s_nop 0
	s_nop 0
	s_nop 0
	s_nop 0
	s_nop 0
	s_nop 0
	s_nop 0
	s_nop 0
	s_nop 0
; #define PG8_STAGE(bufoff, gbase, voff) do { _Pragma("unroll") for (int _i = 0; _i < 2; ++_i) \
;         __builtin_amdgcn_global_load_lds((const unsigned*)((const char*)(gbase) + (voff)[_i]), (LAS unsigned*)(lds + (bufoff) + ldsw + _i * 8192), 16, 0, 0); } while (0)
; #define PG8_LDA(dst, b, h) do { _Pragma("unroll") for (int m = 0; m < 4; ++m) _Pragma("unroll") for (int k = 0; k < 2; ++k) dst[m][k] = *(const LAS bf16x8*)(lds + PG8_SA(b, h) + aoff + m * 2048 + k * 1024); } while (0)
; #define PG8_LDB(dst, b, h) do { _Pragma("unroll") for (int n = 0; n < 2; ++n) _Pragma("unroll") for (int k = 0; k < 2; ++k) dst[n][k] = *(const LAS bf16x8*)(lds + PG8_SB(b, h) + boff + n * 2048 + k * 1024); } while (0)
; #define PG8_MMA(ai, bj, At, Bt) do { __builtin_amdgcn_s_setprio(1); _Pragma("unroll") for (int m = 0; m < 4; ++m) _Pragma("unroll") for (int n = 0; n < 2; ++n) _Pragma("unroll") for (int k = 0; k < 2; ++k) \
;         acc[ai][bj][m][n] = __builtin_amdgcn_mfma_f32_16x16x32_bf16(Bt[n][k], At[m][k], acc[ai][bj][m][n], 0, 0, 0); __builtin_amdgcn_s_setprio(0); } while (0)
; template <class Epi>
; __device__ __forceinline__ void gemm_phase(LAS unsigned char* lds, const Gemm g, const Epi& E) {
;     ...
;         for (int t = 0; t < nt; t += 2) {
;             const bool last = (t == nt - 2);
;             const char* a1 = cA + (size_t)(t + 1) * kstep;
;             const char* a2 = last ? nA : cA + (size_t)(t + 2) * kstep; const char* b2 = last ? nB : cB + (size_t)(t + 2) * kstep;
;             const char* a3 = a2 + kstep; const char* b3 = b2 + kstep;
;             PG8_LDB(B0, 0, 0); PG8_SCHED; PG8_LDA(At, 0, 0); PG8_STAGE(PG8_SA(1, 1), a1 + hstep, voffA);
;             PG8_WAIT_L(8); PG8_BAR; PG8_WAIT_L(0); PG8_MMA(0, 0, At, B0); PG8_BAR; PG8_SCHED;
;             PG8_LDB(B1, 0, 1); PG8_STAGE(PG8_SB(0, 0), b2, voffB);
;             PG8_BAR; PG8_WAIT_L(0); PG8_MMA(0, 1, At, B1); PG8_BAR;
;             PG8_LDA(At, 0, 1); PG8_STAGE(PG8_SA(0, 0), a2, voffA);
;             PG8_BAR; PG8_WAIT_L(0); PG8_MMA(1, 0, At, B0); PG8_BAR; PG8_SCHED;
;             PG8_STAGE(PG8_SB(0, 1), b2 + hstep, voffB);
;             PG8_WAIT_V(6); PG8_BAR; PG8_MMA(1, 1, At, B1); PG8_BAR;
;             PG8_LDB(B0, 1, 0); PG8_SCHED; PG8_LDA(At, 1, 0); PG8_STAGE(PG8_SA(0, 1), a2 + hstep, voffA);
;             PG8_WAIT_L(8); PG8_BAR; PG8_WAIT_L(0); PG8_MMA(0, 0, At, B0); PG8_BAR; PG8_SCHED;
.LBB0_351:
	s_add_i32 s86, s48, 2
	s_add_u32 s50, s46, 0x80
	s_addc_u32 s49, s47, 0
	s_add_i32 s87, 0, 0x10000
	v_add_u32_e32 v142, s87, v165
	ds_read_b128 v[130:133], v142
	ds_read_b128 v[134:137], v142 offset:1024
	ds_read_b128 v[138:141], v142 offset:2048
	ds_read_b128 v[142:145], v142 offset:3072
	s_cmp_eq_u32 s60, s48
	s_cselect_b32 s48, s0, s50
	s_cselect_b32 s49, s1, s49
	s_cselect_b32 s51, s39, s85
	s_cselect_b32 s50, s38, s84
	v_lshl_add_u64 v[162:163], s[46:47], 0, v[154:155]
	s_add_i32 m0, s52, 0xc000
	ds_read_b128 v[158:161], v166
	ds_read_b128 v[168:171], v166 offset:1024
	ds_read_b128 v[172:175], v166 offset:2048
	ds_read_b128 v[194:197], v166 offset:3072
	ds_read_b128 v[198:201], v166 offset:4096
	ds_read_b128 v[202:205], v166 offset:5120
	ds_read_b128 v[206:209], v166 offset:6144
	ds_read_b128 v[210:213], v166 offset:7168
	global_load_lds_dwordx4 v[162:163], off
	v_lshl_add_u64 v[162:163], s[46:47], 0, v[156:157]
	s_add_i32 m0, s52, 0xe000
	s_nop 0
	global_load_lds_dwordx4 v[162:163], off
	s_waitcnt lgkmcnt(8)
	s_barrier
	s_waitcnt lgkmcnt(0)
	s_setprio 1
	s_waitcnt lgkmcnt(0)
	v_mfma_f32_16x16x32_bf16 v[122:125], v[130:133], v[158:161], v[122:125]
	v_mfma_f32_16x16x32_bf16 v[126:129], v[138:141], v[158:161], v[126:129]
	v_mfma_f32_16x16x32_bf16 v[110:113], v[130:133], v[172:175], v[110:113]
	v_mfma_f32_16x16x32_bf16 v[106:109], v[138:141], v[172:175], v[106:109]
	v_mfma_f32_16x16x32_bf16 v[94:97], v[130:133], v[198:201], v[94:97]
	v_mfma_f32_16x16x32_bf16 v[90:93], v[138:141], v[198:201], v[90:93]
	v_mfma_f32_16x16x32_bf16 v[78:81], v[130:133], v[206:209], v[78:81]
	v_mfma_f32_16x16x32_bf16 v[74:77], v[138:141], v[206:209], v[74:77]
	v_mfma_f32_16x16x32_bf16 v[122:125], v[134:137], v[168:171], v[122:125]
	v_mfma_f32_16x16x32_bf16 v[126:129], v[142:145], v[168:171], v[126:129]
	v_mfma_f32_16x16x32_bf16 v[110:113], v[134:137], v[194:197], v[110:113]
	v_mfma_f32_16x16x32_bf16 v[106:109], v[142:145], v[194:197], v[106:109]
	v_mfma_f32_16x16x32_bf16 v[94:97], v[134:137], v[202:205], v[94:97]
	v_mfma_f32_16x16x32_bf16 v[90:93], v[142:145], v[202:205], v[90:93]
	v_mfma_f32_16x16x32_bf16 v[78:81], v[134:137], v[210:213], v[78:81]
	v_mfma_f32_16x16x32_bf16 v[74:77], v[142:145], v[210:213], v[74:77]
	s_setprio 0
	s_barrier
	s_add_i32 s88, 0, 0x14000
	v_add_u32_e32 v162, s88, v165
	s_add_i32 s87, s87, s15
	ds_read_b128 v[220:223], v162
	ds_read_b128 v[224:227], v162 offset:1024
	ds_read_b128 v[228:231], v162 offset:2048
	ds_read_b128 v[232:235], v162 offset:3072
	v_lshl_add_u64 v[162:163], s[50:51], 0, v[150:151]
	s_mov_b32 m0, s87
	v_lshl_add_u64 v[176:177], s[50:51], 0, v[146:147]
	global_load_lds_dwordx4 v[162:163], off
	s_add_i32 m0, s87, 0x2000
	s_nop 0
	global_load_lds_dwordx4 v[176:177], off
	s_barrier
	s_waitcnt lgkmcnt(0)
	s_setprio 1
	s_waitcnt lgkmcnt(0)
	v_mfma_f32_16x16x32_bf16 v[118:121], v[220:223], v[158:161], v[118:121]
	v_mfma_f32_16x16x32_bf16 v[114:117], v[228:231], v[158:161], v[114:117]
	v_mfma_f32_16x16x32_bf16 v[102:105], v[220:223], v[172:175], v[102:105]
	v_mfma_f32_16x16x32_bf16 v[98:101], v[228:231], v[172:175], v[98:101]
	v_mfma_f32_16x16x32_bf16 v[86:89], v[220:223], v[198:201], v[86:89]
	v_mfma_f32_16x16x32_bf16 v[82:85], v[228:231], v[198:201], v[82:85]
	v_mfma_f32_16x16x32_bf16 v[70:73], v[220:223], v[206:209], v[70:73]
	v_mfma_f32_16x16x32_bf16 v[66:69], v[228:231], v[206:209], v[66:69]
	v_mfma_f32_16x16x32_bf16 v[118:121], v[224:227], v[168:171], v[118:121]
	v_mfma_f32_16x16x32_bf16 v[114:117], v[232:235], v[168:171], v[114:117]
	v_mfma_f32_16x16x32_bf16 v[102:105], v[224:227], v[194:197], v[102:105]
	v_mfma_f32_16x16x32_bf16 v[98:101], v[232:235], v[194:197], v[98:101]
	v_mfma_f32_16x16x32_bf16 v[86:89], v[224:227], v[202:205], v[86:89]
	v_mfma_f32_16x16x32_bf16 v[82:85], v[232:235], v[202:205], v[82:85]
	v_mfma_f32_16x16x32_bf16 v[70:73], v[224:227], v[210:213], v[70:73]
	v_mfma_f32_16x16x32_bf16 v[66:69], v[232:235], v[210:213], v[66:69]
	s_setprio 0
	s_mov_b32 m0, s52
	v_lshl_add_u64 v[186:187], s[48:49], 0, v[152:153]
	s_barrier
	ds_read_b128 v[158:161], v166 offset:16384
	ds_read_b128 v[168:171], v166 offset:17408
	ds_read_b128 v[172:175], v166 offset:18432
	ds_read_b128 v[194:197], v166 offset:19456
	ds_read_b128 v[198:201], v166 offset:20480
	ds_read_b128 v[202:205], v166 offset:21504
	ds_read_b128 v[206:209], v166 offset:22528
	ds_read_b128 v[210:213], v166 offset:23552
	global_load_lds_dwordx4 v[186:187], off
	v_lshl_add_u64 v[188:189], s[48:49], 0, v[148:149]
	s_mov_b32 m0, s53
	s_nop 0
	global_load_lds_dwordx4 v[188:189], off
	s_barrier
	s_waitcnt lgkmcnt(0)
	s_setprio 1
	s_waitcnt lgkmcnt(0)
	v_mfma_f32_16x16x32_bf16 v[62:65], v[130:133], v[158:161], v[62:65]
	v_mfma_f32_16x16x32_bf16 v[58:61], v[138:141], v[158:161], v[58:61]
	v_mfma_f32_16x16x32_bf16 v[46:49], v[130:133], v[172:175], v[46:49]
	v_mfma_f32_16x16x32_bf16 v[42:45], v[138:141], v[172:175], v[42:45]
	v_mfma_f32_16x16x32_bf16 v[30:33], v[130:133], v[198:201], v[30:33]
	v_mfma_f32_16x16x32_bf16 v[26:29], v[138:141], v[198:201], v[26:29]
	v_mfma_f32_16x16x32_bf16 v[14:17], v[130:133], v[206:209], v[14:17]
	v_mfma_f32_16x16x32_bf16 v[8:11], v[138:141], v[206:209], v[8:11]
	v_mfma_f32_16x16x32_bf16 v[62:65], v[134:137], v[168:171], v[62:65]
	v_mfma_f32_16x16x32_bf16 v[58:61], v[142:145], v[168:171], v[58:61]
	v_mfma_f32_16x16x32_bf16 v[46:49], v[134:137], v[194:197], v[46:49]
	v_mfma_f32_16x16x32_bf16 v[42:45], v[142:145], v[194:197], v[42:45]
	v_mfma_f32_16x16x32_bf16 v[30:33], v[134:137], v[202:205], v[30:33]
	v_mfma_f32_16x16x32_bf16 v[26:29], v[142:145], v[202:205], v[26:29]
	v_mfma_f32_16x16x32_bf16 v[14:17], v[134:137], v[210:213], v[14:17]
	v_mfma_f32_16x16x32_bf16 v[8:11], v[142:145], v[210:213], v[8:11]
	s_setprio 0
	s_barrier
; #define PG8_STAGE(bufoff, gbase, voff) do { _Pragma("unroll") for (int _i = 0; _i < 2; ++_i) \
;         __builtin_amdgcn_global_load_lds((const unsigned*)((const char*)(gbase) + (voff)[_i]), (LAS unsigned*)(lds + (bufoff) + ldsw + _i * 8192), 16, 0, 0); } while (0)
; #define PG8_LDA(dst, b, h) do { _Pragma("unroll") for (int m = 0; m < 4; ++m) _Pragma("unroll") for (int k = 0; k < 2; ++k) dst[m][k] = *(const LAS bf16x8*)(lds + PG8_SA(b, h) + aoff + m * 2048 + k * 1024); } while (0)
; #define PG8_LDB(dst, b, h) do { _Pragma("unroll") for (int n = 0; n < 2; ++n) _Pragma("unroll") for (int k = 0; k < 2; ++k) dst[n][k] = *(const LAS bf16x8*)(lds + PG8_SB(b, h) + boff + n * 2048 + k * 1024); } while (0)
; #define PG8_MMA(ai, bj, At, Bt) do { __builtin_amdgcn_s_setprio(1); _Pragma("unroll") for (int m = 0; m < 4; ++m) _Pragma("unroll") for (int n = 0; n < 2; ++n) _Pragma("unroll") for (int k = 0; k < 2; ++k) \
;         acc[ai][bj][m][n] = __builtin_amdgcn_mfma_f32_16x16x32_bf16(Bt[n][k], At[m][k], acc[ai][bj][m][n], 0, 0, 0); __builtin_amdgcn_s_setprio(0); } while (0)
; #define PG8_WAIT_V(n) asm volatile("s_waitcnt vmcnt(" #n ")" ::: "memory")
; #define PG8_WAIT_L(n) asm volatile("s_waitcnt lgkmcnt(" #n ")" ::: "memory")
; #define PG8_BAR __builtin_amdgcn_s_barrier()
; #define PG8_SCHED __builtin_amdgcn_sched_barrier(0)
; template <class Epi>
; __device__ __forceinline__ void gemm_phase(LAS unsigned char* lds, const Gemm g, const Epi& E) {
;     ...
;             PG8_WAIT_V(6); PG8_BAR; PG8_MMA(1, 1, At, B1); PG8_BAR;
;             PG8_LDB(B0, 1, 0); PG8_SCHED; PG8_LDA(At, 1, 0); PG8_STAGE(PG8_SA(0, 1), a2 + hstep, voffA);
;             PG8_WAIT_L(8); PG8_BAR; PG8_WAIT_L(0); PG8_MMA(0, 0, At, B0); PG8_BAR; PG8_SCHED;
;             PG8_LDB(B1, 1, 1); PG8_STAGE(PG8_SB(1, 0), b3, voffB);
;             PG8_BAR; PG8_WAIT_L(0); PG8_MMA(0, 1, At, B1); PG8_BAR;
;             PG8_LDA(At, 1, 1); PG8_STAGE(PG8_SA(1, 0), a3, voffA);
	s_add_u32 s50, s50, s26
	s_addc_u32 s51, s51, s27
	s_add_i32 s87, s88, s15
	v_lshl_add_u64 v[236:237], s[50:51], 0, v[150:151]
	s_mov_b32 m0, s87
	v_lshl_add_u64 v[238:239], s[50:51], 0, v[146:147]
	global_load_lds_dwordx4 v[236:237], off
	s_add_i32 m0, s87, 0x2000
	s_nop 0
	global_load_lds_dwordx4 v[238:239], off
	s_waitcnt vmcnt(6)
	s_barrier
	s_setprio 1
	v_mfma_f32_16x16x32_bf16 v[54:57], v[220:223], v[158:161], v[54:57]
	v_mfma_f32_16x16x32_bf16 v[50:53], v[228:231], v[158:161], v[50:53]
	v_mfma_f32_16x16x32_bf16 v[38:41], v[220:223], v[172:175], v[38:41]
	v_mfma_f32_16x16x32_bf16 v[34:37], v[228:231], v[172:175], v[34:37]
	v_mfma_f32_16x16x32_bf16 v[22:25], v[220:223], v[198:201], v[22:25]
	v_mfma_f32_16x16x32_bf16 v[18:21], v[228:231], v[198:201], v[18:21]
	v_mfma_f32_16x16x32_bf16 v[4:7], v[220:223], v[206:209], v[4:7]
	v_mfma_f32_16x16x32_bf16 v[0:3], v[228:231], v[206:209], v[0:3]
	v_mfma_f32_16x16x32_bf16 v[54:57], v[224:227], v[168:171], v[54:57]
	v_mfma_f32_16x16x32_bf16 v[50:53], v[232:235], v[168:171], v[50:53]
	v_mfma_f32_16x16x32_bf16 v[38:41], v[224:227], v[194:197], v[38:41]
	v_mfma_f32_16x16x32_bf16 v[34:37], v[232:235], v[194:197], v[34:37]
	v_mfma_f32_16x16x32_bf16 v[22:25], v[224:227], v[202:205], v[22:25]
	v_mfma_f32_16x16x32_bf16 v[18:21], v[232:235], v[202:205], v[18:21]
	v_mfma_f32_16x16x32_bf16 v[4:7], v[224:227], v[210:213], v[4:7]
	v_mfma_f32_16x16x32_bf16 v[0:3], v[232:235], v[210:213], v[0:3]
	s_setprio 0
	s_add_i32 s50, 0, 0x18000
	v_add_u32_e32 v142, s50, v165
	s_barrier
	ds_read_b128 v[130:133], v142
	ds_read_b128 v[134:137], v142 offset:1024
	ds_read_b128 v[138:141], v142 offset:2048
	ds_read_b128 v[142:145], v142 offset:3072
	s_add_u32 s48, s48, s26
	s_addc_u32 s49, s49, s27
	s_mov_b32 m0, s54
	v_lshl_add_u64 v[220:221], s[48:49], 0, v[152:153]
	ds_read_b128 v[158:161], v166 offset:32768
	ds_read_b128 v[168:171], v166 offset:33792
	ds_read_b128 v[172:175], v166 offset:34816
	ds_read_b128 v[194:197], v166 offset:35840
	ds_read_b128 v[198:201], v166 offset:36864
	ds_read_b128 v[202:205], v166 offset:37888
	ds_read_b128 v[206:209], v166 offset:38912
	ds_read_b128 v[210:213], v166 offset:39936
	global_load_lds_dwordx4 v[220:221], off
	v_lshl_add_u64 v[220:221], s[48:49], 0, v[148:149]
	s_mov_b32 m0, s55
	s_nop 0
	global_load_lds_dwordx4 v[220:221], off
	s_waitcnt lgkmcnt(8)
	s_barrier
	s_waitcnt lgkmcnt(0)
	s_setprio 1
	s_waitcnt lgkmcnt(0)
	v_mfma_f32_16x16x32_bf16 v[122:125], v[130:133], v[158:161], v[122:125]
	v_mfma_f32_16x16x32_bf16 v[126:129], v[138:141], v[158:161], v[126:129]
	v_mfma_f32_16x16x32_bf16 v[110:113], v[130:133], v[172:175], v[110:113]
	v_mfma_f32_16x16x32_bf16 v[106:109], v[138:141], v[172:175], v[106:109]
	v_mfma_f32_16x16x32_bf16 v[94:97], v[130:133], v[198:201], v[94:97]
	v_mfma_f32_16x16x32_bf16 v[90:93], v[138:141], v[198:201], v[90:93]
	v_mfma_f32_16x16x32_bf16 v[78:81], v[130:133], v[206:209], v[78:81]
	v_mfma_f32_16x16x32_bf16 v[74:77], v[138:141], v[206:209], v[74:77]
	v_mfma_f32_16x16x32_bf16 v[122:125], v[134:137], v[168:171], v[122:125]
	v_mfma_f32_16x16x32_bf16 v[126:129], v[142:145], v[168:171], v[126:129]
	v_mfma_f32_16x16x32_bf16 v[110:113], v[134:137], v[194:197], v[110:113]
	v_mfma_f32_16x16x32_bf16 v[106:109], v[142:145], v[194:197], v[106:109]
	v_mfma_f32_16x16x32_bf16 v[94:97], v[134:137], v[202:205], v[94:97]
	v_mfma_f32_16x16x32_bf16 v[90:93], v[142:145], v[202:205], v[90:93]
	v_mfma_f32_16x16x32_bf16 v[78:81], v[134:137], v[210:213], v[78:81]
	v_mfma_f32_16x16x32_bf16 v[74:77], v[142:145], v[210:213], v[74:77]
	s_setprio 0
	s_barrier
	s_add_i32 s48, 0, 0x1c000
	s_add_i32 s49, s50, s15
	v_add_u32_e32 v167, s48, v165
	v_lshl_add_u64 v[162:163], v[162:163], 0, s[20:21]
	s_mov_b32 m0, s49
	ds_read_b128 v[220:223], v167
	ds_read_b128 v[224:227], v167 offset:1024
	ds_read_b128 v[228:231], v167 offset:2048
	ds_read_b128 v[232:235], v167 offset:3072
	global_load_lds_dwordx4 v[162:163], off
	v_lshl_add_u64 v[162:163], v[176:177], 0, s[20:21]
	s_add_i32 m0, s49, 0x2000
	s_nop 0
	global_load_lds_dwordx4 v[162:163], off
	s_barrier
; #define PG8_STAGE(bufoff, gbase, voff) do { _Pragma("unroll") for (int _i = 0; _i < 2; ++_i) \
;         __builtin_amdgcn_global_load_lds((const unsigned*)((const char*)(gbase) + (voff)[_i]), (LAS unsigned*)(lds + (bufoff) + ldsw + _i * 8192), 16, 0, 0); } while (0)
; #define PG8_LDA(dst, b, h) do { _Pragma("unroll") for (int m = 0; m < 4; ++m) _Pragma("unroll") for (int k = 0; k < 2; ++k) dst[m][k] = *(const LAS bf16x8*)(lds + PG8_SA(b, h) + aoff + m * 2048 + k * 1024); } while (0)
; #define PG8_MMA(ai, bj, At, Bt) do { __builtin_amdgcn_s_setprio(1); _Pragma("unroll") for (int m = 0; m < 4; ++m) _Pragma("unroll") for (int n = 0; n < 2; ++n) _Pragma("unroll") for (int k = 0; k < 2; ++k) \
;         acc[ai][bj][m][n] = __builtin_amdgcn_mfma_f32_16x16x32_bf16(Bt[n][k], At[m][k], acc[ai][bj][m][n], 0, 0, 0); __builtin_amdgcn_s_setprio(0); } while (0)
; #define PG8_WAIT_V(n) asm volatile("s_waitcnt vmcnt(" #n ")" ::: "memory")
; #define PG8_WAIT_L(n) asm volatile("s_waitcnt lgkmcnt(" #n ")" ::: "memory")
; #define PG8_BAR __builtin_amdgcn_s_barrier()
; #define PG8_SCHED __builtin_amdgcn_sched_barrier(0)
; template <class Epi>
; __device__ __forceinline__ void gemm_phase(LAS unsigned char* lds, const Gemm g, const Epi& E) {
;     ...
;             PG8_BAR; PG8_WAIT_L(0); PG8_MMA(0, 1, At, B1); PG8_BAR;
;             PG8_LDA(At, 1, 1); PG8_STAGE(PG8_SA(1, 0), a3, voffA);
;             PG8_BAR; PG8_WAIT_L(0); PG8_MMA(1, 0, At, B0); PG8_BAR; PG8_SCHED;
;             PG8_STAGE(PG8_SB(1, 1), b3 + hstep, voffB);
;             PG8_WAIT_V(6); PG8_BAR; PG8_MMA(1, 1, At, B1); PG8_BAR;
	s_waitcnt lgkmcnt(0)
	s_setprio 1
	s_waitcnt lgkmcnt(0)
	v_mfma_f32_16x16x32_bf16 v[118:121], v[220:223], v[158:161], v[118:121]
	v_mfma_f32_16x16x32_bf16 v[114:117], v[228:231], v[158:161], v[114:117]
	v_mfma_f32_16x16x32_bf16 v[102:105], v[220:223], v[172:175], v[102:105]
	v_mfma_f32_16x16x32_bf16 v[98:101], v[228:231], v[172:175], v[98:101]
	v_mfma_f32_16x16x32_bf16 v[86:89], v[220:223], v[198:201], v[86:89]
	v_mfma_f32_16x16x32_bf16 v[82:85], v[228:231], v[198:201], v[82:85]
	v_mfma_f32_16x16x32_bf16 v[70:73], v[220:223], v[206:209], v[70:73]
	v_mfma_f32_16x16x32_bf16 v[66:69], v[228:231], v[206:209], v[66:69]
	v_mfma_f32_16x16x32_bf16 v[118:121], v[224:227], v[168:171], v[118:121]
	v_mfma_f32_16x16x32_bf16 v[114:117], v[232:235], v[168:171], v[114:117]
	v_mfma_f32_16x16x32_bf16 v[102:105], v[224:227], v[194:197], v[102:105]
	v_mfma_f32_16x16x32_bf16 v[98:101], v[232:235], v[194:197], v[98:101]
	v_mfma_f32_16x16x32_bf16 v[86:89], v[224:227], v[202:205], v[86:89]
	v_mfma_f32_16x16x32_bf16 v[82:85], v[232:235], v[202:205], v[82:85]
	v_mfma_f32_16x16x32_bf16 v[70:73], v[224:227], v[210:213], v[70:73]
	v_mfma_f32_16x16x32_bf16 v[66:69], v[232:235], v[210:213], v[66:69]
	s_setprio 0
	s_mov_b32 m0, s58
	v_lshl_add_u64 v[162:163], v[186:187], 0, s[20:21]
	s_barrier
	ds_read_b128 v[158:161], v166 offset:49152
	ds_read_b128 v[168:171], v166 offset:50176
	ds_read_b128 v[172:175], v166 offset:51200
	ds_read_b128 v[194:197], v166 offset:52224
	ds_read_b128 v[198:201], v166 offset:53248
	ds_read_b128 v[202:205], v166 offset:54272
	ds_read_b128 v[206:209], v166 offset:55296
	ds_read_b128 v[210:213], v166 offset:56320
	global_load_lds_dwordx4 v[162:163], off
	v_lshl_add_u64 v[162:163], v[188:189], 0, s[20:21]
	s_mov_b32 m0, s59
	s_nop 0
	global_load_lds_dwordx4 v[162:163], off
	s_barrier
	s_waitcnt lgkmcnt(0)
	s_setprio 1
	s_waitcnt lgkmcnt(0)
	v_mfma_f32_16x16x32_bf16 v[62:65], v[130:133], v[158:161], v[62:65]
	v_mfma_f32_16x16x32_bf16 v[58:61], v[138:141], v[158:161], v[58:61]
	v_mfma_f32_16x16x32_bf16 v[46:49], v[130:133], v[172:175], v[46:49]
	v_mfma_f32_16x16x32_bf16 v[42:45], v[138:141], v[172:175], v[42:45]
	v_mfma_f32_16x16x32_bf16 v[30:33], v[130:133], v[198:201], v[30:33]
	v_mfma_f32_16x16x32_bf16 v[26:29], v[138:141], v[198:201], v[26:29]
	v_mfma_f32_16x16x32_bf16 v[14:17], v[130:133], v[206:209], v[14:17]
	v_mfma_f32_16x16x32_bf16 v[8:11], v[138:141], v[206:209], v[8:11]
	v_mfma_f32_16x16x32_bf16 v[62:65], v[134:137], v[168:171], v[62:65]
	v_mfma_f32_16x16x32_bf16 v[58:61], v[142:145], v[168:171], v[58:61]
	v_mfma_f32_16x16x32_bf16 v[46:49], v[134:137], v[194:197], v[46:49]
	v_mfma_f32_16x16x32_bf16 v[42:45], v[142:145], v[194:197], v[42:45]
	v_mfma_f32_16x16x32_bf16 v[30:33], v[134:137], v[202:205], v[30:33]
	v_mfma_f32_16x16x32_bf16 v[26:29], v[142:145], v[202:205], v[26:29]
	v_mfma_f32_16x16x32_bf16 v[14:17], v[134:137], v[210:213], v[14:17]
	v_mfma_f32_16x16x32_bf16 v[8:11], v[142:145], v[210:213], v[8:11]
	s_setprio 0
	s_barrier
	s_add_i32 s48, s48, s15
	v_lshl_add_u64 v[130:131], v[236:237], 0, s[20:21]
	s_mov_b32 m0, s48
	s_nop 0
	global_load_lds_dwordx4 v[130:131], off
	v_lshl_add_u64 v[130:131], v[238:239], 0, s[20:21]
	s_add_i32 m0, s48, 0x2000
	s_nop 0
	global_load_lds_dwordx4 v[130:131], off
	s_waitcnt vmcnt(6)
	s_barrier
	s_setprio 1
	v_mfma_f32_16x16x32_bf16 v[54:57], v[220:223], v[158:161], v[54:57]
	v_mfma_f32_16x16x32_bf16 v[50:53], v[228:231], v[158:161], v[50:53]
	v_mfma_f32_16x16x32_bf16 v[38:41], v[220:223], v[172:175], v[38:41]
	v_mfma_f32_16x16x32_bf16 v[34:37], v[228:231], v[172:175], v[34:37]
	v_mfma_f32_16x16x32_bf16 v[22:25], v[220:223], v[198:201], v[22:25]
	v_mfma_f32_16x16x32_bf16 v[18:21], v[228:231], v[198:201], v[18:21]
	v_mfma_f32_16x16x32_bf16 v[4:7], v[220:223], v[206:209], v[4:7]
	v_mfma_f32_16x16x32_bf16 v[0:3], v[228:231], v[206:209], v[0:3]
	v_mfma_f32_16x16x32_bf16 v[54:57], v[224:227], v[168:171], v[54:57]
	v_mfma_f32_16x16x32_bf16 v[50:53], v[232:235], v[168:171], v[50:53]
	v_mfma_f32_16x16x32_bf16 v[38:41], v[224:227], v[194:197], v[38:41]
	v_mfma_f32_16x16x32_bf16 v[34:37], v[232:235], v[194:197], v[34:37]
	v_mfma_f32_16x16x32_bf16 v[22:25], v[224:227], v[202:205], v[22:25]
	v_mfma_f32_16x16x32_bf16 v[18:21], v[232:235], v[202:205], v[18:21]
	v_mfma_f32_16x16x32_bf16 v[4:7], v[224:227], v[210:213], v[4:7]
	v_mfma_f32_16x16x32_bf16 v[0:3], v[232:235], v[210:213], v[0:3]
	s_setprio 0
	s_add_u32 s46, s46, 0x100
	s_addc_u32 s47, s47, 0
	s_add_u32 s84, s84, 0x100
	s_addc_u32 s85, s85, 0
	s_cmp_ge_i32 s86, s2
	s_mov_b32 s48, s86
	s_barrier
	s_cbranch_scc0 .LBB0_351
	s_nop 0
	s_nop 0
	s_nop 0
	s_nop 0
	s_nop 0
	s_nop 0
	s_nop 0
	s_nop 0
	s_nop 0
	s_nop 0
	s_nop 0
	s_nop 0
	s_nop 0
	s_nop 0
	s_nop 0
	s_nop 0
	s_nop 0
	s_nop 0
	s_nop 0
	s_nop 0
	s_nop 0
	s_nop 0
	s_branch .LBB0_342

; template <class Epi>
; __device__ __forceinline__ void gemm_phase(LAS unsigned char* lds, const Gemm g, const Epi& E) {
;     ...
;         if (!has_next) break;
; #pragma unroll
;         for (int a = 0; a < 2; ++a)
; #pragma unroll
;             for (int b = 0; b < 2; ++b)
; #pragma unroll
;                 for (int m = 0; m < 4; ++m)
; #pragma unroll
;                     for (int n = 0; n < 2; ++n) acc[a][b][m][n] = (f32x4){0.f, 0.f, 0.f, 0.f};
;         cur = nxt; cA = nA; cB = nB; ++ui;
.LBB0_514:
	v_mov_b32_e32 v145, 0
	s_andn2_b64 vcc, exec, s[48:49]
	v_mov_b32_e32 v144, v145
	v_mov_b32_e32 v143, v145
	v_mov_b32_e32 v142, v145
	v_mov_b32_e32 v141, v145
	v_mov_b32_e32 v140, v145
	v_mov_b32_e32 v139, v145
	v_mov_b32_e32 v138, v145
	v_mov_b32_e32 v129, v145
	v_mov_b32_e32 v128, v145
	v_mov_b32_e32 v127, v145
	v_mov_b32_e32 v126, v145
	v_mov_b32_e32 v125, v145
	v_mov_b32_e32 v124, v145
	v_mov_b32_e32 v123, v145
	v_mov_b32_e32 v122, v145
	v_mov_b32_e32 v113, v145
	v_mov_b32_e32 v112, v145
	v_mov_b32_e32 v111, v145
	v_mov_b32_e32 v110, v145
	v_mov_b32_e32 v109, v145
	v_mov_b32_e32 v108, v145
	v_mov_b32_e32 v107, v145
	v_mov_b32_e32 v106, v145
	v_mov_b32_e32 v97, v145
	v_mov_b32_e32 v96, v145
	v_mov_b32_e32 v95, v145
	v_mov_b32_e32 v94, v145
	v_mov_b32_e32 v93, v145
	v_mov_b32_e32 v92, v145
	v_mov_b32_e32 v91, v145
	v_mov_b32_e32 v90, v145
	v_mov_b32_e32 v137, v145
	v_mov_b32_e32 v136, v145
	v_mov_b32_e32 v135, v145
	v_mov_b32_e32 v134, v145
	v_mov_b32_e32 v133, v145
	v_mov_b32_e32 v132, v145
	v_mov_b32_e32 v131, v145
	v_mov_b32_e32 v130, v145
	v_mov_b32_e32 v121, v145
	v_mov_b32_e32 v120, v145
	v_mov_b32_e32 v119, v145
	v_mov_b32_e32 v118, v145
	v_mov_b32_e32 v117, v145
	v_mov_b32_e32 v116, v145
	v_mov_b32_e32 v115, v145
	v_mov_b32_e32 v114, v145
	v_mov_b32_e32 v105, v145
	v_mov_b32_e32 v104, v145
	v_mov_b32_e32 v103, v145
	v_mov_b32_e32 v102, v145
	v_mov_b32_e32 v101, v145
	v_mov_b32_e32 v100, v145
	v_mov_b32_e32 v99, v145
	v_mov_b32_e32 v98, v145
	v_mov_b32_e32 v89, v145
	v_mov_b32_e32 v88, v145
	v_mov_b32_e32 v87, v145
	v_mov_b32_e32 v86, v145
	v_mov_b32_e32 v85, v145
	v_mov_b32_e32 v84, v145
	v_mov_b32_e32 v83, v145
	v_mov_b32_e32 v82, v145
	v_mov_b32_e32 v81, v145
	v_mov_b32_e32 v80, v145
	v_mov_b32_e32 v79, v145
	v_mov_b32_e32 v78, v145
	v_mov_b32_e32 v77, v145
	v_mov_b32_e32 v76, v145
	v_mov_b32_e32 v75, v145
	v_mov_b32_e32 v74, v145
	s_waitcnt vmcnt(0)
	v_mov_b32_e32 v49, v145
	v_mov_b32_e32 v48, v145
	v_mov_b32_e32 v47, v145
	v_mov_b32_e32 v46, v145
	v_mov_b32_e32 v45, v145
	v_mov_b32_e32 v44, v145
	v_mov_b32_e32 v43, v145
	v_mov_b32_e32 v42, v145
	v_mov_b32_e32 v33, v145
	v_mov_b32_e32 v32, v145
	v_mov_b32_e32 v31, v145
	v_mov_b32_e32 v30, v145
	v_mov_b32_e32 v29, v145
	v_mov_b32_e32 v28, v145
	v_mov_b32_e32 v27, v145
	v_mov_b32_e32 v26, v145
	v_mov_b32_e32 v17, v145
	v_mov_b32_e32 v16, v145
	v_mov_b32_e32 v15, v145
	v_mov_b32_e32 v14, v145
	v_mov_b32_e32 v11, v145
	v_mov_b32_e32 v10, v145
	v_mov_b32_e32 v9, v145
	v_mov_b32_e32 v8, v145
	v_mov_b32_e32 v65, v145
	v_mov_b32_e32 v64, v145
	v_mov_b32_e32 v63, v145
	v_mov_b32_e32 v62, v145
	v_mov_b32_e32 v61, v145
	v_mov_b32_e32 v60, v145
	v_mov_b32_e32 v59, v145
	v_mov_b32_e32 v58, v145
	v_mov_b32_e32 v41, v145
	v_mov_b32_e32 v40, v145
	v_mov_b32_e32 v39, v145
	v_mov_b32_e32 v38, v145
	v_mov_b32_e32 v37, v145
	v_mov_b32_e32 v36, v145
	v_mov_b32_e32 v35, v145
	v_mov_b32_e32 v34, v145
	v_mov_b32_e32 v25, v145
	v_mov_b32_e32 v24, v145
	v_mov_b32_e32 v23, v145
	v_mov_b32_e32 v22, v145
	v_mov_b32_e32 v21, v145
	v_mov_b32_e32 v20, v145
	v_mov_b32_e32 v19, v145
	v_mov_b32_e32 v18, v145
	v_mov_b32_e32 v7, v145
	v_mov_b32_e32 v6, v145
	v_mov_b32_e32 v5, v145
	v_mov_b32_e32 v4, v145
	v_mov_b32_e32 v3, v145
	v_mov_b32_e32 v2, v145
	v_mov_b32_e32 v1, v145
	v_mov_b32_e32 v0, v145
	s_cbranch_vccnz .LBB0_517
	s_add_u32 s38, s52, 0x80
	s_addc_u32 s39, s53, 0
	s_add_u32 s86, s40, 0x100
	v_mov_b32_e32 v0, 0
	s_addc_u32 s87, s41, 0
	s_mov_b32 s40, 0
	v_mov_b32_e32 v1, v0
	v_mov_b32_e32 v2, v0
	v_mov_b32_e32 v3, v0
	v_mov_b32_e32 v4, v0
	v_mov_b32_e32 v5, v0
	v_mov_b32_e32 v6, v0
	v_mov_b32_e32 v7, v0
	v_mov_b32_e32 v18, v0
	v_mov_b32_e32 v19, v0
	v_mov_b32_e32 v20, v0
	v_mov_b32_e32 v21, v0
	v_mov_b32_e32 v22, v0
	v_mov_b32_e32 v23, v0
	v_mov_b32_e32 v24, v0
	v_mov_b32_e32 v25, v0
	v_mov_b32_e32 v34, v0
	v_mov_b32_e32 v35, v0
	v_mov_b32_e32 v36, v0
	v_mov_b32_e32 v37, v0
	v_mov_b32_e32 v38, v0
	v_mov_b32_e32 v39, v0
	v_mov_b32_e32 v40, v0
	v_mov_b32_e32 v41, v0
	v_mov_b32_e32 v58, v0
	v_mov_b32_e32 v59, v0
	v_mov_b32_e32 v60, v0
	v_mov_b32_e32 v61, v0
	v_mov_b32_e32 v62, v0
	v_mov_b32_e32 v63, v0
	v_mov_b32_e32 v64, v0
	v_mov_b32_e32 v65, v0
	v_mov_b32_e32 v8, v0
	v_mov_b32_e32 v9, v0
	v_mov_b32_e32 v10, v0
	v_mov_b32_e32 v11, v0
	v_mov_b32_e32 v14, v0
	v_mov_b32_e32 v15, v0
	v_mov_b32_e32 v16, v0
	v_mov_b32_e32 v17, v0
	v_mov_b32_e32 v26, v0
	v_mov_b32_e32 v27, v0
	v_mov_b32_e32 v28, v0
	v_mov_b32_e32 v29, v0
	v_mov_b32_e32 v30, v0
	v_mov_b32_e32 v31, v0
	v_mov_b32_e32 v32, v0
	v_mov_b32_e32 v33, v0
	v_mov_b32_e32 v42, v0
	v_mov_b32_e32 v43, v0
	v_mov_b32_e32 v44, v0
	v_mov_b32_e32 v45, v0
	v_mov_b32_e32 v46, v0
	v_mov_b32_e32 v47, v0
	v_mov_b32_e32 v48, v0
	v_mov_b32_e32 v49, v0
	v_mov_b32_e32 v74, v0
	v_mov_b32_e32 v75, v0
	v_mov_b32_e32 v76, v0
	v_mov_b32_e32 v77, v0
	v_mov_b32_e32 v78, v0
	v_mov_b32_e32 v79, v0
	v_mov_b32_e32 v80, v0
	v_mov_b32_e32 v81, v0
	v_mov_b32_e32 v82, v0
	v_mov_b32_e32 v83, v0
	v_mov_b32_e32 v84, v0
	v_mov_b32_e32 v85, v0
	v_mov_b32_e32 v86, v0
	v_mov_b32_e32 v87, v0
	v_mov_b32_e32 v88, v0
	v_mov_b32_e32 v89, v0
	v_mov_b32_e32 v98, v0
	v_mov_b32_e32 v99, v0
	v_mov_b32_e32 v100, v0
	v_mov_b32_e32 v101, v0
	v_mov_b32_e32 v102, v0
	v_mov_b32_e32 v103, v0
	v_mov_b32_e32 v104, v0
	v_mov_b32_e32 v105, v0
	v_mov_b32_e32 v114, v0
	v_mov_b32_e32 v115, v0
	v_mov_b32_e32 v116, v0
	v_mov_b32_e32 v117, v0
	v_mov_b32_e32 v118, v0
	v_mov_b32_e32 v119, v0
	v_mov_b32_e32 v120, v0
	v_mov_b32_e32 v121, v0
	v_mov_b32_e32 v130, v0
	v_mov_b32_e32 v131, v0
	v_mov_b32_e32 v132, v0
	v_mov_b32_e32 v133, v0
	v_mov_b32_e32 v134, v0
	v_mov_b32_e32 v135, v0
	v_mov_b32_e32 v136, v0
	v_mov_b32_e32 v137, v0
	v_mov_b32_e32 v90, v0
	v_mov_b32_e32 v91, v0
	v_mov_b32_e32 v92, v0
	v_mov_b32_e32 v93, v0
	v_mov_b32_e32 v94, v0
	v_mov_b32_e32 v95, v0
	v_mov_b32_e32 v96, v0
	v_mov_b32_e32 v97, v0
	v_mov_b32_e32 v106, v0
	v_mov_b32_e32 v107, v0
	v_mov_b32_e32 v108, v0
	v_mov_b32_e32 v109, v0
	v_mov_b32_e32 v110, v0
	v_mov_b32_e32 v111, v0
	v_mov_b32_e32 v112, v0
	v_mov_b32_e32 v113, v0
	v_mov_b32_e32 v122, v0
	v_mov_b32_e32 v123, v0
	v_mov_b32_e32 v124, v0
	v_mov_b32_e32 v125, v0
	v_mov_b32_e32 v126, v0
	v_mov_b32_e32 v127, v0
	v_mov_b32_e32 v128, v0
	v_mov_b32_e32 v129, v0
	v_mov_b32_e32 v138, v0
	v_mov_b32_e32 v139, v0
	v_mov_b32_e32 v140, v0
	v_mov_b32_e32 v141, v0
	v_mov_b32_e32 v142, v0
	v_mov_b32_e32 v143, v0
	v_mov_b32_e32 v144, v0
	v_mov_b32_e32 v145, v0
	s_nop 0
	s_nop 0
	s_nop 0
	s_nop 0
	s_nop 0
	s_nop 0
	s_nop 0
	s_nop 0
	s_nop 0
	s_nop 0
	s_nop 0
	s_nop 0
	s_nop 0
	s_nop 0
	s_nop 0
	s_nop 0
	s_nop 0
	s_nop 0
	s_nop 0
	s_nop 0
	s_nop 0
	s_nop 0
	s_nop 0
	s_nop 0
	s_nop 0
	s_nop 0
	s_nop 0
	s_nop 0
	s_nop 0
	s_nop 0
	s_nop 0
	s_nop 0
	s_nop 0
	s_nop 0
	s_nop 0
	s_nop 0
	s_nop 0
	s_nop 0
	s_nop 0
	s_nop 0
	s_nop 0
	s_nop 0
	s_nop 0
	s_nop 0
	s_nop 0
	s_nop 0
	s_nop 0
	s_nop 0
	s_nop 0
	s_nop 0
	s_nop 0
; #define PG8_STAGE(bufoff, gbase, voff) do { _Pragma("unroll") for (int _i = 0; _i < 2; ++_i) \
;         __builtin_amdgcn_global_load_lds((const unsigned*)((const char*)(gbase) + (voff)[_i]), (LAS unsigned*)(lds + (bufoff) + ldsw + _i * 8192), 16, 0, 0); } while (0)
; #define PG8_LDA(dst, b, h) do { _Pragma("unroll") for (int m = 0; m < 4; ++m) _Pragma("unroll") for (int k = 0; k < 2; ++k) dst[m][k] = *(const LAS bf16x8*)(lds + PG8_SA(b, h) + aoff + m * 2048 + k * 1024); } while (0)
; #define PG8_LDB(dst, b, h) do { _Pragma("unroll") for (int n = 0; n < 2; ++n) _Pragma("unroll") for (int k = 0; k < 2; ++k) dst[n][k] = *(const LAS bf16x8*)(lds + PG8_SB(b, h) + boff + n * 2048 + k * 1024); } while (0)
; #define PG8_MMA(ai, bj, At, Bt) do { __builtin_amdgcn_s_setprio(1); _Pragma("unroll") for (int m = 0; m < 4; ++m) _Pragma("unroll") for (int n = 0; n < 2; ++n) _Pragma("unroll") for (int k = 0; k < 2; ++k) \
;         acc[ai][bj][m][n] = __builtin_amdgcn_mfma_f32_16x16x32_bf16(Bt[n][k], At[m][k], acc[ai][bj][m][n], 0, 0, 0); __builtin_amdgcn_s_setprio(0); } while (0)
; template <class Epi>
; __device__ __forceinline__ void gemm_phase(LAS unsigned char* lds, const Gemm g, const Epi& E) {
;     ...
;         for (int t = 0; t < nt; t += 2) {
;             const bool last = (t == nt - 2);
;             const char* a1 = cA + (size_t)(t + 1) * kstep;
;             const char* a2 = last ? nA : cA + (size_t)(t + 2) * kstep; const char* b2 = last ? nB : cB + (size_t)(t + 2) * kstep;
;             const char* a3 = a2 + kstep; const char* b3 = b2 + kstep;
;             PG8_LDB(B0, 0, 0); PG8_SCHED; PG8_LDA(At, 0, 0); PG8_STAGE(PG8_SA(1, 1), a1 + hstep, voffA);
;             PG8_WAIT_L(8); PG8_BAR; PG8_WAIT_L(0); PG8_MMA(0, 0, At, B0); PG8_BAR; PG8_SCHED;
;             PG8_LDB(B1, 0, 1); PG8_STAGE(PG8_SB(0, 0), b2, voffB);
;             PG8_BAR; PG8_WAIT_L(0); PG8_MMA(0, 1, At, B1); PG8_BAR;
;             PG8_LDA(At, 0, 1); PG8_STAGE(PG8_SA(0, 0), a2, voffA);
;             PG8_BAR; PG8_WAIT_L(0); PG8_MMA(1, 0, At, B0); PG8_BAR; PG8_SCHED;
;             PG8_STAGE(PG8_SB(0, 1), b2 + hstep, voffB);
;             PG8_WAIT_V(6); PG8_BAR; PG8_MMA(1, 1, At, B1); PG8_BAR;
;             PG8_LDB(B0, 1, 0); PG8_SCHED; PG8_LDA(At, 1, 0); PG8_STAGE(PG8_SA(0, 1), a2 + hstep, voffA);
;             PG8_WAIT_L(8); PG8_BAR; PG8_WAIT_L(0); PG8_MMA(0, 0, At, B0); PG8_BAR; PG8_SCHED;
.LBB0_516:
	s_add_i32 s88, s40, 2
	s_add_u32 s52, s38, 0x80
	s_addc_u32 s41, s39, 0
	s_add_i32 s89, 0, 0x10000
	v_add_u32_e32 v70, s89, v167
	ds_read_b128 v[50:53], v70
	ds_read_b128 v[54:57], v70 offset:1024
	ds_read_b128 v[66:69], v70 offset:2048
	ds_read_b128 v[70:73], v70 offset:3072
	s_cmp_eq_u32 s82, s40
	s_cselect_b32 s40, s0, s52
	s_cselect_b32 s41, s1, s41
	s_cselect_b32 s53, s51, s87
	s_cselect_b32 s52, s50, s86
	v_lshl_add_u64 v[186:187], s[38:39], 0, v[154:155]
	s_add_i32 m0, s57, 0xc000
	ds_read_b128 v[158:161], v168
	ds_read_b128 v[162:165], v168 offset:1024
	ds_read_b128 v[170:173], v168 offset:2048
	ds_read_b128 v[174:177], v168 offset:3072
	ds_read_b128 v[194:197], v168 offset:4096
	ds_read_b128 v[198:201], v168 offset:5120
	ds_read_b128 v[202:205], v168 offset:6144
	ds_read_b128 v[206:209], v168 offset:7168
	global_load_lds_dwordx4 v[186:187], off
	v_lshl_add_u64 v[186:187], s[38:39], 0, v[156:157]
	s_add_i32 m0, s57, 0xe000
	s_nop 0
	global_load_lds_dwordx4 v[186:187], off
	s_waitcnt lgkmcnt(8)
	s_barrier
	s_waitcnt lgkmcnt(0)
	s_setprio 1
	s_waitcnt lgkmcnt(0)
	v_mfma_f32_16x16x32_bf16 v[142:145], v[50:53], v[158:161], v[142:145]
	v_mfma_f32_16x16x32_bf16 v[138:141], v[66:69], v[158:161], v[138:141]
	v_mfma_f32_16x16x32_bf16 v[126:129], v[50:53], v[170:173], v[126:129]
	v_mfma_f32_16x16x32_bf16 v[122:125], v[66:69], v[170:173], v[122:125]
	v_mfma_f32_16x16x32_bf16 v[110:113], v[50:53], v[194:197], v[110:113]
	v_mfma_f32_16x16x32_bf16 v[106:109], v[66:69], v[194:197], v[106:109]
	v_mfma_f32_16x16x32_bf16 v[94:97], v[50:53], v[202:205], v[94:97]
	v_mfma_f32_16x16x32_bf16 v[90:93], v[66:69], v[202:205], v[90:93]
	v_mfma_f32_16x16x32_bf16 v[142:145], v[54:57], v[162:165], v[142:145]
	v_mfma_f32_16x16x32_bf16 v[138:141], v[70:73], v[162:165], v[138:141]
	v_mfma_f32_16x16x32_bf16 v[126:129], v[54:57], v[174:177], v[126:129]
	v_mfma_f32_16x16x32_bf16 v[122:125], v[70:73], v[174:177], v[122:125]
	v_mfma_f32_16x16x32_bf16 v[110:113], v[54:57], v[198:201], v[110:113]
	v_mfma_f32_16x16x32_bf16 v[106:109], v[70:73], v[198:201], v[106:109]
	v_mfma_f32_16x16x32_bf16 v[94:97], v[54:57], v[206:209], v[94:97]
	v_mfma_f32_16x16x32_bf16 v[90:93], v[70:73], v[206:209], v[90:93]
	s_setprio 0
	s_barrier
	s_add_i32 s90, 0, 0x14000
	s_add_i32 s89, s89, s56
	v_add_u32_e32 v169, s90, v167
	v_lshl_add_u64 v[186:187], s[52:53], 0, v[148:149]
	s_mov_b32 m0, s89
	ds_read_b128 v[210:213], v169
	ds_read_b128 v[220:223], v169 offset:1024
	ds_read_b128 v[224:227], v169 offset:2048
	ds_read_b128 v[228:231], v169 offset:3072
	global_load_lds_dwordx4 v[186:187], off
	v_lshl_add_u64 v[188:189], s[52:53], 0, v[152:153]
	s_add_i32 m0, s89, 0x2000
	s_nop 0
	global_load_lds_dwordx4 v[188:189], off
	s_barrier
	s_waitcnt lgkmcnt(0)
	s_setprio 1
	s_waitcnt lgkmcnt(0)
	v_mfma_f32_16x16x32_bf16 v[134:137], v[210:213], v[158:161], v[134:137]
	v_mfma_f32_16x16x32_bf16 v[130:133], v[224:227], v[158:161], v[130:133]
	v_mfma_f32_16x16x32_bf16 v[118:121], v[210:213], v[170:173], v[118:121]
	v_mfma_f32_16x16x32_bf16 v[114:117], v[224:227], v[170:173], v[114:117]
	v_mfma_f32_16x16x32_bf16 v[102:105], v[210:213], v[194:197], v[102:105]
	v_mfma_f32_16x16x32_bf16 v[98:101], v[224:227], v[194:197], v[98:101]
	v_mfma_f32_16x16x32_bf16 v[86:89], v[210:213], v[202:205], v[86:89]
	v_mfma_f32_16x16x32_bf16 v[82:85], v[224:227], v[202:205], v[82:85]
	v_mfma_f32_16x16x32_bf16 v[134:137], v[220:223], v[162:165], v[134:137]
	v_mfma_f32_16x16x32_bf16 v[130:133], v[228:231], v[162:165], v[130:133]
	v_mfma_f32_16x16x32_bf16 v[118:121], v[220:223], v[174:177], v[118:121]
	v_mfma_f32_16x16x32_bf16 v[114:117], v[228:231], v[174:177], v[114:117]
	v_mfma_f32_16x16x32_bf16 v[102:105], v[220:223], v[198:201], v[102:105]
	v_mfma_f32_16x16x32_bf16 v[98:101], v[228:231], v[198:201], v[98:101]
	v_mfma_f32_16x16x32_bf16 v[86:89], v[220:223], v[206:209], v[86:89]
	v_mfma_f32_16x16x32_bf16 v[82:85], v[228:231], v[206:209], v[82:85]
	s_setprio 0
	s_mov_b32 m0, s57
	v_lshl_add_u64 v[232:233], s[40:41], 0, v[146:147]
	s_barrier
	ds_read_b128 v[158:161], v168 offset:16384
	ds_read_b128 v[162:165], v168 offset:17408
	ds_read_b128 v[170:173], v168 offset:18432
	ds_read_b128 v[174:177], v168 offset:19456
	ds_read_b128 v[194:197], v168 offset:20480
	ds_read_b128 v[198:201], v168 offset:21504
	ds_read_b128 v[202:205], v168 offset:22528
	ds_read_b128 v[206:209], v168 offset:23552
	global_load_lds_dwordx4 v[232:233], off
	v_lshl_add_u64 v[234:235], s[40:41], 0, v[150:151]
	s_mov_b32 m0, s58
	s_nop 0
	global_load_lds_dwordx4 v[234:235], off
	s_barrier
	s_waitcnt lgkmcnt(0)
	s_setprio 1
	s_waitcnt lgkmcnt(0)
	v_mfma_f32_16x16x32_bf16 v[78:81], v[50:53], v[158:161], v[78:81]
	v_mfma_f32_16x16x32_bf16 v[74:77], v[66:69], v[158:161], v[74:77]
	v_mfma_f32_16x16x32_bf16 v[46:49], v[50:53], v[170:173], v[46:49]
	v_mfma_f32_16x16x32_bf16 v[42:45], v[66:69], v[170:173], v[42:45]
	v_mfma_f32_16x16x32_bf16 v[30:33], v[50:53], v[194:197], v[30:33]
	v_mfma_f32_16x16x32_bf16 v[26:29], v[66:69], v[194:197], v[26:29]
	v_mfma_f32_16x16x32_bf16 v[14:17], v[50:53], v[202:205], v[14:17]
	v_mfma_f32_16x16x32_bf16 v[8:11], v[66:69], v[202:205], v[8:11]
	v_mfma_f32_16x16x32_bf16 v[78:81], v[54:57], v[162:165], v[78:81]
	v_mfma_f32_16x16x32_bf16 v[74:77], v[70:73], v[162:165], v[74:77]
	v_mfma_f32_16x16x32_bf16 v[46:49], v[54:57], v[174:177], v[46:49]
	v_mfma_f32_16x16x32_bf16 v[42:45], v[70:73], v[174:177], v[42:45]
	v_mfma_f32_16x16x32_bf16 v[30:33], v[54:57], v[198:201], v[30:33]
	v_mfma_f32_16x16x32_bf16 v[26:29], v[70:73], v[198:201], v[26:29]
	v_mfma_f32_16x16x32_bf16 v[14:17], v[54:57], v[206:209], v[14:17]
	v_mfma_f32_16x16x32_bf16 v[8:11], v[70:73], v[206:209], v[8:11]
	s_setprio 0
	s_barrier
; #define PG8_STAGE(bufoff, gbase, voff) do { _Pragma("unroll") for (int _i = 0; _i < 2; ++_i) \
;         __builtin_amdgcn_global_load_lds((const unsigned*)((const char*)(gbase) + (voff)[_i]), (LAS unsigned*)(lds + (bufoff) + ldsw + _i * 8192), 16, 0, 0); } while (0)
; #define PG8_LDA(dst, b, h) do { _Pragma("unroll") for (int m = 0; m < 4; ++m) _Pragma("unroll") for (int k = 0; k < 2; ++k) dst[m][k] = *(const LAS bf16x8*)(lds + PG8_SA(b, h) + aoff + m * 2048 + k * 1024); } while (0)
; #define PG8_LDB(dst, b, h) do { _Pragma("unroll") for (int n = 0; n < 2; ++n) _Pragma("unroll") for (int k = 0; k < 2; ++k) dst[n][k] = *(const LAS bf16x8*)(lds + PG8_SB(b, h) + boff + n * 2048 + k * 1024); } while (0)
; #define PG8_MMA(ai, bj, At, Bt) do { __builtin_amdgcn_s_setprio(1); _Pragma("unroll") for (int m = 0; m < 4; ++m) _Pragma("unroll") for (int n = 0; n < 2; ++n) _Pragma("unroll") for (int k = 0; k < 2; ++k) \
;         acc[ai][bj][m][n] = __builtin_amdgcn_mfma_f32_16x16x32_bf16(Bt[n][k], At[m][k], acc[ai][bj][m][n], 0, 0, 0); __builtin_amdgcn_s_setprio(0); } while (0)
; #define PG8_WAIT_V(n) asm volatile("s_waitcnt vmcnt(" #n ")" ::: "memory")
; #define PG8_WAIT_L(n) asm volatile("s_waitcnt lgkmcnt(" #n ")" ::: "memory")
; #define PG8_BAR __builtin_amdgcn_s_barrier()
; #define PG8_SCHED __builtin_amdgcn_sched_barrier(0)
; template <class Epi>
; __device__ __forceinline__ void gemm_phase(LAS unsigned char* lds, const Gemm g, const Epi& E) {
;     ...
;             PG8_WAIT_V(6); PG8_BAR; PG8_MMA(1, 1, At, B1); PG8_BAR;
;             PG8_LDB(B0, 1, 0); PG8_SCHED; PG8_LDA(At, 1, 0); PG8_STAGE(PG8_SA(0, 1), a2 + hstep, voffA);
;             PG8_WAIT_L(8); PG8_BAR; PG8_WAIT_L(0); PG8_MMA(0, 0, At, B0); PG8_BAR; PG8_SCHED;
;             PG8_LDB(B1, 1, 1); PG8_STAGE(PG8_SB(1, 0), b3, voffB);
;             PG8_BAR; PG8_WAIT_L(0); PG8_MMA(0, 1, At, B1); PG8_BAR;
;             PG8_LDA(At, 1, 1); PG8_STAGE(PG8_SA(1, 0), a3, voffA);
	s_add_u32 s52, s52, s26
	s_addc_u32 s53, s53, s27
	s_add_i32 s89, s90, s56
	v_lshl_add_u64 v[236:237], s[52:53], 0, v[148:149]
	s_mov_b32 m0, s89
	v_lshl_add_u64 v[238:239], s[52:53], 0, v[152:153]
	global_load_lds_dwordx4 v[236:237], off
	s_add_i32 m0, s89, 0x2000
	s_nop 0
	global_load_lds_dwordx4 v[238:239], off
	s_waitcnt vmcnt(6)
	s_barrier
	s_setprio 1
	v_mfma_f32_16x16x32_bf16 v[38:41], v[210:213], v[170:173], v[38:41]
	v_mfma_f32_16x16x32_bf16 v[34:37], v[224:227], v[170:173], v[34:37]
	v_mfma_f32_16x16x32_bf16 v[22:25], v[210:213], v[194:197], v[22:25]
	v_mfma_f32_16x16x32_bf16 v[18:21], v[224:227], v[194:197], v[18:21]
	v_mfma_f32_16x16x32_bf16 v[4:7], v[210:213], v[202:205], v[4:7]
	v_mfma_f32_16x16x32_bf16 v[0:3], v[224:227], v[202:205], v[0:3]
	v_mfma_f32_16x16x32_bf16 v[50:53], v[210:213], v[158:161], v[62:65]
	v_mfma_f32_16x16x32_bf16 v[54:57], v[224:227], v[158:161], v[58:61]
	v_mfma_f32_16x16x32_bf16 v[38:41], v[220:223], v[174:177], v[38:41]
	v_mfma_f32_16x16x32_bf16 v[34:37], v[228:231], v[174:177], v[34:37]
	v_mfma_f32_16x16x32_bf16 v[22:25], v[220:223], v[198:201], v[22:25]
	v_mfma_f32_16x16x32_bf16 v[18:21], v[228:231], v[198:201], v[18:21]
	v_mfma_f32_16x16x32_bf16 v[4:7], v[220:223], v[206:209], v[4:7]
	v_mfma_f32_16x16x32_bf16 v[0:3], v[228:231], v[206:209], v[0:3]
	v_mfma_f32_16x16x32_bf16 v[50:53], v[220:223], v[162:165], v[50:53]
	v_mfma_f32_16x16x32_bf16 v[54:57], v[228:231], v[162:165], v[54:57]
	s_setprio 0
	s_add_i32 s52, 0, 0x18000
	v_add_u32_e32 v70, s52, v167
	s_barrier
	ds_read_b128 v[58:61], v70
	ds_read_b128 v[62:65], v70 offset:1024
	ds_read_b128 v[66:69], v70 offset:2048
	ds_read_b128 v[70:73], v70 offset:3072
	s_add_u32 s40, s40, s26
	s_addc_u32 s41, s41, s27
	s_mov_b32 m0, s14
	v_lshl_add_u64 v[210:211], s[40:41], 0, v[146:147]
	ds_read_b128 v[158:161], v168 offset:32768
	ds_read_b128 v[162:165], v168 offset:33792
	ds_read_b128 v[170:173], v168 offset:34816
	ds_read_b128 v[174:177], v168 offset:35840
	ds_read_b128 v[194:197], v168 offset:36864
	ds_read_b128 v[198:201], v168 offset:37888
	ds_read_b128 v[202:205], v168 offset:38912
	ds_read_b128 v[206:209], v168 offset:39936
	global_load_lds_dwordx4 v[210:211], off
	v_lshl_add_u64 v[210:211], s[40:41], 0, v[150:151]
	s_mov_b32 m0, s15
	s_nop 0
	global_load_lds_dwordx4 v[210:211], off
	s_waitcnt lgkmcnt(8)
	s_barrier
	s_waitcnt lgkmcnt(0)
	s_setprio 1
	s_waitcnt lgkmcnt(0)
	v_mfma_f32_16x16x32_bf16 v[142:145], v[58:61], v[158:161], v[142:145]
	v_mfma_f32_16x16x32_bf16 v[138:141], v[66:69], v[158:161], v[138:141]
	v_mfma_f32_16x16x32_bf16 v[126:129], v[58:61], v[170:173], v[126:129]
	v_mfma_f32_16x16x32_bf16 v[122:125], v[66:69], v[170:173], v[122:125]
	v_mfma_f32_16x16x32_bf16 v[110:113], v[58:61], v[194:197], v[110:113]
	v_mfma_f32_16x16x32_bf16 v[106:109], v[66:69], v[194:197], v[106:109]
	v_mfma_f32_16x16x32_bf16 v[94:97], v[58:61], v[202:205], v[94:97]
	v_mfma_f32_16x16x32_bf16 v[90:93], v[66:69], v[202:205], v[90:93]
	v_mfma_f32_16x16x32_bf16 v[142:145], v[62:65], v[162:165], v[142:145]
	v_mfma_f32_16x16x32_bf16 v[138:141], v[70:73], v[162:165], v[138:141]
	v_mfma_f32_16x16x32_bf16 v[126:129], v[62:65], v[174:177], v[126:129]
	v_mfma_f32_16x16x32_bf16 v[122:125], v[70:73], v[174:177], v[122:125]
	v_mfma_f32_16x16x32_bf16 v[110:113], v[62:65], v[198:201], v[110:113]
	v_mfma_f32_16x16x32_bf16 v[106:109], v[70:73], v[198:201], v[106:109]
	v_mfma_f32_16x16x32_bf16 v[94:97], v[62:65], v[206:209], v[94:97]
	v_mfma_f32_16x16x32_bf16 v[90:93], v[70:73], v[206:209], v[90:93]
	s_setprio 0
	s_barrier
	s_add_i32 s40, 0, 0x1c000
	s_add_i32 s41, s52, s56
	v_add_u32_e32 v169, s40, v167
	v_lshl_add_u64 v[186:187], v[186:187], 0, s[20:21]
	s_mov_b32 m0, s41
	ds_read_b128 v[210:213], v169
	ds_read_b128 v[220:223], v169 offset:1024
	ds_read_b128 v[224:227], v169 offset:2048
	ds_read_b128 v[228:231], v169 offset:3072
	global_load_lds_dwordx4 v[186:187], off
	v_lshl_add_u64 v[186:187], v[188:189], 0, s[20:21]
	s_add_i32 m0, s41, 0x2000
	s_nop 0
	global_load_lds_dwordx4 v[186:187], off
	s_barrier
; #define PG8_STAGE(bufoff, gbase, voff) do { _Pragma("unroll") for (int _i = 0; _i < 2; ++_i) \
;         __builtin_amdgcn_global_load_lds((const unsigned*)((const char*)(gbase) + (voff)[_i]), (LAS unsigned*)(lds + (bufoff) + ldsw + _i * 8192), 16, 0, 0); } while (0)
; #define PG8_LDA(dst, b, h) do { _Pragma("unroll") for (int m = 0; m < 4; ++m) _Pragma("unroll") for (int k = 0; k < 2; ++k) dst[m][k] = *(const LAS bf16x8*)(lds + PG8_SA(b, h) + aoff + m * 2048 + k * 1024); } while (0)
; #define PG8_MMA(ai, bj, At, Bt) do { __builtin_amdgcn_s_setprio(1); _Pragma("unroll") for (int m = 0; m < 4; ++m) _Pragma("unroll") for (int n = 0; n < 2; ++n) _Pragma("unroll") for (int k = 0; k < 2; ++k) \
;         acc[ai][bj][m][n] = __builtin_amdgcn_mfma_f32_16x16x32_bf16(Bt[n][k], At[m][k], acc[ai][bj][m][n], 0, 0, 0); __builtin_amdgcn_s_setprio(0); } while (0)
; #define PG8_WAIT_V(n) asm volatile("s_waitcnt vmcnt(" #n ")" ::: "memory")
; #define PG8_WAIT_L(n) asm volatile("s_waitcnt lgkmcnt(" #n ")" ::: "memory")
; #define PG8_BAR __builtin_amdgcn_s_barrier()
; #define PG8_SCHED __builtin_amdgcn_sched_barrier(0)
; template <class Epi>
; __device__ __forceinline__ void gemm_phase(LAS unsigned char* lds, const Gemm g, const Epi& E) {
;     ...
;             PG8_BAR; PG8_WAIT_L(0); PG8_MMA(0, 1, At, B1); PG8_BAR;
;             PG8_LDA(At, 1, 1); PG8_STAGE(PG8_SA(1, 0), a3, voffA);
;             PG8_BAR; PG8_WAIT_L(0); PG8_MMA(1, 0, At, B0); PG8_BAR; PG8_SCHED;
;             PG8_STAGE(PG8_SB(1, 1), b3 + hstep, voffB);
;             PG8_WAIT_V(6); PG8_BAR; PG8_MMA(1, 1, At, B1); PG8_BAR;
	s_waitcnt lgkmcnt(0)
	s_setprio 1
	s_waitcnt lgkmcnt(0)
	v_mfma_f32_16x16x32_bf16 v[134:137], v[210:213], v[158:161], v[134:137]
	v_mfma_f32_16x16x32_bf16 v[130:133], v[224:227], v[158:161], v[130:133]
	v_mfma_f32_16x16x32_bf16 v[118:121], v[210:213], v[170:173], v[118:121]
	v_mfma_f32_16x16x32_bf16 v[114:117], v[224:227], v[170:173], v[114:117]
	v_mfma_f32_16x16x32_bf16 v[102:105], v[210:213], v[194:197], v[102:105]
	v_mfma_f32_16x16x32_bf16 v[98:101], v[224:227], v[194:197], v[98:101]
	v_mfma_f32_16x16x32_bf16 v[86:89], v[210:213], v[202:205], v[86:89]
	v_mfma_f32_16x16x32_bf16 v[82:85], v[224:227], v[202:205], v[82:85]
	v_mfma_f32_16x16x32_bf16 v[134:137], v[220:223], v[162:165], v[134:137]
	v_mfma_f32_16x16x32_bf16 v[130:133], v[228:231], v[162:165], v[130:133]
	v_mfma_f32_16x16x32_bf16 v[118:121], v[220:223], v[174:177], v[118:121]
	v_mfma_f32_16x16x32_bf16 v[114:117], v[228:231], v[174:177], v[114:117]
	v_mfma_f32_16x16x32_bf16 v[102:105], v[220:223], v[198:201], v[102:105]
	v_mfma_f32_16x16x32_bf16 v[98:101], v[228:231], v[198:201], v[98:101]
	v_mfma_f32_16x16x32_bf16 v[86:89], v[220:223], v[206:209], v[86:89]
	v_mfma_f32_16x16x32_bf16 v[82:85], v[228:231], v[206:209], v[82:85]
	s_setprio 0
	s_mov_b32 m0, s59
	v_lshl_add_u64 v[186:187], v[232:233], 0, s[20:21]
	s_barrier
	ds_read_b128 v[158:161], v168 offset:49152
	ds_read_b128 v[162:165], v168 offset:50176
	ds_read_b128 v[170:173], v168 offset:51200
	ds_read_b128 v[174:177], v168 offset:52224
	ds_read_b128 v[194:197], v168 offset:53248
	ds_read_b128 v[198:201], v168 offset:54272
	ds_read_b128 v[202:205], v168 offset:55296
	ds_read_b128 v[206:209], v168 offset:56320
	global_load_lds_dwordx4 v[186:187], off
	v_lshl_add_u64 v[186:187], v[234:235], 0, s[20:21]
	s_mov_b32 m0, s60
	s_nop 0
	global_load_lds_dwordx4 v[186:187], off
	s_barrier
	s_waitcnt lgkmcnt(0)
	s_setprio 1
	s_waitcnt lgkmcnt(0)
	v_mfma_f32_16x16x32_bf16 v[78:81], v[58:61], v[158:161], v[78:81]
	v_mfma_f32_16x16x32_bf16 v[74:77], v[66:69], v[158:161], v[74:77]
	v_mfma_f32_16x16x32_bf16 v[46:49], v[58:61], v[170:173], v[46:49]
	v_mfma_f32_16x16x32_bf16 v[42:45], v[66:69], v[170:173], v[42:45]
	v_mfma_f32_16x16x32_bf16 v[30:33], v[58:61], v[194:197], v[30:33]
	v_mfma_f32_16x16x32_bf16 v[26:29], v[66:69], v[194:197], v[26:29]
	v_mfma_f32_16x16x32_bf16 v[14:17], v[58:61], v[202:205], v[14:17]
	v_mfma_f32_16x16x32_bf16 v[8:11], v[66:69], v[202:205], v[8:11]
	v_mfma_f32_16x16x32_bf16 v[78:81], v[62:65], v[162:165], v[78:81]
	v_mfma_f32_16x16x32_bf16 v[74:77], v[70:73], v[162:165], v[74:77]
	v_mfma_f32_16x16x32_bf16 v[46:49], v[62:65], v[174:177], v[46:49]
	v_mfma_f32_16x16x32_bf16 v[42:45], v[70:73], v[174:177], v[42:45]
	v_mfma_f32_16x16x32_bf16 v[30:33], v[62:65], v[198:201], v[30:33]
	v_mfma_f32_16x16x32_bf16 v[26:29], v[70:73], v[198:201], v[26:29]
	v_mfma_f32_16x16x32_bf16 v[14:17], v[62:65], v[206:209], v[14:17]
	v_mfma_f32_16x16x32_bf16 v[8:11], v[70:73], v[206:209], v[8:11]
	s_setprio 0
	s_barrier
	s_add_i32 s40, s40, s56
	v_lshl_add_u64 v[58:59], v[236:237], 0, s[20:21]
	s_mov_b32 m0, s40
	s_nop 0
	global_load_lds_dwordx4 v[58:59], off
	v_lshl_add_u64 v[58:59], v[238:239], 0, s[20:21]
	s_add_i32 m0, s40, 0x2000
	s_nop 0
	global_load_lds_dwordx4 v[58:59], off
	s_waitcnt vmcnt(6)
	s_barrier
	s_setprio 1
	v_mfma_f32_16x16x32_bf16 v[50:53], v[210:213], v[158:161], v[50:53]
	v_mfma_f32_16x16x32_bf16 v[62:65], v[220:223], v[162:165], v[50:53]
	v_mfma_f32_16x16x32_bf16 v[50:53], v[224:227], v[158:161], v[54:57]
	v_mfma_f32_16x16x32_bf16 v[38:41], v[210:213], v[170:173], v[38:41]
	v_mfma_f32_16x16x32_bf16 v[34:37], v[224:227], v[170:173], v[34:37]
	v_mfma_f32_16x16x32_bf16 v[22:25], v[210:213], v[194:197], v[22:25]
	v_mfma_f32_16x16x32_bf16 v[18:21], v[224:227], v[194:197], v[18:21]
	v_mfma_f32_16x16x32_bf16 v[4:7], v[210:213], v[202:205], v[4:7]
	v_mfma_f32_16x16x32_bf16 v[0:3], v[224:227], v[202:205], v[0:3]
	v_mfma_f32_16x16x32_bf16 v[58:61], v[228:231], v[162:165], v[50:53]
	v_mfma_f32_16x16x32_bf16 v[38:41], v[220:223], v[174:177], v[38:41]
	v_mfma_f32_16x16x32_bf16 v[34:37], v[228:231], v[174:177], v[34:37]
	v_mfma_f32_16x16x32_bf16 v[22:25], v[220:223], v[198:201], v[22:25]
	v_mfma_f32_16x16x32_bf16 v[18:21], v[228:231], v[198:201], v[18:21]
	v_mfma_f32_16x16x32_bf16 v[4:7], v[220:223], v[206:209], v[4:7]
	v_mfma_f32_16x16x32_bf16 v[0:3], v[228:231], v[206:209], v[0:3]
	s_setprio 0
	s_add_u32 s38, s38, 0x100
	s_addc_u32 s39, s39, 0
	s_add_u32 s86, s86, 0x100
	s_addc_u32 s87, s87, 0
	s_cmp_ge_i32 s88, s61
	s_mov_b32 s40, s88
	s_barrier
	s_cbranch_scc0 .LBB0_516
	s_nop 0
	s_nop 0
	s_nop 0
	s_nop 0
	s_nop 0
	s_nop 0
	s_nop 0
	s_nop 0
	s_nop 0
	s_nop 0
	s_nop 0
	s_nop 0
	s_nop 0

; template <class Epi>
; __device__ __forceinline__ void gemm_phase(LAS unsigned char* lds, const Gemm g, const Epi& E) {
;     ...
;         if (!has_next) break;
; #pragma unroll
;         for (int a = 0; a < 2; ++a)
; #pragma unroll
;             for (int b = 0; b < 2; ++b)
; #pragma unroll
;                 for (int m = 0; m < 4; ++m)
; #pragma unroll
;                     for (int n = 0; n < 2; ++n) acc[a][b][m][n] = (f32x4){0.f, 0.f, 0.f, 0.f};
;         cur = nxt; cA = nA; cB = nB; ++ui;
.LBB0_668:
	v_mov_b32_e32 v145, 0
	s_andn2_b64 vcc, exec, s[44:45]
	v_mov_b32_e32 v144, v145
	v_mov_b32_e32 v143, v145
	v_mov_b32_e32 v142, v145
	v_mov_b32_e32 v141, v145
	v_mov_b32_e32 v140, v145
	v_mov_b32_e32 v139, v145
	v_mov_b32_e32 v138, v145
	v_mov_b32_e32 v129, v145
	v_mov_b32_e32 v128, v145
	v_mov_b32_e32 v127, v145
	v_mov_b32_e32 v126, v145
	v_mov_b32_e32 v125, v145
	v_mov_b32_e32 v124, v145
	v_mov_b32_e32 v123, v145
	v_mov_b32_e32 v122, v145
	v_mov_b32_e32 v113, v145
	v_mov_b32_e32 v112, v145
	v_mov_b32_e32 v111, v145
	v_mov_b32_e32 v110, v145
	v_mov_b32_e32 v109, v145
	v_mov_b32_e32 v108, v145
	v_mov_b32_e32 v107, v145
	v_mov_b32_e32 v106, v145
	v_mov_b32_e32 v97, v145
	v_mov_b32_e32 v96, v145
	v_mov_b32_e32 v95, v145
	v_mov_b32_e32 v94, v145
	v_mov_b32_e32 v93, v145
	v_mov_b32_e32 v92, v145
	v_mov_b32_e32 v91, v145
	v_mov_b32_e32 v90, v145
	v_mov_b32_e32 v137, v145
	v_mov_b32_e32 v136, v145
	v_mov_b32_e32 v135, v145
	v_mov_b32_e32 v134, v145
	v_mov_b32_e32 v133, v145
	v_mov_b32_e32 v132, v145
	v_mov_b32_e32 v131, v145
	v_mov_b32_e32 v130, v145
	v_mov_b32_e32 v121, v145
	v_mov_b32_e32 v120, v145
	v_mov_b32_e32 v119, v145
	v_mov_b32_e32 v118, v145
	v_mov_b32_e32 v117, v145
	v_mov_b32_e32 v116, v145
	v_mov_b32_e32 v115, v145
	v_mov_b32_e32 v114, v145
	v_mov_b32_e32 v105, v145
	v_mov_b32_e32 v104, v145
	v_mov_b32_e32 v103, v145
	v_mov_b32_e32 v102, v145
	v_mov_b32_e32 v101, v145
	v_mov_b32_e32 v100, v145
	v_mov_b32_e32 v99, v145
	v_mov_b32_e32 v98, v145
	v_mov_b32_e32 v89, v145
	v_mov_b32_e32 v88, v145
	v_mov_b32_e32 v87, v145
	v_mov_b32_e32 v86, v145
	v_mov_b32_e32 v85, v145
	v_mov_b32_e32 v84, v145
	v_mov_b32_e32 v83, v145
	v_mov_b32_e32 v82, v145
	v_mov_b32_e32 v81, v145
	v_mov_b32_e32 v80, v145
	v_mov_b32_e32 v79, v145
	v_mov_b32_e32 v78, v145
	v_mov_b32_e32 v77, v145
	v_mov_b32_e32 v76, v145
	v_mov_b32_e32 v75, v145
	v_mov_b32_e32 v74, v145
	s_waitcnt vmcnt(0)
	v_mov_b32_e32 v61, v145
	v_mov_b32_e32 v60, v145
	v_mov_b32_e32 v59, v145
	v_mov_b32_e32 v58, v145
	v_mov_b32_e32 v53, v145
	v_mov_b32_e32 v52, v145
	v_mov_b32_e32 v51, v145
	v_mov_b32_e32 v50, v145
	v_mov_b32_e32 v33, v145
	v_mov_b32_e32 v32, v145
	v_mov_b32_e32 v31, v145
	v_mov_b32_e32 v30, v145
	v_mov_b32_e32 v29, v145
	v_mov_b32_e32 v28, v145
	v_mov_b32_e32 v27, v145
	v_mov_b32_e32 v26, v145
	v_mov_b32_e32 v17, v145
	v_mov_b32_e32 v16, v145
	v_mov_b32_e32 v15, v145
	v_mov_b32_e32 v14, v145
	v_mov_b32_e32 v11, v145
	v_mov_b32_e32 v10, v145
	v_mov_b32_e32 v9, v145
	v_mov_b32_e32 v8, v145
	v_mov_b32_e32 v73, v145
	v_mov_b32_e32 v72, v145
	v_mov_b32_e32 v71, v145
	v_mov_b32_e32 v70, v145
	v_mov_b32_e32 v69, v145
	v_mov_b32_e32 v68, v145
	v_mov_b32_e32 v67, v145
	v_mov_b32_e32 v66, v145
	v_mov_b32_e32 v45, v145
	v_mov_b32_e32 v44, v145
	v_mov_b32_e32 v43, v145
	v_mov_b32_e32 v42, v145
	v_mov_b32_e32 v37, v145
	v_mov_b32_e32 v36, v145
	v_mov_b32_e32 v35, v145
	v_mov_b32_e32 v34, v145
	v_mov_b32_e32 v25, v145
	v_mov_b32_e32 v24, v145
	v_mov_b32_e32 v23, v145
	v_mov_b32_e32 v22, v145
	v_mov_b32_e32 v21, v145
	v_mov_b32_e32 v20, v145
	v_mov_b32_e32 v19, v145
	v_mov_b32_e32 v18, v145
	v_mov_b32_e32 v7, v145
	v_mov_b32_e32 v6, v145
	v_mov_b32_e32 v5, v145
	v_mov_b32_e32 v4, v145
	v_mov_b32_e32 v3, v145
	v_mov_b32_e32 v2, v145
	v_mov_b32_e32 v1, v145
	v_mov_b32_e32 v0, v145
	s_cbranch_vccnz .LBB0_657
	s_add_u32 s46, s46, 0x80
	s_addc_u32 s47, s47, 0
	s_add_u32 s84, s48, 0x100
	v_mov_b32_e32 v0, 0
	s_addc_u32 s85, s49, 0
	s_mov_b32 s48, 0
	v_mov_b32_e32 v1, v0
	v_mov_b32_e32 v2, v0
	v_mov_b32_e32 v3, v0
	v_mov_b32_e32 v4, v0
	v_mov_b32_e32 v5, v0
	v_mov_b32_e32 v6, v0
	v_mov_b32_e32 v7, v0
	v_mov_b32_e32 v18, v0
	v_mov_b32_e32 v19, v0
	v_mov_b32_e32 v20, v0
	v_mov_b32_e32 v21, v0
	v_mov_b32_e32 v22, v0
	v_mov_b32_e32 v23, v0
	v_mov_b32_e32 v24, v0
	v_mov_b32_e32 v25, v0
	v_mov_b32_e32 v34, v0
	v_mov_b32_e32 v35, v0
	v_mov_b32_e32 v36, v0
	v_mov_b32_e32 v37, v0
	v_mov_b32_e32 v42, v0
	v_mov_b32_e32 v43, v0
	v_mov_b32_e32 v44, v0
	v_mov_b32_e32 v45, v0
	v_mov_b32_e32 v66, v0
	v_mov_b32_e32 v67, v0
	v_mov_b32_e32 v68, v0
	v_mov_b32_e32 v69, v0
	v_mov_b32_e32 v70, v0
	v_mov_b32_e32 v71, v0
	v_mov_b32_e32 v72, v0
	v_mov_b32_e32 v73, v0
	v_mov_b32_e32 v8, v0
	v_mov_b32_e32 v9, v0
	v_mov_b32_e32 v10, v0
	v_mov_b32_e32 v11, v0
	v_mov_b32_e32 v14, v0
	v_mov_b32_e32 v15, v0
	v_mov_b32_e32 v16, v0
	v_mov_b32_e32 v17, v0
	v_mov_b32_e32 v26, v0
	v_mov_b32_e32 v27, v0
	v_mov_b32_e32 v28, v0
	v_mov_b32_e32 v29, v0
	v_mov_b32_e32 v30, v0
	v_mov_b32_e32 v31, v0
	v_mov_b32_e32 v32, v0
	v_mov_b32_e32 v33, v0
	v_mov_b32_e32 v50, v0
	v_mov_b32_e32 v51, v0
	v_mov_b32_e32 v52, v0
	v_mov_b32_e32 v53, v0
	v_mov_b32_e32 v58, v0
	v_mov_b32_e32 v59, v0
	v_mov_b32_e32 v60, v0
	v_mov_b32_e32 v61, v0
	v_mov_b32_e32 v74, v0
	v_mov_b32_e32 v75, v0
	v_mov_b32_e32 v76, v0
	v_mov_b32_e32 v77, v0
	v_mov_b32_e32 v78, v0
	v_mov_b32_e32 v79, v0
	v_mov_b32_e32 v80, v0
	v_mov_b32_e32 v81, v0
	v_mov_b32_e32 v82, v0
	v_mov_b32_e32 v83, v0
	v_mov_b32_e32 v84, v0
	v_mov_b32_e32 v85, v0
	v_mov_b32_e32 v86, v0
	v_mov_b32_e32 v87, v0
	v_mov_b32_e32 v88, v0
	v_mov_b32_e32 v89, v0
	v_mov_b32_e32 v98, v0
	v_mov_b32_e32 v99, v0
	v_mov_b32_e32 v100, v0
	v_mov_b32_e32 v101, v0
	v_mov_b32_e32 v102, v0
	v_mov_b32_e32 v103, v0
	v_mov_b32_e32 v104, v0
	v_mov_b32_e32 v105, v0
	v_mov_b32_e32 v114, v0
	v_mov_b32_e32 v115, v0
	v_mov_b32_e32 v116, v0
	v_mov_b32_e32 v117, v0
	v_mov_b32_e32 v118, v0
	v_mov_b32_e32 v119, v0
	v_mov_b32_e32 v120, v0
	v_mov_b32_e32 v121, v0
	v_mov_b32_e32 v130, v0
	v_mov_b32_e32 v131, v0
	v_mov_b32_e32 v132, v0
	v_mov_b32_e32 v133, v0
	v_mov_b32_e32 v134, v0
	v_mov_b32_e32 v135, v0
	v_mov_b32_e32 v136, v0
	v_mov_b32_e32 v137, v0
	v_mov_b32_e32 v90, v0
	v_mov_b32_e32 v91, v0
	v_mov_b32_e32 v92, v0
	v_mov_b32_e32 v93, v0
	v_mov_b32_e32 v94, v0
	v_mov_b32_e32 v95, v0
	v_mov_b32_e32 v96, v0
	v_mov_b32_e32 v97, v0
	v_mov_b32_e32 v106, v0
	v_mov_b32_e32 v107, v0
	v_mov_b32_e32 v108, v0
	v_mov_b32_e32 v109, v0
	v_mov_b32_e32 v110, v0
	v_mov_b32_e32 v111, v0
	v_mov_b32_e32 v112, v0
	v_mov_b32_e32 v113, v0
	v_mov_b32_e32 v122, v0
	v_mov_b32_e32 v123, v0
	v_mov_b32_e32 v124, v0
	v_mov_b32_e32 v125, v0
	v_mov_b32_e32 v126, v0
	v_mov_b32_e32 v127, v0
	v_mov_b32_e32 v128, v0
	v_mov_b32_e32 v129, v0
	v_mov_b32_e32 v138, v0
	v_mov_b32_e32 v139, v0
	v_mov_b32_e32 v140, v0
	v_mov_b32_e32 v141, v0
	v_mov_b32_e32 v142, v0
	v_mov_b32_e32 v143, v0
	v_mov_b32_e32 v144, v0
	v_mov_b32_e32 v145, v0
	s_nop 0
	s_nop 0
	s_nop 0
	s_nop 0
	s_nop 0
	s_nop 0
	s_nop 0
	s_nop 0
	s_nop 0
	s_nop 0
	s_nop 0
	s_nop 0
	s_nop 0
	s_nop 0
	s_nop 0
	s_nop 0
	s_nop 0
	s_nop 0
	s_nop 0
	s_nop 0
	s_nop 0
	s_nop 0
; #define PG8_STAGE(bufoff, gbase, voff) do { _Pragma("unroll") for (int _i = 0; _i < 2; ++_i) \
;         __builtin_amdgcn_global_load_lds((const unsigned*)((const char*)(gbase) + (voff)[_i]), (LAS unsigned*)(lds + (bufoff) + ldsw + _i * 8192), 16, 0, 0); } while (0)
; #define PG8_LDA(dst, b, h) do { _Pragma("unroll") for (int m = 0; m < 4; ++m) _Pragma("unroll") for (int k = 0; k < 2; ++k) dst[m][k] = *(const LAS bf16x8*)(lds + PG8_SA(b, h) + aoff + m * 2048 + k * 1024); } while (0)
; #define PG8_LDB(dst, b, h) do { _Pragma("unroll") for (int n = 0; n < 2; ++n) _Pragma("unroll") for (int k = 0; k < 2; ++k) dst[n][k] = *(const LAS bf16x8*)(lds + PG8_SB(b, h) + boff + n * 2048 + k * 1024); } while (0)
; #define PG8_MMA(ai, bj, At, Bt) do { __builtin_amdgcn_s_setprio(1); _Pragma("unroll") for (int m = 0; m < 4; ++m) _Pragma("unroll") for (int n = 0; n < 2; ++n) _Pragma("unroll") for (int k = 0; k < 2; ++k) \
;         acc[ai][bj][m][n] = __builtin_amdgcn_mfma_f32_16x16x32_bf16(Bt[n][k], At[m][k], acc[ai][bj][m][n], 0, 0, 0); __builtin_amdgcn_s_setprio(0); } while (0)
; template <class Epi>
; __device__ __forceinline__ void gemm_phase(LAS unsigned char* lds, const Gemm g, const Epi& E) {
;     ...
;         for (int t = 0; t < nt; t += 2) {
;             const bool last = (t == nt - 2);
;             const char* a1 = cA + (size_t)(t + 1) * kstep;
;             const char* a2 = last ? nA : cA + (size_t)(t + 2) * kstep; const char* b2 = last ? nB : cB + (size_t)(t + 2) * kstep;
;             const char* a3 = a2 + kstep; const char* b3 = b2 + kstep;
;             PG8_LDB(B0, 0, 0); PG8_SCHED; PG8_LDA(At, 0, 0); PG8_STAGE(PG8_SA(1, 1), a1 + hstep, voffA);
;             PG8_WAIT_L(8); PG8_BAR; PG8_WAIT_L(0); PG8_MMA(0, 0, At, B0); PG8_BAR; PG8_SCHED;
;             PG8_LDB(B1, 0, 1); PG8_STAGE(PG8_SB(0, 0), b2, voffB);
;             PG8_BAR; PG8_WAIT_L(0); PG8_MMA(0, 1, At, B1); PG8_BAR;
;             PG8_LDA(At, 0, 1); PG8_STAGE(PG8_SA(0, 0), a2, voffA);
;             PG8_BAR; PG8_WAIT_L(0); PG8_MMA(1, 0, At, B0); PG8_BAR; PG8_SCHED;
;             PG8_STAGE(PG8_SB(0, 1), b2 + hstep, voffB);
;             PG8_WAIT_V(6); PG8_BAR; PG8_MMA(1, 1, At, B1); PG8_BAR;
;             PG8_LDB(B0, 1, 0); PG8_SCHED; PG8_LDA(At, 1, 0); PG8_STAGE(PG8_SA(0, 1), a2 + hstep, voffA);
;             PG8_WAIT_L(8); PG8_BAR; PG8_WAIT_L(0); PG8_MMA(0, 0, At, B0); PG8_BAR; PG8_SCHED;
.LBB0_670:
	s_add_i32 s86, s48, 2
	s_add_u32 s50, s46, 0x80
	s_addc_u32 s49, s47, 0
	s_add_i32 s87, 0, 0x10000
	v_add_u32_e32 v62, s87, v220
	ds_read_b128 v[38:41], v62
	ds_read_b128 v[46:49], v62 offset:1024
	ds_read_b128 v[54:57], v62 offset:2048
	ds_read_b128 v[62:65], v62 offset:3072
	s_cmp_eq_u32 s17, s48
	s_cselect_b32 s48, s0, s50
	s_cselect_b32 s49, s1, s49
	s_cselect_b32 s51, s39, s85
	s_cselect_b32 s50, s38, s84
	v_lshl_add_u64 v[186:187], s[46:47], 0, v[202:203]
	s_add_i32 m0, s54, 0xc000
	ds_read_b128 v[146:149], v221
	ds_read_b128 v[150:153], v221 offset:1024
	ds_read_b128 v[154:157], v221 offset:2048
	ds_read_b128 v[158:161], v221 offset:3072
	ds_read_b128 v[162:165], v221 offset:4096
	ds_read_b128 v[166:169], v221 offset:5120
	ds_read_b128 v[170:173], v221 offset:6144
	ds_read_b128 v[174:177], v221 offset:7168
	global_load_lds_dwordx4 v[186:187], off
	v_lshl_add_u64 v[186:187], s[46:47], 0, v[204:205]
	s_add_i32 m0, s54, 0xe000
	s_nop 0
	global_load_lds_dwordx4 v[186:187], off
	s_waitcnt lgkmcnt(8)
	s_barrier
	s_waitcnt lgkmcnt(0)
	s_setprio 1
	s_waitcnt lgkmcnt(0)
	v_mfma_f32_16x16x32_bf16 v[142:145], v[38:41], v[146:149], v[142:145]
	v_mfma_f32_16x16x32_bf16 v[138:141], v[54:57], v[146:149], v[138:141]
	v_mfma_f32_16x16x32_bf16 v[126:129], v[38:41], v[154:157], v[126:129]
	v_mfma_f32_16x16x32_bf16 v[122:125], v[54:57], v[154:157], v[122:125]
	v_mfma_f32_16x16x32_bf16 v[110:113], v[38:41], v[162:165], v[110:113]
	v_mfma_f32_16x16x32_bf16 v[106:109], v[54:57], v[162:165], v[106:109]
	v_mfma_f32_16x16x32_bf16 v[94:97], v[38:41], v[170:173], v[94:97]
	v_mfma_f32_16x16x32_bf16 v[90:93], v[54:57], v[170:173], v[90:93]
	v_mfma_f32_16x16x32_bf16 v[142:145], v[46:49], v[150:153], v[142:145]
	v_mfma_f32_16x16x32_bf16 v[138:141], v[62:65], v[150:153], v[138:141]
	v_mfma_f32_16x16x32_bf16 v[126:129], v[46:49], v[158:161], v[126:129]
	v_mfma_f32_16x16x32_bf16 v[122:125], v[62:65], v[158:161], v[122:125]
	v_mfma_f32_16x16x32_bf16 v[110:113], v[46:49], v[166:169], v[110:113]
	v_mfma_f32_16x16x32_bf16 v[106:109], v[62:65], v[166:169], v[106:109]
	v_mfma_f32_16x16x32_bf16 v[94:97], v[46:49], v[174:177], v[94:97]
	v_mfma_f32_16x16x32_bf16 v[90:93], v[62:65], v[174:177], v[90:93]
	s_setprio 0
	s_barrier
	s_add_i32 s88, 0, 0x14000
	v_add_u32_e32 v186, s88, v220
	s_add_i32 s87, s87, s53
	ds_read_b128 v[206:209], v186
	ds_read_b128 v[210:213], v186 offset:1024
	ds_read_b128 v[222:225], v186 offset:2048
	ds_read_b128 v[226:229], v186 offset:3072
	v_lshl_add_u64 v[186:187], s[50:51], 0, v[196:197]
	s_mov_b32 m0, s87
	v_lshl_add_u64 v[188:189], s[50:51], 0, v[200:201]
	global_load_lds_dwordx4 v[186:187], off
	s_add_i32 m0, s87, 0x2000
	s_nop 0
	global_load_lds_dwordx4 v[188:189], off
	s_barrier
	s_waitcnt lgkmcnt(0)
	s_setprio 1
	s_waitcnt lgkmcnt(0)
	v_mfma_f32_16x16x32_bf16 v[134:137], v[206:209], v[146:149], v[134:137]
	v_mfma_f32_16x16x32_bf16 v[130:133], v[222:225], v[146:149], v[130:133]
	v_mfma_f32_16x16x32_bf16 v[118:121], v[206:209], v[154:157], v[118:121]
	v_mfma_f32_16x16x32_bf16 v[114:117], v[222:225], v[154:157], v[114:117]
	v_mfma_f32_16x16x32_bf16 v[102:105], v[206:209], v[162:165], v[102:105]
	v_mfma_f32_16x16x32_bf16 v[98:101], v[222:225], v[162:165], v[98:101]
	v_mfma_f32_16x16x32_bf16 v[86:89], v[206:209], v[170:173], v[86:89]
	v_mfma_f32_16x16x32_bf16 v[82:85], v[222:225], v[170:173], v[82:85]
	v_mfma_f32_16x16x32_bf16 v[134:137], v[210:213], v[150:153], v[134:137]
	v_mfma_f32_16x16x32_bf16 v[130:133], v[226:229], v[150:153], v[130:133]
	v_mfma_f32_16x16x32_bf16 v[118:121], v[210:213], v[158:161], v[118:121]
	v_mfma_f32_16x16x32_bf16 v[114:117], v[226:229], v[158:161], v[114:117]
	v_mfma_f32_16x16x32_bf16 v[102:105], v[210:213], v[166:169], v[102:105]
	v_mfma_f32_16x16x32_bf16 v[98:101], v[226:229], v[166:169], v[98:101]
	v_mfma_f32_16x16x32_bf16 v[86:89], v[210:213], v[174:177], v[86:89]
	v_mfma_f32_16x16x32_bf16 v[82:85], v[226:229], v[174:177], v[82:85]
	s_setprio 0
	s_mov_b32 m0, s54
	v_lshl_add_u64 v[230:231], s[48:49], 0, v[194:195]
	s_barrier
	ds_read_b128 v[146:149], v221 offset:16384
	ds_read_b128 v[150:153], v221 offset:17408
	ds_read_b128 v[154:157], v221 offset:18432
	ds_read_b128 v[158:161], v221 offset:19456
	ds_read_b128 v[162:165], v221 offset:20480
	ds_read_b128 v[166:169], v221 offset:21504
	ds_read_b128 v[170:173], v221 offset:22528
	ds_read_b128 v[174:177], v221 offset:23552
	global_load_lds_dwordx4 v[230:231], off
	v_lshl_add_u64 v[232:233], s[48:49], 0, v[198:199]
	s_mov_b32 m0, s55
	s_nop 0
	global_load_lds_dwordx4 v[232:233], off
	s_barrier
	s_waitcnt lgkmcnt(0)
	s_setprio 1
	s_waitcnt lgkmcnt(0)
	v_mfma_f32_16x16x32_bf16 v[78:81], v[38:41], v[146:149], v[78:81]
	v_mfma_f32_16x16x32_bf16 v[74:77], v[54:57], v[146:149], v[74:77]
	v_mfma_f32_16x16x32_bf16 v[58:61], v[38:41], v[154:157], v[58:61]
	v_mfma_f32_16x16x32_bf16 v[50:53], v[54:57], v[154:157], v[50:53]
	v_mfma_f32_16x16x32_bf16 v[30:33], v[38:41], v[162:165], v[30:33]
	v_mfma_f32_16x16x32_bf16 v[26:29], v[54:57], v[162:165], v[26:29]
	v_mfma_f32_16x16x32_bf16 v[14:17], v[38:41], v[170:173], v[14:17]
	v_mfma_f32_16x16x32_bf16 v[8:11], v[54:57], v[170:173], v[8:11]
	v_mfma_f32_16x16x32_bf16 v[78:81], v[46:49], v[150:153], v[78:81]
	v_mfma_f32_16x16x32_bf16 v[74:77], v[62:65], v[150:153], v[74:77]
	v_mfma_f32_16x16x32_bf16 v[58:61], v[46:49], v[158:161], v[58:61]
	v_mfma_f32_16x16x32_bf16 v[50:53], v[62:65], v[158:161], v[50:53]
	v_mfma_f32_16x16x32_bf16 v[30:33], v[46:49], v[166:169], v[30:33]
	v_mfma_f32_16x16x32_bf16 v[26:29], v[62:65], v[166:169], v[26:29]
	v_mfma_f32_16x16x32_bf16 v[14:17], v[46:49], v[174:177], v[14:17]
	v_mfma_f32_16x16x32_bf16 v[8:11], v[62:65], v[174:177], v[8:11]
	s_setprio 0
	s_barrier
; #define PG8_STAGE(bufoff, gbase, voff) do { _Pragma("unroll") for (int _i = 0; _i < 2; ++_i) \
;         __builtin_amdgcn_global_load_lds((const unsigned*)((const char*)(gbase) + (voff)[_i]), (LAS unsigned*)(lds + (bufoff) + ldsw + _i * 8192), 16, 0, 0); } while (0)
; #define PG8_LDA(dst, b, h) do { _Pragma("unroll") for (int m = 0; m < 4; ++m) _Pragma("unroll") for (int k = 0; k < 2; ++k) dst[m][k] = *(const LAS bf16x8*)(lds + PG8_SA(b, h) + aoff + m * 2048 + k * 1024); } while (0)
; #define PG8_LDB(dst, b, h) do { _Pragma("unroll") for (int n = 0; n < 2; ++n) _Pragma("unroll") for (int k = 0; k < 2; ++k) dst[n][k] = *(const LAS bf16x8*)(lds + PG8_SB(b, h) + boff + n * 2048 + k * 1024); } while (0)
; #define PG8_MMA(ai, bj, At, Bt) do { __builtin_amdgcn_s_setprio(1); _Pragma("unroll") for (int m = 0; m < 4; ++m) _Pragma("unroll") for (int n = 0; n < 2; ++n) _Pragma("unroll") for (int k = 0; k < 2; ++k) \
;         acc[ai][bj][m][n] = __builtin_amdgcn_mfma_f32_16x16x32_bf16(Bt[n][k], At[m][k], acc[ai][bj][m][n], 0, 0, 0); __builtin_amdgcn_s_setprio(0); } while (0)
; #define PG8_WAIT_V(n) asm volatile("s_waitcnt vmcnt(" #n ")" ::: "memory")
; #define PG8_WAIT_L(n) asm volatile("s_waitcnt lgkmcnt(" #n ")" ::: "memory")
; #define PG8_BAR __builtin_amdgcn_s_barrier()
; #define PG8_SCHED __builtin_amdgcn_sched_barrier(0)
; template <class Epi>
; __device__ __forceinline__ void gemm_phase(LAS unsigned char* lds, const Gemm g, const Epi& E) {
;     ...
;             PG8_WAIT_V(6); PG8_BAR; PG8_MMA(1, 1, At, B1); PG8_BAR;
;             PG8_LDB(B0, 1, 0); PG8_SCHED; PG8_LDA(At, 1, 0); PG8_STAGE(PG8_SA(0, 1), a2 + hstep, voffA);
;             PG8_WAIT_L(8); PG8_BAR; PG8_WAIT_L(0); PG8_MMA(0, 0, At, B0); PG8_BAR; PG8_SCHED;
;             PG8_LDB(B1, 1, 1); PG8_STAGE(PG8_SB(1, 0), b3, voffB);
;             PG8_BAR; PG8_WAIT_L(0); PG8_MMA(0, 1, At, B1); PG8_BAR;
;             PG8_LDA(At, 1, 1); PG8_STAGE(PG8_SA(1, 0), a3, voffA);
	s_add_u32 s50, s50, s40
	s_addc_u32 s51, s51, s41
	s_add_i32 s87, s88, s53
	v_lshl_add_u64 v[234:235], s[50:51], 0, v[196:197]
	s_mov_b32 m0, s87
	v_lshl_add_u64 v[236:237], s[50:51], 0, v[200:201]
	global_load_lds_dwordx4 v[234:235], off
	s_add_i32 m0, s87, 0x2000
	s_nop 0
	global_load_lds_dwordx4 v[236:237], off
	s_waitcnt vmcnt(6)
	s_barrier
	s_setprio 1
	v_mfma_f32_16x16x32_bf16 v[42:45], v[206:209], v[154:157], v[42:45]
	v_mfma_f32_16x16x32_bf16 v[34:37], v[222:225], v[154:157], v[34:37]
	v_mfma_f32_16x16x32_bf16 v[22:25], v[206:209], v[162:165], v[22:25]
	v_mfma_f32_16x16x32_bf16 v[18:21], v[222:225], v[162:165], v[18:21]
	v_mfma_f32_16x16x32_bf16 v[4:7], v[206:209], v[170:173], v[4:7]
	v_mfma_f32_16x16x32_bf16 v[0:3], v[222:225], v[170:173], v[0:3]
	v_mfma_f32_16x16x32_bf16 v[38:41], v[206:209], v[146:149], v[70:73]
	v_mfma_f32_16x16x32_bf16 v[46:49], v[222:225], v[146:149], v[66:69]
	v_mfma_f32_16x16x32_bf16 v[42:45], v[210:213], v[158:161], v[42:45]
	v_mfma_f32_16x16x32_bf16 v[34:37], v[226:229], v[158:161], v[34:37]
	v_mfma_f32_16x16x32_bf16 v[22:25], v[210:213], v[166:169], v[22:25]
	v_mfma_f32_16x16x32_bf16 v[18:21], v[226:229], v[166:169], v[18:21]
	v_mfma_f32_16x16x32_bf16 v[4:7], v[210:213], v[174:177], v[4:7]
	v_mfma_f32_16x16x32_bf16 v[0:3], v[226:229], v[174:177], v[0:3]
	v_mfma_f32_16x16x32_bf16 v[38:41], v[210:213], v[150:153], v[38:41]
	v_mfma_f32_16x16x32_bf16 v[46:49], v[226:229], v[150:153], v[46:49]
	s_setprio 0
	s_add_i32 s50, 0, 0x18000
	v_add_u32_e32 v70, s50, v220
	s_barrier
	ds_read_b128 v[54:57], v70
	ds_read_b128 v[62:65], v70 offset:1024
	ds_read_b128 v[66:69], v70 offset:2048
	ds_read_b128 v[70:73], v70 offset:3072
	s_add_u32 s48, s48, s40
	s_addc_u32 s49, s49, s41
	s_mov_b32 m0, s56
	v_lshl_add_u64 v[206:207], s[48:49], 0, v[194:195]
	ds_read_b128 v[146:149], v221 offset:32768
	ds_read_b128 v[150:153], v221 offset:33792
	ds_read_b128 v[154:157], v221 offset:34816
	ds_read_b128 v[158:161], v221 offset:35840
	ds_read_b128 v[162:165], v221 offset:36864
	ds_read_b128 v[166:169], v221 offset:37888
	ds_read_b128 v[170:173], v221 offset:38912
	ds_read_b128 v[174:177], v221 offset:39936
	global_load_lds_dwordx4 v[206:207], off
	v_lshl_add_u64 v[206:207], s[48:49], 0, v[198:199]
	s_mov_b32 m0, s57
	s_nop 0
	global_load_lds_dwordx4 v[206:207], off
	s_waitcnt lgkmcnt(8)
	s_barrier
	s_waitcnt lgkmcnt(0)
	s_setprio 1
	s_waitcnt lgkmcnt(0)
	v_mfma_f32_16x16x32_bf16 v[142:145], v[54:57], v[146:149], v[142:145]
	v_mfma_f32_16x16x32_bf16 v[138:141], v[66:69], v[146:149], v[138:141]
	v_mfma_f32_16x16x32_bf16 v[126:129], v[54:57], v[154:157], v[126:129]
	v_mfma_f32_16x16x32_bf16 v[122:125], v[66:69], v[154:157], v[122:125]
	v_mfma_f32_16x16x32_bf16 v[110:113], v[54:57], v[162:165], v[110:113]
	v_mfma_f32_16x16x32_bf16 v[106:109], v[66:69], v[162:165], v[106:109]
	v_mfma_f32_16x16x32_bf16 v[94:97], v[54:57], v[170:173], v[94:97]
	v_mfma_f32_16x16x32_bf16 v[90:93], v[66:69], v[170:173], v[90:93]
	v_mfma_f32_16x16x32_bf16 v[142:145], v[62:65], v[150:153], v[142:145]
	v_mfma_f32_16x16x32_bf16 v[138:141], v[70:73], v[150:153], v[138:141]
	v_mfma_f32_16x16x32_bf16 v[126:129], v[62:65], v[158:161], v[126:129]
	v_mfma_f32_16x16x32_bf16 v[122:125], v[70:73], v[158:161], v[122:125]
	v_mfma_f32_16x16x32_bf16 v[110:113], v[62:65], v[166:169], v[110:113]
	v_mfma_f32_16x16x32_bf16 v[106:109], v[70:73], v[166:169], v[106:109]
	v_mfma_f32_16x16x32_bf16 v[94:97], v[62:65], v[174:177], v[94:97]
	v_mfma_f32_16x16x32_bf16 v[90:93], v[70:73], v[174:177], v[90:93]
	s_setprio 0
	s_barrier
	s_add_i32 s48, 0, 0x1c000
	s_add_i32 s49, s50, s53
	v_add_u32_e32 v226, s48, v220
	v_lshl_add_u64 v[186:187], v[186:187], 0, s[20:21]
	s_mov_b32 m0, s49
	ds_read_b128 v[206:209], v226
	ds_read_b128 v[210:213], v226 offset:1024
	ds_read_b128 v[222:225], v226 offset:2048
	ds_read_b128 v[226:229], v226 offset:3072
	global_load_lds_dwordx4 v[186:187], off
	v_lshl_add_u64 v[186:187], v[188:189], 0, s[20:21]
	s_add_i32 m0, s49, 0x2000
	s_nop 0
	global_load_lds_dwordx4 v[186:187], off
	s_barrier
; #define PG8_STAGE(bufoff, gbase, voff) do { _Pragma("unroll") for (int _i = 0; _i < 2; ++_i) \
;         __builtin_amdgcn_global_load_lds((const unsigned*)((const char*)(gbase) + (voff)[_i]), (LAS unsigned*)(lds + (bufoff) + ldsw + _i * 8192), 16, 0, 0); } while (0)
; #define PG8_LDA(dst, b, h) do { _Pragma("unroll") for (int m = 0; m < 4; ++m) _Pragma("unroll") for (int k = 0; k < 2; ++k) dst[m][k] = *(const LAS bf16x8*)(lds + PG8_SA(b, h) + aoff + m * 2048 + k * 1024); } while (0)
; #define PG8_MMA(ai, bj, At, Bt) do { __builtin_amdgcn_s_setprio(1); _Pragma("unroll") for (int m = 0; m < 4; ++m) _Pragma("unroll") for (int n = 0; n < 2; ++n) _Pragma("unroll") for (int k = 0; k < 2; ++k) \
;         acc[ai][bj][m][n] = __builtin_amdgcn_mfma_f32_16x16x32_bf16(Bt[n][k], At[m][k], acc[ai][bj][m][n], 0, 0, 0); __builtin_amdgcn_s_setprio(0); } while (0)
; #define PG8_WAIT_V(n) asm volatile("s_waitcnt vmcnt(" #n ")" ::: "memory")
; #define PG8_WAIT_L(n) asm volatile("s_waitcnt lgkmcnt(" #n ")" ::: "memory")
; #define PG8_BAR __builtin_amdgcn_s_barrier()
; #define PG8_SCHED __builtin_amdgcn_sched_barrier(0)
; template <class Epi>
; __device__ __forceinline__ void gemm_phase(LAS unsigned char* lds, const Gemm g, const Epi& E) {
;     ...
;             PG8_BAR; PG8_WAIT_L(0); PG8_MMA(0, 1, At, B1); PG8_BAR;
;             PG8_LDA(At, 1, 1); PG8_STAGE(PG8_SA(1, 0), a3, voffA);
;             PG8_BAR; PG8_WAIT_L(0); PG8_MMA(1, 0, At, B0); PG8_BAR; PG8_SCHED;
;             PG8_STAGE(PG8_SB(1, 1), b3 + hstep, voffB);
;             PG8_WAIT_V(6); PG8_BAR; PG8_MMA(1, 1, At, B1); PG8_BAR;
	s_waitcnt lgkmcnt(0)
	s_setprio 1
	s_waitcnt lgkmcnt(0)
	v_mfma_f32_16x16x32_bf16 v[134:137], v[206:209], v[146:149], v[134:137]
	v_mfma_f32_16x16x32_bf16 v[130:133], v[222:225], v[146:149], v[130:133]
	v_mfma_f32_16x16x32_bf16 v[118:121], v[206:209], v[154:157], v[118:121]
	v_mfma_f32_16x16x32_bf16 v[114:117], v[222:225], v[154:157], v[114:117]
	v_mfma_f32_16x16x32_bf16 v[102:105], v[206:209], v[162:165], v[102:105]
	v_mfma_f32_16x16x32_bf16 v[98:101], v[222:225], v[162:165], v[98:101]
	v_mfma_f32_16x16x32_bf16 v[86:89], v[206:209], v[170:173], v[86:89]
	v_mfma_f32_16x16x32_bf16 v[82:85], v[222:225], v[170:173], v[82:85]
	v_mfma_f32_16x16x32_bf16 v[134:137], v[210:213], v[150:153], v[134:137]
	v_mfma_f32_16x16x32_bf16 v[130:133], v[226:229], v[150:153], v[130:133]
	v_mfma_f32_16x16x32_bf16 v[118:121], v[210:213], v[158:161], v[118:121]
	v_mfma_f32_16x16x32_bf16 v[114:117], v[226:229], v[158:161], v[114:117]
	v_mfma_f32_16x16x32_bf16 v[102:105], v[210:213], v[166:169], v[102:105]
	v_mfma_f32_16x16x32_bf16 v[98:101], v[226:229], v[166:169], v[98:101]
	v_mfma_f32_16x16x32_bf16 v[86:89], v[210:213], v[174:177], v[86:89]
	v_mfma_f32_16x16x32_bf16 v[82:85], v[226:229], v[174:177], v[82:85]
	s_setprio 0
	s_mov_b32 m0, s58
	v_lshl_add_u64 v[186:187], v[230:231], 0, s[20:21]
	s_barrier
	ds_read_b128 v[146:149], v221 offset:49152
	ds_read_b128 v[150:153], v221 offset:50176
	ds_read_b128 v[154:157], v221 offset:51200
	ds_read_b128 v[158:161], v221 offset:52224
	ds_read_b128 v[162:165], v221 offset:53248
	ds_read_b128 v[166:169], v221 offset:54272
	ds_read_b128 v[170:173], v221 offset:55296
	ds_read_b128 v[174:177], v221 offset:56320
	global_load_lds_dwordx4 v[186:187], off
	v_lshl_add_u64 v[186:187], v[232:233], 0, s[20:21]
	s_mov_b32 m0, s59
	s_nop 0
	global_load_lds_dwordx4 v[186:187], off
	s_barrier
	s_waitcnt lgkmcnt(0)
	s_setprio 1
	s_waitcnt lgkmcnt(0)
	v_mfma_f32_16x16x32_bf16 v[78:81], v[54:57], v[146:149], v[78:81]
	v_mfma_f32_16x16x32_bf16 v[74:77], v[66:69], v[146:149], v[74:77]
	v_mfma_f32_16x16x32_bf16 v[58:61], v[54:57], v[154:157], v[58:61]
	v_mfma_f32_16x16x32_bf16 v[50:53], v[66:69], v[154:157], v[50:53]
	v_mfma_f32_16x16x32_bf16 v[30:33], v[54:57], v[162:165], v[30:33]
	v_mfma_f32_16x16x32_bf16 v[26:29], v[66:69], v[162:165], v[26:29]
	v_mfma_f32_16x16x32_bf16 v[14:17], v[54:57], v[170:173], v[14:17]
	v_mfma_f32_16x16x32_bf16 v[8:11], v[66:69], v[170:173], v[8:11]
	v_mfma_f32_16x16x32_bf16 v[78:81], v[62:65], v[150:153], v[78:81]
	v_mfma_f32_16x16x32_bf16 v[74:77], v[70:73], v[150:153], v[74:77]
	v_mfma_f32_16x16x32_bf16 v[58:61], v[62:65], v[158:161], v[58:61]
	v_mfma_f32_16x16x32_bf16 v[50:53], v[70:73], v[158:161], v[50:53]
	v_mfma_f32_16x16x32_bf16 v[30:33], v[62:65], v[166:169], v[30:33]
	v_mfma_f32_16x16x32_bf16 v[26:29], v[70:73], v[166:169], v[26:29]
	v_mfma_f32_16x16x32_bf16 v[14:17], v[62:65], v[174:177], v[14:17]
	v_mfma_f32_16x16x32_bf16 v[8:11], v[70:73], v[174:177], v[8:11]
	s_setprio 0
	s_barrier
	s_add_i32 s48, s48, s53
	v_lshl_add_u64 v[54:55], v[234:235], 0, s[20:21]
	s_mov_b32 m0, s48
	s_nop 0
	global_load_lds_dwordx4 v[54:55], off
	v_lshl_add_u64 v[54:55], v[236:237], 0, s[20:21]
	s_add_i32 m0, s48, 0x2000
	s_nop 0
	global_load_lds_dwordx4 v[54:55], off
	s_waitcnt vmcnt(6)
	s_barrier
	s_setprio 1
	v_mfma_f32_16x16x32_bf16 v[38:41], v[206:209], v[146:149], v[38:41]
	v_mfma_f32_16x16x32_bf16 v[70:73], v[210:213], v[150:153], v[38:41]
	v_mfma_f32_16x16x32_bf16 v[38:41], v[222:225], v[146:149], v[46:49]
	v_mfma_f32_16x16x32_bf16 v[66:69], v[226:229], v[150:153], v[38:41]
	v_mfma_f32_16x16x32_bf16 v[38:41], v[206:209], v[154:157], v[42:45]
	v_mfma_f32_16x16x32_bf16 v[34:37], v[222:225], v[154:157], v[34:37]
	v_mfma_f32_16x16x32_bf16 v[22:25], v[206:209], v[162:165], v[22:25]
	v_mfma_f32_16x16x32_bf16 v[18:21], v[222:225], v[162:165], v[18:21]
	v_mfma_f32_16x16x32_bf16 v[4:7], v[206:209], v[170:173], v[4:7]
	v_mfma_f32_16x16x32_bf16 v[0:3], v[222:225], v[170:173], v[0:3]
	v_mfma_f32_16x16x32_bf16 v[42:45], v[210:213], v[158:161], v[38:41]
	v_mfma_f32_16x16x32_bf16 v[34:37], v[226:229], v[158:161], v[34:37]
	v_mfma_f32_16x16x32_bf16 v[22:25], v[210:213], v[166:169], v[22:25]
	v_mfma_f32_16x16x32_bf16 v[18:21], v[226:229], v[166:169], v[18:21]
	v_mfma_f32_16x16x32_bf16 v[4:7], v[210:213], v[174:177], v[4:7]
	v_mfma_f32_16x16x32_bf16 v[0:3], v[226:229], v[174:177], v[0:3]
	s_setprio 0
	s_add_u32 s46, s46, 0x100
	s_addc_u32 s47, s47, 0
	s_add_u32 s84, s84, 0x100
	s_addc_u32 s85, s85, 0
	s_cmp_ge_i32 s86, s2
	s_mov_b32 s48, s86
	s_barrier
	s_cbranch_scc0 .LBB0_670
	s_nop 0
	s_nop 0
	s_nop 0
	s_nop 0
	s_nop 0
	s_nop 0
	s_nop 0
	s_nop 0
	s_nop 0
	s_nop 0
	s_nop 0
	s_nop 0
	s_nop 0
	s_nop 0
	s_nop 0
	s_nop 0
	s_nop 0
	s_nop 0
	s_nop 0
	s_nop 0
	s_nop 0
	s_nop 0
	s_nop 0
	s_nop 0
	s_nop 0
	s_nop 0
	s_nop 0
	s_nop 0
	s_nop 0
	s_nop 0
	s_nop 0
	s_nop 0
	s_nop 0
	s_nop 0
	s_nop 0
	s_nop 0
	s_nop 0
	s_nop 0
	s_nop 0
	s_nop 0
	s_nop 0
	s_nop 0
	s_branch .LBB0_657

; template <class Epi>
; __device__ __forceinline__ void gemm_phase(LAS unsigned char* lds, const Gemm g, const Epi& E) {
;     ...
;         if (!has_next) break;
; #pragma unroll
;         for (int a = 0; a < 2; ++a)
; #pragma unroll
;             for (int b = 0; b < 2; ++b)
; #pragma unroll
;                 for (int m = 0; m < 4; ++m)
; #pragma unroll
;                     for (int n = 0; n < 2; ++n) acc[a][b][m][n] = (f32x4){0.f, 0.f, 0.f, 0.f};
;         cur = nxt; cA = nA; cB = nB; ++ui;
.LBB0_928:
	v_mov_b32_e32 v145, 0
	s_andn2_b64 vcc, exec, s[42:43]
	v_mov_b32_e32 v144, v145
	v_mov_b32_e32 v143, v145
	v_mov_b32_e32 v142, v145
	v_mov_b32_e32 v141, v145
	v_mov_b32_e32 v140, v145
	v_mov_b32_e32 v139, v145
	v_mov_b32_e32 v138, v145
	v_mov_b32_e32 v129, v145
	v_mov_b32_e32 v128, v145
	v_mov_b32_e32 v127, v145
	v_mov_b32_e32 v126, v145
	v_mov_b32_e32 v125, v145
	v_mov_b32_e32 v124, v145
	v_mov_b32_e32 v123, v145
	v_mov_b32_e32 v122, v145
	v_mov_b32_e32 v113, v145
	v_mov_b32_e32 v112, v145
	v_mov_b32_e32 v111, v145
	v_mov_b32_e32 v110, v145
	v_mov_b32_e32 v109, v145
	v_mov_b32_e32 v108, v145
	v_mov_b32_e32 v107, v145
	v_mov_b32_e32 v106, v145
	v_mov_b32_e32 v97, v145
	v_mov_b32_e32 v96, v145
	v_mov_b32_e32 v95, v145
	v_mov_b32_e32 v94, v145
	v_mov_b32_e32 v93, v145
	v_mov_b32_e32 v92, v145
	v_mov_b32_e32 v91, v145
	v_mov_b32_e32 v90, v145
	v_mov_b32_e32 v137, v145
	v_mov_b32_e32 v136, v145
	v_mov_b32_e32 v135, v145
	v_mov_b32_e32 v134, v145
	v_mov_b32_e32 v133, v145
	v_mov_b32_e32 v132, v145
	v_mov_b32_e32 v131, v145
	v_mov_b32_e32 v130, v145
	v_mov_b32_e32 v121, v145
	v_mov_b32_e32 v120, v145
	v_mov_b32_e32 v119, v145
	v_mov_b32_e32 v118, v145
	v_mov_b32_e32 v117, v145
	v_mov_b32_e32 v116, v145
	v_mov_b32_e32 v115, v145
	v_mov_b32_e32 v114, v145
	v_mov_b32_e32 v105, v145
	v_mov_b32_e32 v104, v145
	v_mov_b32_e32 v103, v145
	v_mov_b32_e32 v102, v145
	v_mov_b32_e32 v101, v145
	v_mov_b32_e32 v100, v145
	v_mov_b32_e32 v99, v145
	v_mov_b32_e32 v98, v145
	v_mov_b32_e32 v85, v145
	v_mov_b32_e32 v84, v145
	v_mov_b32_e32 v83, v145
	v_mov_b32_e32 v82, v145
	v_mov_b32_e32 v77, v145
	v_mov_b32_e32 v76, v145
	v_mov_b32_e32 v75, v145
	v_mov_b32_e32 v74, v145
	v_mov_b32_e32 v69, v145
	v_mov_b32_e32 v68, v145
	v_mov_b32_e32 v67, v145
	v_mov_b32_e32 v66, v145
	v_mov_b32_e32 v61, v145
	v_mov_b32_e32 v60, v145
	v_mov_b32_e32 v59, v145
	v_mov_b32_e32 v58, v145
	v_mov_b32_e32 v49, v145
	v_mov_b32_e32 v48, v145
	v_mov_b32_e32 v47, v145
	v_mov_b32_e32 v46, v145
	v_mov_b32_e32 v45, v145
	v_mov_b32_e32 v44, v145
	v_mov_b32_e32 v43, v145
	v_mov_b32_e32 v42, v145
	v_mov_b32_e32 v33, v145
	v_mov_b32_e32 v32, v145
	v_mov_b32_e32 v31, v145
	v_mov_b32_e32 v30, v145
	v_mov_b32_e32 v29, v145
	v_mov_b32_e32 v28, v145
	v_mov_b32_e32 v27, v145
	v_mov_b32_e32 v26, v145
	v_mov_b32_e32 v17, v145
	v_mov_b32_e32 v16, v145
	v_mov_b32_e32 v15, v145
	v_mov_b32_e32 v14, v145
	v_mov_b32_e32 v11, v145
	v_mov_b32_e32 v10, v145
	v_mov_b32_e32 v9, v145
	v_mov_b32_e32 v8, v145
	v_mov_b32_e32 v57, v145
	v_mov_b32_e32 v56, v145
	v_mov_b32_e32 v55, v145
	v_mov_b32_e32 v54, v145
	v_mov_b32_e32 v53, v145
	v_mov_b32_e32 v52, v145
	v_mov_b32_e32 v51, v145
	v_mov_b32_e32 v50, v145
	v_mov_b32_e32 v41, v145
	v_mov_b32_e32 v40, v145
	v_mov_b32_e32 v39, v145
	v_mov_b32_e32 v38, v145
	v_mov_b32_e32 v37, v145
	v_mov_b32_e32 v36, v145
	v_mov_b32_e32 v35, v145
	v_mov_b32_e32 v34, v145
	v_mov_b32_e32 v25, v145
	v_mov_b32_e32 v24, v145
	v_mov_b32_e32 v23, v145
	v_mov_b32_e32 v22, v145
	v_mov_b32_e32 v21, v145
	v_mov_b32_e32 v20, v145
	v_mov_b32_e32 v19, v145
	v_mov_b32_e32 v18, v145
	v_mov_b32_e32 v7, v145
	v_mov_b32_e32 v6, v145
	v_mov_b32_e32 v5, v145
	v_mov_b32_e32 v4, v145
	v_mov_b32_e32 v3, v145
	v_mov_b32_e32 v2, v145
	v_mov_b32_e32 v1, v145
	v_mov_b32_e32 v0, v145
	s_cbranch_vccnz .LBB0_917
	s_add_u32 s44, s44, 0x80
	s_addc_u32 s45, s45, 0
	s_add_u32 s82, s46, 0x100
	v_mov_b32_e32 v0, 0
	s_addc_u32 s83, s47, 0
	s_mov_b32 s46, 0
	v_mov_b32_e32 v1, v0
	v_mov_b32_e32 v2, v0
	v_mov_b32_e32 v3, v0
	v_mov_b32_e32 v4, v0
	v_mov_b32_e32 v5, v0
	v_mov_b32_e32 v6, v0
	v_mov_b32_e32 v7, v0
	v_mov_b32_e32 v18, v0
	v_mov_b32_e32 v19, v0
	v_mov_b32_e32 v20, v0
	v_mov_b32_e32 v21, v0
	v_mov_b32_e32 v22, v0
	v_mov_b32_e32 v23, v0
	v_mov_b32_e32 v24, v0
	v_mov_b32_e32 v25, v0
	v_mov_b32_e32 v34, v0
	v_mov_b32_e32 v35, v0
	v_mov_b32_e32 v36, v0
	v_mov_b32_e32 v37, v0
	v_mov_b32_e32 v38, v0
	v_mov_b32_e32 v39, v0
	v_mov_b32_e32 v40, v0
	v_mov_b32_e32 v41, v0
	v_mov_b32_e32 v50, v0
	v_mov_b32_e32 v51, v0
	v_mov_b32_e32 v52, v0
	v_mov_b32_e32 v53, v0
	v_mov_b32_e32 v54, v0
	v_mov_b32_e32 v55, v0
	v_mov_b32_e32 v56, v0
	v_mov_b32_e32 v57, v0
	v_mov_b32_e32 v8, v0
	v_mov_b32_e32 v9, v0
	v_mov_b32_e32 v10, v0
	v_mov_b32_e32 v11, v0
	v_mov_b32_e32 v14, v0
	v_mov_b32_e32 v15, v0
	v_mov_b32_e32 v16, v0
	v_mov_b32_e32 v17, v0
	v_mov_b32_e32 v26, v0
	v_mov_b32_e32 v27, v0
	v_mov_b32_e32 v28, v0
	v_mov_b32_e32 v29, v0
	v_mov_b32_e32 v30, v0
	v_mov_b32_e32 v31, v0
	v_mov_b32_e32 v32, v0
	v_mov_b32_e32 v33, v0
	v_mov_b32_e32 v42, v0
	v_mov_b32_e32 v43, v0
	v_mov_b32_e32 v44, v0
	v_mov_b32_e32 v45, v0
	v_mov_b32_e32 v46, v0
	v_mov_b32_e32 v47, v0
	v_mov_b32_e32 v48, v0
	v_mov_b32_e32 v49, v0
	v_mov_b32_e32 v58, v0
	v_mov_b32_e32 v59, v0
	v_mov_b32_e32 v60, v0
	v_mov_b32_e32 v61, v0
	v_mov_b32_e32 v66, v0
	v_mov_b32_e32 v67, v0
	v_mov_b32_e32 v68, v0
	v_mov_b32_e32 v69, v0
	v_mov_b32_e32 v74, v0
	v_mov_b32_e32 v75, v0
	v_mov_b32_e32 v76, v0
	v_mov_b32_e32 v77, v0
	v_mov_b32_e32 v82, v0
	v_mov_b32_e32 v83, v0
	v_mov_b32_e32 v84, v0
	v_mov_b32_e32 v85, v0
	v_mov_b32_e32 v98, v0
	v_mov_b32_e32 v99, v0
	v_mov_b32_e32 v100, v0
	v_mov_b32_e32 v101, v0
	v_mov_b32_e32 v102, v0
	v_mov_b32_e32 v103, v0
	v_mov_b32_e32 v104, v0
	v_mov_b32_e32 v105, v0
	v_mov_b32_e32 v114, v0
	v_mov_b32_e32 v115, v0
	v_mov_b32_e32 v116, v0
	v_mov_b32_e32 v117, v0
	v_mov_b32_e32 v118, v0
	v_mov_b32_e32 v119, v0
	v_mov_b32_e32 v120, v0
	v_mov_b32_e32 v121, v0
	v_mov_b32_e32 v130, v0
	v_mov_b32_e32 v131, v0
	v_mov_b32_e32 v132, v0
	v_mov_b32_e32 v133, v0
	v_mov_b32_e32 v134, v0
	v_mov_b32_e32 v135, v0
	v_mov_b32_e32 v136, v0
	v_mov_b32_e32 v137, v0
	v_mov_b32_e32 v90, v0
	v_mov_b32_e32 v91, v0
	v_mov_b32_e32 v92, v0
	v_mov_b32_e32 v93, v0
	v_mov_b32_e32 v94, v0
	v_mov_b32_e32 v95, v0
	v_mov_b32_e32 v96, v0
	v_mov_b32_e32 v97, v0
	v_mov_b32_e32 v106, v0
	v_mov_b32_e32 v107, v0
	v_mov_b32_e32 v108, v0
	v_mov_b32_e32 v109, v0
	v_mov_b32_e32 v110, v0
	v_mov_b32_e32 v111, v0
	v_mov_b32_e32 v112, v0
	v_mov_b32_e32 v113, v0
	v_mov_b32_e32 v122, v0
	v_mov_b32_e32 v123, v0
	v_mov_b32_e32 v124, v0
	v_mov_b32_e32 v125, v0
	v_mov_b32_e32 v126, v0
	v_mov_b32_e32 v127, v0
	v_mov_b32_e32 v128, v0
	v_mov_b32_e32 v129, v0
	v_mov_b32_e32 v138, v0
	v_mov_b32_e32 v139, v0
	v_mov_b32_e32 v140, v0
	v_mov_b32_e32 v141, v0
	v_mov_b32_e32 v142, v0
	v_mov_b32_e32 v143, v0
	v_mov_b32_e32 v144, v0
	v_mov_b32_e32 v145, v0
	s_nop 0
	s_nop 0
	s_nop 0
	s_nop 0
	s_nop 0
	s_nop 0
	s_nop 0
	s_nop 0
	s_nop 0
	s_nop 0
	s_nop 0
	s_nop 0
	s_nop 0
	s_nop 0
	s_nop 0
	s_nop 0
	s_nop 0
	s_nop 0
	s_nop 0
	s_nop 0
	s_nop 0
	s_nop 0
	s_nop 0
	s_nop 0
	s_nop 0
	s_nop 0
	s_nop 0
	s_nop 0
	s_nop 0
	s_nop 0
; #define PG8_STAGE(bufoff, gbase, voff) do { _Pragma("unroll") for (int _i = 0; _i < 2; ++_i) \
;         __builtin_amdgcn_global_load_lds((const unsigned*)((const char*)(gbase) + (voff)[_i]), (LAS unsigned*)(lds + (bufoff) + ldsw + _i * 8192), 16, 0, 0); } while (0)
; #define PG8_LDA(dst, b, h) do { _Pragma("unroll") for (int m = 0; m < 4; ++m) _Pragma("unroll") for (int k = 0; k < 2; ++k) dst[m][k] = *(const LAS bf16x8*)(lds + PG8_SA(b, h) + aoff + m * 2048 + k * 1024); } while (0)
; #define PG8_LDB(dst, b, h) do { _Pragma("unroll") for (int n = 0; n < 2; ++n) _Pragma("unroll") for (int k = 0; k < 2; ++k) dst[n][k] = *(const LAS bf16x8*)(lds + PG8_SB(b, h) + boff + n * 2048 + k * 1024); } while (0)
; #define PG8_MMA(ai, bj, At, Bt) do { __builtin_amdgcn_s_setprio(1); _Pragma("unroll") for (int m = 0; m < 4; ++m) _Pragma("unroll") for (int n = 0; n < 2; ++n) _Pragma("unroll") for (int k = 0; k < 2; ++k) \
;         acc[ai][bj][m][n] = __builtin_amdgcn_mfma_f32_16x16x32_bf16(Bt[n][k], At[m][k], acc[ai][bj][m][n], 0, 0, 0); __builtin_amdgcn_s_setprio(0); } while (0)
; template <class Epi>
; __device__ __forceinline__ void gemm_phase(LAS unsigned char* lds, const Gemm g, const Epi& E) {
;     ...
;         for (int t = 0; t < nt; t += 2) {
;             const bool last = (t == nt - 2);
;             const char* a1 = cA + (size_t)(t + 1) * kstep;
;             const char* a2 = last ? nA : cA + (size_t)(t + 2) * kstep; const char* b2 = last ? nB : cB + (size_t)(t + 2) * kstep;
;             const char* a3 = a2 + kstep; const char* b3 = b2 + kstep;
;             PG8_LDB(B0, 0, 0); PG8_SCHED; PG8_LDA(At, 0, 0); PG8_STAGE(PG8_SA(1, 1), a1 + hstep, voffA);
;             PG8_WAIT_L(8); PG8_BAR; PG8_WAIT_L(0); PG8_MMA(0, 0, At, B0); PG8_BAR; PG8_SCHED;
;             PG8_LDB(B1, 0, 1); PG8_STAGE(PG8_SB(0, 0), b2, voffB);
;             PG8_BAR; PG8_WAIT_L(0); PG8_MMA(0, 1, At, B1); PG8_BAR;
;             PG8_LDA(At, 0, 1); PG8_STAGE(PG8_SA(0, 0), a2, voffA);
;             PG8_BAR; PG8_WAIT_L(0); PG8_MMA(1, 0, At, B0); PG8_BAR; PG8_SCHED;
;             PG8_STAGE(PG8_SB(0, 1), b2 + hstep, voffB);
;             PG8_WAIT_V(6); PG8_BAR; PG8_MMA(1, 1, At, B1); PG8_BAR;
;             PG8_LDB(B0, 1, 0); PG8_SCHED; PG8_LDA(At, 1, 0); PG8_STAGE(PG8_SA(0, 1), a2 + hstep, voffA);
;             PG8_WAIT_L(8); PG8_BAR; PG8_WAIT_L(0); PG8_MMA(0, 0, At, B0); PG8_BAR; PG8_SCHED;
.LBB0_930:
	s_add_i32 s84, s46, 2
	s_add_u32 s48, s44, 0x80
	s_addc_u32 s47, s45, 0
	s_add_i32 s85, 0, 0x10000
	v_add_u32_e32 v86, s85, v163
	ds_read_b128 v[62:65], v86
	ds_read_b128 v[70:73], v86 offset:1024
	ds_read_b128 v[78:81], v86 offset:2048
	ds_read_b128 v[86:89], v86 offset:3072
	s_cmp_eq_u32 s58, s46
	s_cselect_b32 s46, s0, s48
	s_cselect_b32 s47, s1, s47
	s_cselect_b32 s49, s39, s83
	s_cselect_b32 s48, s38, s82
	v_lshl_add_u64 v[206:207], s[44:45], 0, v[154:155]
	s_add_i32 m0, s50, 0xc000
	ds_read_b128 v[158:161], v164
	ds_read_b128 v[166:169], v164 offset:1024
	ds_read_b128 v[170:173], v164 offset:2048
	ds_read_b128 v[174:177], v164 offset:3072
	ds_read_b128 v[186:189], v164 offset:4096
	ds_read_b128 v[194:197], v164 offset:5120
	ds_read_b128 v[198:201], v164 offset:6144
	ds_read_b128 v[202:205], v164 offset:7168
	global_load_lds_dwordx4 v[206:207], off
	v_lshl_add_u64 v[206:207], s[44:45], 0, v[156:157]
	s_add_i32 m0, s50, 0xe000
	s_nop 0
	global_load_lds_dwordx4 v[206:207], off
	s_waitcnt lgkmcnt(8)
	s_barrier
	s_waitcnt lgkmcnt(0)
	s_setprio 1
	s_waitcnt lgkmcnt(0)
	v_mfma_f32_16x16x32_bf16 v[142:145], v[62:65], v[158:161], v[142:145]
	v_mfma_f32_16x16x32_bf16 v[138:141], v[78:81], v[158:161], v[138:141]
	v_mfma_f32_16x16x32_bf16 v[126:129], v[62:65], v[170:173], v[126:129]
	v_mfma_f32_16x16x32_bf16 v[122:125], v[78:81], v[170:173], v[122:125]
	v_mfma_f32_16x16x32_bf16 v[110:113], v[62:65], v[186:189], v[110:113]
	v_mfma_f32_16x16x32_bf16 v[106:109], v[78:81], v[186:189], v[106:109]
	v_mfma_f32_16x16x32_bf16 v[94:97], v[62:65], v[198:201], v[94:97]
	v_mfma_f32_16x16x32_bf16 v[90:93], v[78:81], v[198:201], v[90:93]
	v_mfma_f32_16x16x32_bf16 v[142:145], v[70:73], v[166:169], v[142:145]
	v_mfma_f32_16x16x32_bf16 v[138:141], v[86:89], v[166:169], v[138:141]
	v_mfma_f32_16x16x32_bf16 v[126:129], v[70:73], v[174:177], v[126:129]
	v_mfma_f32_16x16x32_bf16 v[122:125], v[86:89], v[174:177], v[122:125]
	v_mfma_f32_16x16x32_bf16 v[110:113], v[70:73], v[194:197], v[110:113]
	v_mfma_f32_16x16x32_bf16 v[106:109], v[86:89], v[194:197], v[106:109]
	v_mfma_f32_16x16x32_bf16 v[94:97], v[70:73], v[202:205], v[94:97]
	v_mfma_f32_16x16x32_bf16 v[90:93], v[86:89], v[202:205], v[90:93]
	s_setprio 0
	s_barrier
	s_add_i32 s86, 0, 0x14000
	s_add_i32 s85, s85, s25
	v_add_u32_e32 v165, s86, v163
	v_lshl_add_u64 v[228:229], s[48:49], 0, v[148:149]
	s_mov_b32 m0, s85
	ds_read_b128 v[206:209], v165
	ds_read_b128 v[210:213], v165 offset:1024
	ds_read_b128 v[220:223], v165 offset:2048
	ds_read_b128 v[224:227], v165 offset:3072
	global_load_lds_dwordx4 v[228:229], off
	v_lshl_add_u64 v[230:231], s[48:49], 0, v[152:153]
	s_add_i32 m0, s85, 0x2000
	s_nop 0
	global_load_lds_dwordx4 v[230:231], off
	s_barrier
	s_waitcnt lgkmcnt(0)
	s_setprio 1
	s_waitcnt lgkmcnt(0)
	v_mfma_f32_16x16x32_bf16 v[134:137], v[206:209], v[158:161], v[134:137]
	v_mfma_f32_16x16x32_bf16 v[130:133], v[220:223], v[158:161], v[130:133]
	v_mfma_f32_16x16x32_bf16 v[118:121], v[206:209], v[170:173], v[118:121]
	v_mfma_f32_16x16x32_bf16 v[114:117], v[220:223], v[170:173], v[114:117]
	v_mfma_f32_16x16x32_bf16 v[102:105], v[206:209], v[186:189], v[102:105]
	v_mfma_f32_16x16x32_bf16 v[98:101], v[220:223], v[186:189], v[98:101]
	v_mfma_f32_16x16x32_bf16 v[82:85], v[206:209], v[198:201], v[82:85]
	v_mfma_f32_16x16x32_bf16 v[74:77], v[220:223], v[198:201], v[74:77]
	v_mfma_f32_16x16x32_bf16 v[134:137], v[210:213], v[166:169], v[134:137]
	v_mfma_f32_16x16x32_bf16 v[130:133], v[224:227], v[166:169], v[130:133]
	v_mfma_f32_16x16x32_bf16 v[118:121], v[210:213], v[174:177], v[118:121]
	v_mfma_f32_16x16x32_bf16 v[114:117], v[224:227], v[174:177], v[114:117]
	v_mfma_f32_16x16x32_bf16 v[102:105], v[210:213], v[194:197], v[102:105]
	v_mfma_f32_16x16x32_bf16 v[98:101], v[224:227], v[194:197], v[98:101]
	v_mfma_f32_16x16x32_bf16 v[82:85], v[210:213], v[202:205], v[82:85]
	v_mfma_f32_16x16x32_bf16 v[74:77], v[224:227], v[202:205], v[74:77]
	s_setprio 0
	s_mov_b32 m0, s50
	v_lshl_add_u64 v[232:233], s[46:47], 0, v[146:147]
	s_barrier
	ds_read_b128 v[158:161], v164 offset:16384
	ds_read_b128 v[166:169], v164 offset:17408
	ds_read_b128 v[170:173], v164 offset:18432
	ds_read_b128 v[174:177], v164 offset:19456
	ds_read_b128 v[186:189], v164 offset:20480
	ds_read_b128 v[194:197], v164 offset:21504
	ds_read_b128 v[198:201], v164 offset:22528
	ds_read_b128 v[202:205], v164 offset:23552
	global_load_lds_dwordx4 v[232:233], off
	v_lshl_add_u64 v[234:235], s[46:47], 0, v[150:151]
	s_mov_b32 m0, s51
	s_nop 0
	global_load_lds_dwordx4 v[234:235], off
	s_barrier
	s_waitcnt lgkmcnt(0)
	s_setprio 1
	s_waitcnt lgkmcnt(0)
	v_mfma_f32_16x16x32_bf16 v[66:69], v[62:65], v[158:161], v[66:69]
	v_mfma_f32_16x16x32_bf16 v[58:61], v[78:81], v[158:161], v[58:61]
	v_mfma_f32_16x16x32_bf16 v[46:49], v[62:65], v[170:173], v[46:49]
	v_mfma_f32_16x16x32_bf16 v[42:45], v[78:81], v[170:173], v[42:45]
	v_mfma_f32_16x16x32_bf16 v[30:33], v[62:65], v[186:189], v[30:33]
	v_mfma_f32_16x16x32_bf16 v[26:29], v[78:81], v[186:189], v[26:29]
	v_mfma_f32_16x16x32_bf16 v[14:17], v[62:65], v[198:201], v[14:17]
	v_mfma_f32_16x16x32_bf16 v[8:11], v[78:81], v[198:201], v[8:11]
	v_mfma_f32_16x16x32_bf16 v[66:69], v[70:73], v[166:169], v[66:69]
	v_mfma_f32_16x16x32_bf16 v[58:61], v[86:89], v[166:169], v[58:61]
	v_mfma_f32_16x16x32_bf16 v[46:49], v[70:73], v[174:177], v[46:49]
	v_mfma_f32_16x16x32_bf16 v[42:45], v[86:89], v[174:177], v[42:45]
	v_mfma_f32_16x16x32_bf16 v[30:33], v[70:73], v[194:197], v[30:33]
	v_mfma_f32_16x16x32_bf16 v[26:29], v[86:89], v[194:197], v[26:29]
	v_mfma_f32_16x16x32_bf16 v[14:17], v[70:73], v[202:205], v[14:17]
	v_mfma_f32_16x16x32_bf16 v[8:11], v[86:89], v[202:205], v[8:11]
	s_setprio 0
	s_barrier
; #define PG8_STAGE(bufoff, gbase, voff) do { _Pragma("unroll") for (int _i = 0; _i < 2; ++_i) \
;         __builtin_amdgcn_global_load_lds((const unsigned*)((const char*)(gbase) + (voff)[_i]), (LAS unsigned*)(lds + (bufoff) + ldsw + _i * 8192), 16, 0, 0); } while (0)
; #define PG8_LDA(dst, b, h) do { _Pragma("unroll") for (int m = 0; m < 4; ++m) _Pragma("unroll") for (int k = 0; k < 2; ++k) dst[m][k] = *(const LAS bf16x8*)(lds + PG8_SA(b, h) + aoff + m * 2048 + k * 1024); } while (0)
; #define PG8_LDB(dst, b, h) do { _Pragma("unroll") for (int n = 0; n < 2; ++n) _Pragma("unroll") for (int k = 0; k < 2; ++k) dst[n][k] = *(const LAS bf16x8*)(lds + PG8_SB(b, h) + boff + n * 2048 + k * 1024); } while (0)
; #define PG8_MMA(ai, bj, At, Bt) do { __builtin_amdgcn_s_setprio(1); _Pragma("unroll") for (int m = 0; m < 4; ++m) _Pragma("unroll") for (int n = 0; n < 2; ++n) _Pragma("unroll") for (int k = 0; k < 2; ++k) \
;         acc[ai][bj][m][n] = __builtin_amdgcn_mfma_f32_16x16x32_bf16(Bt[n][k], At[m][k], acc[ai][bj][m][n], 0, 0, 0); __builtin_amdgcn_s_setprio(0); } while (0)
; #define PG8_WAIT_V(n) asm volatile("s_waitcnt vmcnt(" #n ")" ::: "memory")
; #define PG8_WAIT_L(n) asm volatile("s_waitcnt lgkmcnt(" #n ")" ::: "memory")
; #define PG8_BAR __builtin_amdgcn_s_barrier()
; #define PG8_SCHED __builtin_amdgcn_sched_barrier(0)
; template <class Epi>
; __device__ __forceinline__ void gemm_phase(LAS unsigned char* lds, const Gemm g, const Epi& E) {
;     ...
;             PG8_WAIT_V(6); PG8_BAR; PG8_MMA(1, 1, At, B1); PG8_BAR;
;             PG8_LDB(B0, 1, 0); PG8_SCHED; PG8_LDA(At, 1, 0); PG8_STAGE(PG8_SA(0, 1), a2 + hstep, voffA);
;             PG8_WAIT_L(8); PG8_BAR; PG8_WAIT_L(0); PG8_MMA(0, 0, At, B0); PG8_BAR; PG8_SCHED;
;             PG8_LDB(B1, 1, 1); PG8_STAGE(PG8_SB(1, 0), b3, voffB);
;             PG8_BAR; PG8_WAIT_L(0); PG8_MMA(0, 1, At, B1); PG8_BAR;
;             PG8_LDA(At, 1, 1); PG8_STAGE(PG8_SA(1, 0), a3, voffA);
	s_add_u32 s48, s48, s26
	s_addc_u32 s49, s49, s27
	s_add_i32 s85, s86, s25
	v_lshl_add_u64 v[236:237], s[48:49], 0, v[148:149]
	s_mov_b32 m0, s85
	v_lshl_add_u64 v[238:239], s[48:49], 0, v[152:153]
	global_load_lds_dwordx4 v[236:237], off
	s_add_i32 m0, s85, 0x2000
	s_nop 0
	global_load_lds_dwordx4 v[238:239], off
	s_waitcnt vmcnt(6)
	s_barrier
	s_setprio 1
	v_mfma_f32_16x16x32_bf16 v[54:57], v[206:209], v[158:161], v[54:57]
	v_mfma_f32_16x16x32_bf16 v[50:53], v[220:223], v[158:161], v[50:53]
	v_mfma_f32_16x16x32_bf16 v[38:41], v[206:209], v[170:173], v[38:41]
	v_mfma_f32_16x16x32_bf16 v[34:37], v[220:223], v[170:173], v[34:37]
	v_mfma_f32_16x16x32_bf16 v[22:25], v[206:209], v[186:189], v[22:25]
	v_mfma_f32_16x16x32_bf16 v[18:21], v[220:223], v[186:189], v[18:21]
	v_mfma_f32_16x16x32_bf16 v[4:7], v[206:209], v[198:201], v[4:7]
	v_mfma_f32_16x16x32_bf16 v[0:3], v[220:223], v[198:201], v[0:3]
	v_mfma_f32_16x16x32_bf16 v[54:57], v[210:213], v[166:169], v[54:57]
	v_mfma_f32_16x16x32_bf16 v[50:53], v[224:227], v[166:169], v[50:53]
	v_mfma_f32_16x16x32_bf16 v[38:41], v[210:213], v[174:177], v[38:41]
	v_mfma_f32_16x16x32_bf16 v[34:37], v[224:227], v[174:177], v[34:37]
	v_mfma_f32_16x16x32_bf16 v[22:25], v[210:213], v[194:197], v[22:25]
	v_mfma_f32_16x16x32_bf16 v[18:21], v[224:227], v[194:197], v[18:21]
	v_mfma_f32_16x16x32_bf16 v[4:7], v[210:213], v[202:205], v[4:7]
	v_mfma_f32_16x16x32_bf16 v[0:3], v[224:227], v[202:205], v[0:3]
	s_setprio 0
	s_add_i32 s48, 0, 0x18000
	v_add_u32_e32 v86, s48, v163
	s_barrier
	ds_read_b128 v[62:65], v86
	ds_read_b128 v[70:73], v86 offset:1024
	ds_read_b128 v[78:81], v86 offset:2048
	ds_read_b128 v[86:89], v86 offset:3072
	s_add_u32 s46, s46, s26
	s_addc_u32 s47, s47, s27
	s_mov_b32 m0, s52
	v_lshl_add_u64 v[206:207], s[46:47], 0, v[146:147]
	ds_read_b128 v[158:161], v164 offset:32768
	ds_read_b128 v[166:169], v164 offset:33792
	ds_read_b128 v[170:173], v164 offset:34816
	ds_read_b128 v[174:177], v164 offset:35840
	ds_read_b128 v[186:189], v164 offset:36864
	ds_read_b128 v[194:197], v164 offset:37888
	ds_read_b128 v[198:201], v164 offset:38912
	ds_read_b128 v[202:205], v164 offset:39936
	global_load_lds_dwordx4 v[206:207], off
	v_lshl_add_u64 v[206:207], s[46:47], 0, v[150:151]
	s_mov_b32 m0, s53
	s_nop 0
	global_load_lds_dwordx4 v[206:207], off
	s_waitcnt lgkmcnt(8)
	s_barrier
	s_waitcnt lgkmcnt(0)
	s_setprio 1
	s_waitcnt lgkmcnt(0)
	v_mfma_f32_16x16x32_bf16 v[142:145], v[62:65], v[158:161], v[142:145]
	v_mfma_f32_16x16x32_bf16 v[138:141], v[78:81], v[158:161], v[138:141]
	v_mfma_f32_16x16x32_bf16 v[126:129], v[62:65], v[170:173], v[126:129]
	v_mfma_f32_16x16x32_bf16 v[122:125], v[78:81], v[170:173], v[122:125]
	v_mfma_f32_16x16x32_bf16 v[110:113], v[62:65], v[186:189], v[110:113]
	v_mfma_f32_16x16x32_bf16 v[106:109], v[78:81], v[186:189], v[106:109]
	v_mfma_f32_16x16x32_bf16 v[94:97], v[62:65], v[198:201], v[94:97]
	v_mfma_f32_16x16x32_bf16 v[90:93], v[78:81], v[198:201], v[90:93]
	v_mfma_f32_16x16x32_bf16 v[142:145], v[70:73], v[166:169], v[142:145]
	v_mfma_f32_16x16x32_bf16 v[138:141], v[86:89], v[166:169], v[138:141]
	v_mfma_f32_16x16x32_bf16 v[126:129], v[70:73], v[174:177], v[126:129]
	v_mfma_f32_16x16x32_bf16 v[122:125], v[86:89], v[174:177], v[122:125]
	v_mfma_f32_16x16x32_bf16 v[110:113], v[70:73], v[194:197], v[110:113]
	v_mfma_f32_16x16x32_bf16 v[106:109], v[86:89], v[194:197], v[106:109]
	v_mfma_f32_16x16x32_bf16 v[94:97], v[70:73], v[202:205], v[94:97]
	v_mfma_f32_16x16x32_bf16 v[90:93], v[86:89], v[202:205], v[90:93]
	s_setprio 0
	s_barrier
	s_add_i32 s46, 0, 0x1c000
	s_add_i32 s47, s48, s25
	v_add_u32_e32 v165, s46, v163
	v_lshl_add_u64 v[228:229], v[228:229], 0, s[20:21]
	s_mov_b32 m0, s47
	ds_read_b128 v[206:209], v165
	ds_read_b128 v[210:213], v165 offset:1024
	ds_read_b128 v[220:223], v165 offset:2048
	ds_read_b128 v[224:227], v165 offset:3072
	global_load_lds_dwordx4 v[228:229], off
	v_lshl_add_u64 v[228:229], v[230:231], 0, s[20:21]
	s_add_i32 m0, s47, 0x2000
	s_nop 0
	global_load_lds_dwordx4 v[228:229], off
	s_barrier
; #define PG8_STAGE(bufoff, gbase, voff) do { _Pragma("unroll") for (int _i = 0; _i < 2; ++_i) \
;         __builtin_amdgcn_global_load_lds((const unsigned*)((const char*)(gbase) + (voff)[_i]), (LAS unsigned*)(lds + (bufoff) + ldsw + _i * 8192), 16, 0, 0); } while (0)
; #define PG8_LDA(dst, b, h) do { _Pragma("unroll") for (int m = 0; m < 4; ++m) _Pragma("unroll") for (int k = 0; k < 2; ++k) dst[m][k] = *(const LAS bf16x8*)(lds + PG8_SA(b, h) + aoff + m * 2048 + k * 1024); } while (0)
; #define PG8_MMA(ai, bj, At, Bt) do { __builtin_amdgcn_s_setprio(1); _Pragma("unroll") for (int m = 0; m < 4; ++m) _Pragma("unroll") for (int n = 0; n < 2; ++n) _Pragma("unroll") for (int k = 0; k < 2; ++k) \
;         acc[ai][bj][m][n] = __builtin_amdgcn_mfma_f32_16x16x32_bf16(Bt[n][k], At[m][k], acc[ai][bj][m][n], 0, 0, 0); __builtin_amdgcn_s_setprio(0); } while (0)
; #define PG8_WAIT_V(n) asm volatile("s_waitcnt vmcnt(" #n ")" ::: "memory")
; #define PG8_WAIT_L(n) asm volatile("s_waitcnt lgkmcnt(" #n ")" ::: "memory")
; #define PG8_BAR __builtin_amdgcn_s_barrier()
; #define PG8_SCHED __builtin_amdgcn_sched_barrier(0)
; template <class Epi>
; __device__ __forceinline__ void gemm_phase(LAS unsigned char* lds, const Gemm g, const Epi& E) {
;     ...
;             PG8_BAR; PG8_WAIT_L(0); PG8_MMA(0, 1, At, B1); PG8_BAR;
;             PG8_LDA(At, 1, 1); PG8_STAGE(PG8_SA(1, 0), a3, voffA);
;             PG8_BAR; PG8_WAIT_L(0); PG8_MMA(1, 0, At, B0); PG8_BAR; PG8_SCHED;
;             PG8_STAGE(PG8_SB(1, 1), b3 + hstep, voffB);
;             PG8_WAIT_V(6); PG8_BAR; PG8_MMA(1, 1, At, B1); PG8_BAR;
	s_waitcnt lgkmcnt(0)
	s_setprio 1
	s_waitcnt lgkmcnt(0)
	v_mfma_f32_16x16x32_bf16 v[134:137], v[206:209], v[158:161], v[134:137]
	v_mfma_f32_16x16x32_bf16 v[130:133], v[220:223], v[158:161], v[130:133]
	v_mfma_f32_16x16x32_bf16 v[118:121], v[206:209], v[170:173], v[118:121]
	v_mfma_f32_16x16x32_bf16 v[114:117], v[220:223], v[170:173], v[114:117]
	v_mfma_f32_16x16x32_bf16 v[102:105], v[206:209], v[186:189], v[102:105]
	v_mfma_f32_16x16x32_bf16 v[98:101], v[220:223], v[186:189], v[98:101]
	v_mfma_f32_16x16x32_bf16 v[82:85], v[206:209], v[198:201], v[82:85]
	v_mfma_f32_16x16x32_bf16 v[74:77], v[220:223], v[198:201], v[74:77]
	v_mfma_f32_16x16x32_bf16 v[134:137], v[210:213], v[166:169], v[134:137]
	v_mfma_f32_16x16x32_bf16 v[130:133], v[224:227], v[166:169], v[130:133]
	v_mfma_f32_16x16x32_bf16 v[118:121], v[210:213], v[174:177], v[118:121]
	v_mfma_f32_16x16x32_bf16 v[114:117], v[224:227], v[174:177], v[114:117]
	v_mfma_f32_16x16x32_bf16 v[102:105], v[210:213], v[194:197], v[102:105]
	v_mfma_f32_16x16x32_bf16 v[98:101], v[224:227], v[194:197], v[98:101]
	v_mfma_f32_16x16x32_bf16 v[82:85], v[210:213], v[202:205], v[82:85]
	v_mfma_f32_16x16x32_bf16 v[74:77], v[224:227], v[202:205], v[74:77]
	s_setprio 0
	s_mov_b32 m0, s54
	v_lshl_add_u64 v[228:229], v[232:233], 0, s[20:21]
	s_barrier
	ds_read_b128 v[158:161], v164 offset:49152
	ds_read_b128 v[166:169], v164 offset:50176
	ds_read_b128 v[170:173], v164 offset:51200
	ds_read_b128 v[174:177], v164 offset:52224
	ds_read_b128 v[186:189], v164 offset:53248
	ds_read_b128 v[194:197], v164 offset:54272
	ds_read_b128 v[198:201], v164 offset:55296
	ds_read_b128 v[202:205], v164 offset:56320
	global_load_lds_dwordx4 v[228:229], off
	v_lshl_add_u64 v[228:229], v[234:235], 0, s[20:21]
	s_mov_b32 m0, s55
	s_nop 0
	global_load_lds_dwordx4 v[228:229], off
	s_barrier
	s_waitcnt lgkmcnt(0)
	s_setprio 1
	s_waitcnt lgkmcnt(0)
	v_mfma_f32_16x16x32_bf16 v[66:69], v[62:65], v[158:161], v[66:69]
	v_mfma_f32_16x16x32_bf16 v[58:61], v[78:81], v[158:161], v[58:61]
	v_mfma_f32_16x16x32_bf16 v[46:49], v[62:65], v[170:173], v[46:49]
	v_mfma_f32_16x16x32_bf16 v[42:45], v[78:81], v[170:173], v[42:45]
	v_mfma_f32_16x16x32_bf16 v[30:33], v[62:65], v[186:189], v[30:33]
	v_mfma_f32_16x16x32_bf16 v[26:29], v[78:81], v[186:189], v[26:29]
	v_mfma_f32_16x16x32_bf16 v[14:17], v[62:65], v[198:201], v[14:17]
	v_mfma_f32_16x16x32_bf16 v[8:11], v[78:81], v[198:201], v[8:11]
	v_mfma_f32_16x16x32_bf16 v[66:69], v[70:73], v[166:169], v[66:69]
	v_mfma_f32_16x16x32_bf16 v[58:61], v[86:89], v[166:169], v[58:61]
	v_mfma_f32_16x16x32_bf16 v[46:49], v[70:73], v[174:177], v[46:49]
	v_mfma_f32_16x16x32_bf16 v[42:45], v[86:89], v[174:177], v[42:45]
	v_mfma_f32_16x16x32_bf16 v[30:33], v[70:73], v[194:197], v[30:33]
	v_mfma_f32_16x16x32_bf16 v[26:29], v[86:89], v[194:197], v[26:29]
	v_mfma_f32_16x16x32_bf16 v[14:17], v[70:73], v[202:205], v[14:17]
	v_mfma_f32_16x16x32_bf16 v[8:11], v[86:89], v[202:205], v[8:11]
	s_setprio 0
	s_barrier
	s_add_i32 s46, s46, s25
	v_lshl_add_u64 v[62:63], v[236:237], 0, s[20:21]
	s_mov_b32 m0, s46
	s_nop 0
	global_load_lds_dwordx4 v[62:63], off
	v_lshl_add_u64 v[62:63], v[238:239], 0, s[20:21]
	s_add_i32 m0, s46, 0x2000
	s_nop 0
	global_load_lds_dwordx4 v[62:63], off
	s_waitcnt vmcnt(6)
	s_barrier
	s_setprio 1
	v_mfma_f32_16x16x32_bf16 v[54:57], v[206:209], v[158:161], v[54:57]
	v_mfma_f32_16x16x32_bf16 v[50:53], v[220:223], v[158:161], v[50:53]
	v_mfma_f32_16x16x32_bf16 v[38:41], v[206:209], v[170:173], v[38:41]
	v_mfma_f32_16x16x32_bf16 v[34:37], v[220:223], v[170:173], v[34:37]
	v_mfma_f32_16x16x32_bf16 v[22:25], v[206:209], v[186:189], v[22:25]
	v_mfma_f32_16x16x32_bf16 v[18:21], v[220:223], v[186:189], v[18:21]
	v_mfma_f32_16x16x32_bf16 v[4:7], v[206:209], v[198:201], v[4:7]
	v_mfma_f32_16x16x32_bf16 v[0:3], v[220:223], v[198:201], v[0:3]
	v_mfma_f32_16x16x32_bf16 v[54:57], v[210:213], v[166:169], v[54:57]
	v_mfma_f32_16x16x32_bf16 v[50:53], v[224:227], v[166:169], v[50:53]
	v_mfma_f32_16x16x32_bf16 v[38:41], v[210:213], v[174:177], v[38:41]
	v_mfma_f32_16x16x32_bf16 v[34:37], v[224:227], v[174:177], v[34:37]
	v_mfma_f32_16x16x32_bf16 v[22:25], v[210:213], v[194:197], v[22:25]
	v_mfma_f32_16x16x32_bf16 v[18:21], v[224:227], v[194:197], v[18:21]
	v_mfma_f32_16x16x32_bf16 v[4:7], v[210:213], v[202:205], v[4:7]
	v_mfma_f32_16x16x32_bf16 v[0:3], v[224:227], v[202:205], v[0:3]
	s_setprio 0
	s_add_u32 s44, s44, 0x100
	s_addc_u32 s45, s45, 0
	s_add_u32 s82, s82, 0x100
	s_addc_u32 s83, s83, 0
	s_cmp_ge_i32 s84, s2
	s_mov_b32 s46, s84
	s_barrier
	s_cbranch_scc0 .LBB0_930
	s_nop 0
	s_nop 0
	s_nop 0
	s_nop 0
	s_nop 0
	s_nop 0
	s_nop 0
	s_nop 0
	s_nop 0
	s_nop 0
	s_nop 0
	s_nop 0
	s_nop 0
	s_nop 0
	s_nop 0
	s_nop 0
	s_nop 0
	s_nop 0
	s_nop 0
	s_nop 0
	s_nop 0
	s_nop 0
	s_nop 0
	s_nop 0
	s_nop 0
	s_nop 0
	s_nop 0
	s_nop 0
	s_nop 0
	s_nop 0
	s_nop 0
	s_nop 0
	s_nop 0
	s_nop 0
	v_readlane_b32 s48, v254, 63
	v_readlane_b32 s49, v243, 0
	s_branch .LBB0_917

; template <class Epi>
; __device__ __forceinline__ void gemm_phase(LAS unsigned char* lds, const Gemm g, const Epi& E) {
;     ...
;         if (!has_next) break;
; #pragma unroll
;         for (int a = 0; a < 2; ++a)
; #pragma unroll
;             for (int b = 0; b < 2; ++b)
; #pragma unroll
;                 for (int m = 0; m < 4; ++m)
; #pragma unroll
;                     for (int n = 0; n < 2; ++n) acc[a][b][m][n] = (f32x4){0.f, 0.f, 0.f, 0.f};
;         cur = nxt; cA = nA; cB = nB; ++ui;
.LBB0_1006:
	v_mov_b32_e32 v125, 0
	s_andn2_b64 vcc, exec, s[42:43]
	v_mov_b32_e32 v124, v125
	v_mov_b32_e32 v123, v125
	v_mov_b32_e32 v122, v125
	v_mov_b32_e32 v129, v125
	v_mov_b32_e32 v128, v125
	v_mov_b32_e32 v127, v125
	v_mov_b32_e32 v126, v125
	v_mov_b32_e32 v113, v125
	v_mov_b32_e32 v112, v125
	v_mov_b32_e32 v111, v125
	v_mov_b32_e32 v110, v125
	v_mov_b32_e32 v109, v125
	v_mov_b32_e32 v108, v125
	v_mov_b32_e32 v107, v125
	v_mov_b32_e32 v106, v125
	v_mov_b32_e32 v97, v125
	v_mov_b32_e32 v96, v125
	v_mov_b32_e32 v95, v125
	v_mov_b32_e32 v94, v125
	v_mov_b32_e32 v93, v125
	v_mov_b32_e32 v92, v125
	v_mov_b32_e32 v91, v125
	v_mov_b32_e32 v90, v125
	v_mov_b32_e32 v81, v125
	v_mov_b32_e32 v80, v125
	v_mov_b32_e32 v79, v125
	v_mov_b32_e32 v78, v125
	v_mov_b32_e32 v77, v125
	v_mov_b32_e32 v76, v125
	v_mov_b32_e32 v75, v125
	v_mov_b32_e32 v74, v125
	v_mov_b32_e32 v121, v125
	v_mov_b32_e32 v120, v125
	v_mov_b32_e32 v119, v125
	v_mov_b32_e32 v118, v125
	v_mov_b32_e32 v117, v125
	v_mov_b32_e32 v116, v125
	v_mov_b32_e32 v115, v125
	v_mov_b32_e32 v114, v125
	v_mov_b32_e32 v105, v125
	v_mov_b32_e32 v104, v125
	v_mov_b32_e32 v103, v125
	v_mov_b32_e32 v102, v125
	v_mov_b32_e32 v101, v125
	v_mov_b32_e32 v100, v125
	v_mov_b32_e32 v99, v125
	v_mov_b32_e32 v98, v125
	v_mov_b32_e32 v89, v125
	v_mov_b32_e32 v88, v125
	v_mov_b32_e32 v87, v125
	v_mov_b32_e32 v86, v125
	v_mov_b32_e32 v85, v125
	v_mov_b32_e32 v84, v125
	v_mov_b32_e32 v83, v125
	v_mov_b32_e32 v82, v125
	v_mov_b32_e32 v73, v125
	v_mov_b32_e32 v72, v125
	v_mov_b32_e32 v71, v125
	v_mov_b32_e32 v70, v125
	v_mov_b32_e32 v69, v125
	v_mov_b32_e32 v68, v125
	v_mov_b32_e32 v67, v125
	v_mov_b32_e32 v66, v125
	v_mov_b32_e32 v65, v125
	v_mov_b32_e32 v64, v125
	v_mov_b32_e32 v63, v125
	v_mov_b32_e32 v62, v125
	v_mov_b32_e32 v61, v125
	v_mov_b32_e32 v60, v125
	v_mov_b32_e32 v59, v125
	v_mov_b32_e32 v58, v125
	v_mov_b32_e32 v49, v125
	v_mov_b32_e32 v48, v125
	v_mov_b32_e32 v47, v125
	v_mov_b32_e32 v46, v125
	v_mov_b32_e32 v45, v125
	v_mov_b32_e32 v44, v125
	v_mov_b32_e32 v43, v125
	v_mov_b32_e32 v42, v125
	v_mov_b32_e32 v33, v125
	v_mov_b32_e32 v32, v125
	v_mov_b32_e32 v31, v125
	v_mov_b32_e32 v30, v125
	v_mov_b32_e32 v29, v125
	v_mov_b32_e32 v28, v125
	v_mov_b32_e32 v27, v125
	v_mov_b32_e32 v26, v125
	v_mov_b32_e32 v17, v125
	v_mov_b32_e32 v16, v125
	v_mov_b32_e32 v15, v125
	v_mov_b32_e32 v14, v125
	v_mov_b32_e32 v11, v125
	v_mov_b32_e32 v10, v125
	v_mov_b32_e32 v9, v125
	v_mov_b32_e32 v8, v125
	v_mov_b32_e32 v57, v125
	v_mov_b32_e32 v56, v125
	v_mov_b32_e32 v55, v125
	v_mov_b32_e32 v54, v125
	v_mov_b32_e32 v53, v125
	v_mov_b32_e32 v52, v125
	v_mov_b32_e32 v51, v125
	v_mov_b32_e32 v50, v125
	v_mov_b32_e32 v41, v125
	v_mov_b32_e32 v40, v125
	v_mov_b32_e32 v39, v125
	v_mov_b32_e32 v38, v125
	v_mov_b32_e32 v37, v125
	v_mov_b32_e32 v36, v125
	v_mov_b32_e32 v35, v125
	v_mov_b32_e32 v34, v125
	v_mov_b32_e32 v25, v125
	v_mov_b32_e32 v24, v125
	v_mov_b32_e32 v23, v125
	v_mov_b32_e32 v22, v125
	v_mov_b32_e32 v21, v125
	v_mov_b32_e32 v20, v125
	v_mov_b32_e32 v19, v125
	v_mov_b32_e32 v18, v125
	v_mov_b32_e32 v7, v125
	v_mov_b32_e32 v6, v125
	v_mov_b32_e32 v5, v125
	v_mov_b32_e32 v4, v125
	v_mov_b32_e32 v3, v125
	v_mov_b32_e32 v2, v125
	v_mov_b32_e32 v1, v125
	v_mov_b32_e32 v0, v125
	s_cbranch_vccnz .LBB0_995
	s_add_u32 s44, s44, 0x80
	s_addc_u32 s45, s45, 0
	s_add_u32 s82, s46, 0x100
	v_mov_b32_e32 v0, 0
	s_addc_u32 s83, s47, 0
	s_mov_b32 s46, 0
	v_mov_b32_e32 v1, v0
	v_mov_b32_e32 v2, v0
	v_mov_b32_e32 v3, v0
	v_mov_b32_e32 v4, v0
	v_mov_b32_e32 v5, v0
	v_mov_b32_e32 v6, v0
	v_mov_b32_e32 v7, v0
	v_mov_b32_e32 v18, v0
	v_mov_b32_e32 v19, v0
	v_mov_b32_e32 v20, v0
	v_mov_b32_e32 v21, v0
	v_mov_b32_e32 v22, v0
	v_mov_b32_e32 v23, v0
	v_mov_b32_e32 v24, v0
	v_mov_b32_e32 v25, v0
	v_mov_b32_e32 v34, v0
	v_mov_b32_e32 v35, v0
	v_mov_b32_e32 v36, v0
	v_mov_b32_e32 v37, v0
	v_mov_b32_e32 v38, v0
	v_mov_b32_e32 v39, v0
	v_mov_b32_e32 v40, v0
	v_mov_b32_e32 v41, v0
	v_mov_b32_e32 v50, v0
	v_mov_b32_e32 v51, v0
	v_mov_b32_e32 v52, v0
	v_mov_b32_e32 v53, v0
	v_mov_b32_e32 v54, v0
	v_mov_b32_e32 v55, v0
	v_mov_b32_e32 v56, v0
	v_mov_b32_e32 v57, v0
	v_mov_b32_e32 v8, v0
	v_mov_b32_e32 v9, v0
	v_mov_b32_e32 v10, v0
	v_mov_b32_e32 v11, v0
	v_mov_b32_e32 v14, v0
	v_mov_b32_e32 v15, v0
	v_mov_b32_e32 v16, v0
	v_mov_b32_e32 v17, v0
	v_mov_b32_e32 v26, v0
	v_mov_b32_e32 v27, v0
	v_mov_b32_e32 v28, v0
	v_mov_b32_e32 v29, v0
	v_mov_b32_e32 v30, v0
	v_mov_b32_e32 v31, v0
	v_mov_b32_e32 v32, v0
	v_mov_b32_e32 v33, v0
	v_mov_b32_e32 v42, v0
	v_mov_b32_e32 v43, v0
	v_mov_b32_e32 v44, v0
	v_mov_b32_e32 v45, v0
	v_mov_b32_e32 v46, v0
	v_mov_b32_e32 v47, v0
	v_mov_b32_e32 v48, v0
	v_mov_b32_e32 v49, v0
	v_mov_b32_e32 v58, v0
	v_mov_b32_e32 v59, v0
	v_mov_b32_e32 v60, v0
	v_mov_b32_e32 v61, v0
	v_mov_b32_e32 v62, v0
	v_mov_b32_e32 v63, v0
	v_mov_b32_e32 v64, v0
	v_mov_b32_e32 v65, v0
	v_mov_b32_e32 v66, v0
	v_mov_b32_e32 v67, v0
	v_mov_b32_e32 v68, v0
	v_mov_b32_e32 v69, v0
	v_mov_b32_e32 v70, v0
	v_mov_b32_e32 v71, v0
	v_mov_b32_e32 v72, v0
	v_mov_b32_e32 v73, v0
	v_mov_b32_e32 v82, v0
	v_mov_b32_e32 v83, v0
	v_mov_b32_e32 v84, v0
	v_mov_b32_e32 v85, v0
	v_mov_b32_e32 v86, v0
	v_mov_b32_e32 v87, v0
	v_mov_b32_e32 v88, v0
	v_mov_b32_e32 v89, v0
	v_mov_b32_e32 v98, v0
	v_mov_b32_e32 v99, v0
	v_mov_b32_e32 v100, v0
	v_mov_b32_e32 v101, v0
	v_mov_b32_e32 v102, v0
	v_mov_b32_e32 v103, v0
	v_mov_b32_e32 v104, v0
	v_mov_b32_e32 v105, v0
	v_mov_b32_e32 v114, v0
	v_mov_b32_e32 v115, v0
	v_mov_b32_e32 v116, v0
	v_mov_b32_e32 v117, v0
	v_mov_b32_e32 v118, v0
	v_mov_b32_e32 v119, v0
	v_mov_b32_e32 v120, v0
	v_mov_b32_e32 v121, v0
	v_mov_b32_e32 v74, v0
	v_mov_b32_e32 v75, v0
	v_mov_b32_e32 v76, v0
	v_mov_b32_e32 v77, v0
	v_mov_b32_e32 v78, v0
	v_mov_b32_e32 v79, v0
	v_mov_b32_e32 v80, v0
	v_mov_b32_e32 v81, v0
	v_mov_b32_e32 v90, v0
	v_mov_b32_e32 v91, v0
	v_mov_b32_e32 v92, v0
	v_mov_b32_e32 v93, v0
	v_mov_b32_e32 v94, v0
	v_mov_b32_e32 v95, v0
	v_mov_b32_e32 v96, v0
	v_mov_b32_e32 v97, v0
	v_mov_b32_e32 v106, v0
	v_mov_b32_e32 v107, v0
	v_mov_b32_e32 v108, v0
	v_mov_b32_e32 v109, v0
	v_mov_b32_e32 v110, v0
	v_mov_b32_e32 v111, v0
	v_mov_b32_e32 v112, v0
	v_mov_b32_e32 v113, v0
	v_mov_b32_e32 v126, v0
	v_mov_b32_e32 v127, v0
	v_mov_b32_e32 v128, v0
	v_mov_b32_e32 v129, v0
	v_mov_b32_e32 v122, v0
	v_mov_b32_e32 v123, v0
	v_mov_b32_e32 v124, v0
	v_mov_b32_e32 v125, v0
	s_nop 0
	s_nop 0
	s_nop 0
	s_nop 0
	s_nop 0
	s_nop 0
	s_nop 0
	s_nop 0
	s_nop 0
; #define PG8_STAGE(bufoff, gbase, voff) do { _Pragma("unroll") for (int _i = 0; _i < 2; ++_i) \
;         __builtin_amdgcn_global_load_lds((const unsigned*)((const char*)(gbase) + (voff)[_i]), (LAS unsigned*)(lds + (bufoff) + ldsw + _i * 8192), 16, 0, 0); } while (0)
; #define PG8_LDA(dst, b, h) do { _Pragma("unroll") for (int m = 0; m < 4; ++m) _Pragma("unroll") for (int k = 0; k < 2; ++k) dst[m][k] = *(const LAS bf16x8*)(lds + PG8_SA(b, h) + aoff + m * 2048 + k * 1024); } while (0)
; #define PG8_LDB(dst, b, h) do { _Pragma("unroll") for (int n = 0; n < 2; ++n) _Pragma("unroll") for (int k = 0; k < 2; ++k) dst[n][k] = *(const LAS bf16x8*)(lds + PG8_SB(b, h) + boff + n * 2048 + k * 1024); } while (0)
; #define PG8_MMA(ai, bj, At, Bt) do { __builtin_amdgcn_s_setprio(1); _Pragma("unroll") for (int m = 0; m < 4; ++m) _Pragma("unroll") for (int n = 0; n < 2; ++n) _Pragma("unroll") for (int k = 0; k < 2; ++k) \
;         acc[ai][bj][m][n] = __builtin_amdgcn_mfma_f32_16x16x32_bf16(Bt[n][k], At[m][k], acc[ai][bj][m][n], 0, 0, 0); __builtin_amdgcn_s_setprio(0); } while (0)
; template <class Epi>
; __device__ __forceinline__ void gemm_phase(LAS unsigned char* lds, const Gemm g, const Epi& E) {
;     ...
;         for (int t = 0; t < nt; t += 2) {
;             const bool last = (t == nt - 2);
;             const char* a1 = cA + (size_t)(t + 1) * kstep;
;             const char* a2 = last ? nA : cA + (size_t)(t + 2) * kstep; const char* b2 = last ? nB : cB + (size_t)(t + 2) * kstep;
;             const char* a3 = a2 + kstep; const char* b3 = b2 + kstep;
;             PG8_LDB(B0, 0, 0); PG8_SCHED; PG8_LDA(At, 0, 0); PG8_STAGE(PG8_SA(1, 1), a1 + hstep, voffA);
;             PG8_WAIT_L(8); PG8_BAR; PG8_WAIT_L(0); PG8_MMA(0, 0, At, B0); PG8_BAR; PG8_SCHED;
;             PG8_LDB(B1, 0, 1); PG8_STAGE(PG8_SB(0, 0), b2, voffB);
;             PG8_BAR; PG8_WAIT_L(0); PG8_MMA(0, 1, At, B1); PG8_BAR;
;             PG8_LDA(At, 0, 1); PG8_STAGE(PG8_SA(0, 0), a2, voffA);
;             PG8_BAR; PG8_WAIT_L(0); PG8_MMA(1, 0, At, B0); PG8_BAR; PG8_SCHED;
;             PG8_STAGE(PG8_SB(0, 1), b2 + hstep, voffB);
;             PG8_WAIT_V(6); PG8_BAR; PG8_MMA(1, 1, At, B1); PG8_BAR;
;             PG8_LDB(B0, 1, 0); PG8_SCHED; PG8_LDA(At, 1, 0); PG8_STAGE(PG8_SA(0, 1), a2 + hstep, voffA);
;             PG8_WAIT_L(8); PG8_BAR; PG8_WAIT_L(0); PG8_MMA(0, 0, At, B0); PG8_BAR; PG8_SCHED;
.LBB0_1008:
	s_add_i32 s84, s46, 2
	s_add_u32 s48, s44, 0x80
	s_addc_u32 s47, s45, 0
	s_add_i32 s85, 0, 0x10000
	v_add_u32_e32 v149, s85, v147
	ds_read_b128 v[142:145], v149
	ds_read_b128 v[150:153], v149 offset:1024
	ds_read_b128 v[154:157], v149 offset:2048
	ds_read_b128 v[158:161], v149 offset:3072
	s_cmp_eq_u32 s58, s46
	s_cselect_b32 s46, s0, s48
	s_cselect_b32 s47, s1, s47
	s_cselect_b32 s49, s39, s83
	s_cselect_b32 s48, s38, s82
	v_lshl_add_u64 v[206:207], s[44:45], 0, v[138:139]
	s_add_i32 m0, s50, 0xc000
	ds_read_b128 v[162:165], v148
	ds_read_b128 v[166:169], v148 offset:1024
	ds_read_b128 v[170:173], v148 offset:2048
	ds_read_b128 v[174:177], v148 offset:3072
	ds_read_b128 v[186:189], v148 offset:4096
	ds_read_b128 v[194:197], v148 offset:5120
	ds_read_b128 v[198:201], v148 offset:6144
	ds_read_b128 v[202:205], v148 offset:7168
	global_load_lds_dwordx4 v[206:207], off
	v_lshl_add_u64 v[206:207], s[44:45], 0, v[140:141]
	s_add_i32 m0, s50, 0xe000
	s_nop 0
	global_load_lds_dwordx4 v[206:207], off
	s_waitcnt lgkmcnt(8)
	s_barrier
	s_waitcnt lgkmcnt(0)
	s_setprio 1
	s_waitcnt lgkmcnt(0)
	v_mfma_f32_16x16x32_bf16 v[122:125], v[142:145], v[162:165], v[122:125]
	v_mfma_f32_16x16x32_bf16 v[126:129], v[154:157], v[162:165], v[126:129]
	v_mfma_f32_16x16x32_bf16 v[110:113], v[142:145], v[170:173], v[110:113]
	v_mfma_f32_16x16x32_bf16 v[106:109], v[154:157], v[170:173], v[106:109]
	v_mfma_f32_16x16x32_bf16 v[94:97], v[142:145], v[186:189], v[94:97]
	v_mfma_f32_16x16x32_bf16 v[90:93], v[154:157], v[186:189], v[90:93]
	v_mfma_f32_16x16x32_bf16 v[78:81], v[142:145], v[198:201], v[78:81]
	v_mfma_f32_16x16x32_bf16 v[74:77], v[154:157], v[198:201], v[74:77]
	v_mfma_f32_16x16x32_bf16 v[122:125], v[150:153], v[166:169], v[122:125]
	v_mfma_f32_16x16x32_bf16 v[126:129], v[158:161], v[166:169], v[126:129]
	v_mfma_f32_16x16x32_bf16 v[110:113], v[150:153], v[174:177], v[110:113]
	v_mfma_f32_16x16x32_bf16 v[106:109], v[158:161], v[174:177], v[106:109]
	v_mfma_f32_16x16x32_bf16 v[94:97], v[150:153], v[194:197], v[94:97]
	v_mfma_f32_16x16x32_bf16 v[90:93], v[158:161], v[194:197], v[90:93]
	v_mfma_f32_16x16x32_bf16 v[78:81], v[150:153], v[202:205], v[78:81]
	v_mfma_f32_16x16x32_bf16 v[74:77], v[158:161], v[202:205], v[74:77]
	s_setprio 0
	s_barrier
	s_add_i32 s86, 0, 0x14000
	s_add_i32 s85, s85, s25
	v_add_u32_e32 v149, s86, v147
	v_lshl_add_u64 v[228:229], s[48:49], 0, v[132:133]
	s_mov_b32 m0, s85
	ds_read_b128 v[206:209], v149
	ds_read_b128 v[210:213], v149 offset:1024
	ds_read_b128 v[220:223], v149 offset:2048
	ds_read_b128 v[224:227], v149 offset:3072
	global_load_lds_dwordx4 v[228:229], off
	v_lshl_add_u64 v[230:231], s[48:49], 0, v[136:137]
	s_add_i32 m0, s85, 0x2000
	s_nop 0
	global_load_lds_dwordx4 v[230:231], off
	s_barrier
	s_waitcnt lgkmcnt(0)
	s_setprio 1
	s_waitcnt lgkmcnt(0)
	v_mfma_f32_16x16x32_bf16 v[118:121], v[206:209], v[162:165], v[118:121]
	v_mfma_f32_16x16x32_bf16 v[114:117], v[220:223], v[162:165], v[114:117]
	v_mfma_f32_16x16x32_bf16 v[102:105], v[206:209], v[170:173], v[102:105]
	v_mfma_f32_16x16x32_bf16 v[98:101], v[220:223], v[170:173], v[98:101]
	v_mfma_f32_16x16x32_bf16 v[86:89], v[206:209], v[186:189], v[86:89]
	v_mfma_f32_16x16x32_bf16 v[82:85], v[220:223], v[186:189], v[82:85]
	v_mfma_f32_16x16x32_bf16 v[70:73], v[206:209], v[198:201], v[70:73]
	v_mfma_f32_16x16x32_bf16 v[66:69], v[220:223], v[198:201], v[66:69]
	v_mfma_f32_16x16x32_bf16 v[118:121], v[210:213], v[166:169], v[118:121]
	v_mfma_f32_16x16x32_bf16 v[114:117], v[224:227], v[166:169], v[114:117]
	v_mfma_f32_16x16x32_bf16 v[102:105], v[210:213], v[174:177], v[102:105]
	v_mfma_f32_16x16x32_bf16 v[98:101], v[224:227], v[174:177], v[98:101]
	v_mfma_f32_16x16x32_bf16 v[86:89], v[210:213], v[194:197], v[86:89]
	v_mfma_f32_16x16x32_bf16 v[82:85], v[224:227], v[194:197], v[82:85]
	v_mfma_f32_16x16x32_bf16 v[70:73], v[210:213], v[202:205], v[70:73]
	v_mfma_f32_16x16x32_bf16 v[66:69], v[224:227], v[202:205], v[66:69]
	s_setprio 0
	s_mov_b32 m0, s50
	v_lshl_add_u64 v[232:233], s[46:47], 0, v[130:131]
	s_barrier
	ds_read_b128 v[162:165], v148 offset:16384
	ds_read_b128 v[166:169], v148 offset:17408
	ds_read_b128 v[170:173], v148 offset:18432
	ds_read_b128 v[174:177], v148 offset:19456
	ds_read_b128 v[186:189], v148 offset:20480
	ds_read_b128 v[194:197], v148 offset:21504
	ds_read_b128 v[198:201], v148 offset:22528
	ds_read_b128 v[202:205], v148 offset:23552
	global_load_lds_dwordx4 v[232:233], off
	v_lshl_add_u64 v[234:235], s[46:47], 0, v[134:135]
	s_mov_b32 m0, s51
	s_nop 0
	global_load_lds_dwordx4 v[234:235], off
	s_barrier
	s_waitcnt lgkmcnt(0)
	s_setprio 1
	s_waitcnt lgkmcnt(0)
	v_mfma_f32_16x16x32_bf16 v[62:65], v[142:145], v[162:165], v[62:65]
	v_mfma_f32_16x16x32_bf16 v[58:61], v[154:157], v[162:165], v[58:61]
	v_mfma_f32_16x16x32_bf16 v[46:49], v[142:145], v[170:173], v[46:49]
	v_mfma_f32_16x16x32_bf16 v[42:45], v[154:157], v[170:173], v[42:45]
	v_mfma_f32_16x16x32_bf16 v[30:33], v[142:145], v[186:189], v[30:33]
	v_mfma_f32_16x16x32_bf16 v[26:29], v[154:157], v[186:189], v[26:29]
	v_mfma_f32_16x16x32_bf16 v[14:17], v[142:145], v[198:201], v[14:17]
	v_mfma_f32_16x16x32_bf16 v[8:11], v[154:157], v[198:201], v[8:11]
	v_mfma_f32_16x16x32_bf16 v[62:65], v[150:153], v[166:169], v[62:65]
	v_mfma_f32_16x16x32_bf16 v[58:61], v[158:161], v[166:169], v[58:61]
	v_mfma_f32_16x16x32_bf16 v[46:49], v[150:153], v[174:177], v[46:49]
	v_mfma_f32_16x16x32_bf16 v[42:45], v[158:161], v[174:177], v[42:45]
	v_mfma_f32_16x16x32_bf16 v[30:33], v[150:153], v[194:197], v[30:33]
	v_mfma_f32_16x16x32_bf16 v[26:29], v[158:161], v[194:197], v[26:29]
	v_mfma_f32_16x16x32_bf16 v[14:17], v[150:153], v[202:205], v[14:17]
	v_mfma_f32_16x16x32_bf16 v[8:11], v[158:161], v[202:205], v[8:11]
	s_setprio 0
	s_barrier
; #define PG8_STAGE(bufoff, gbase, voff) do { _Pragma("unroll") for (int _i = 0; _i < 2; ++_i) \
;         __builtin_amdgcn_global_load_lds((const unsigned*)((const char*)(gbase) + (voff)[_i]), (LAS unsigned*)(lds + (bufoff) + ldsw + _i * 8192), 16, 0, 0); } while (0)
; #define PG8_LDA(dst, b, h) do { _Pragma("unroll") for (int m = 0; m < 4; ++m) _Pragma("unroll") for (int k = 0; k < 2; ++k) dst[m][k] = *(const LAS bf16x8*)(lds + PG8_SA(b, h) + aoff + m * 2048 + k * 1024); } while (0)
; #define PG8_LDB(dst, b, h) do { _Pragma("unroll") for (int n = 0; n < 2; ++n) _Pragma("unroll") for (int k = 0; k < 2; ++k) dst[n][k] = *(const LAS bf16x8*)(lds + PG8_SB(b, h) + boff + n * 2048 + k * 1024); } while (0)
; #define PG8_MMA(ai, bj, At, Bt) do { __builtin_amdgcn_s_setprio(1); _Pragma("unroll") for (int m = 0; m < 4; ++m) _Pragma("unroll") for (int n = 0; n < 2; ++n) _Pragma("unroll") for (int k = 0; k < 2; ++k) \
;         acc[ai][bj][m][n] = __builtin_amdgcn_mfma_f32_16x16x32_bf16(Bt[n][k], At[m][k], acc[ai][bj][m][n], 0, 0, 0); __builtin_amdgcn_s_setprio(0); } while (0)
; #define PG8_WAIT_V(n) asm volatile("s_waitcnt vmcnt(" #n ")" ::: "memory")
; #define PG8_WAIT_L(n) asm volatile("s_waitcnt lgkmcnt(" #n ")" ::: "memory")
; #define PG8_BAR __builtin_amdgcn_s_barrier()
; #define PG8_SCHED __builtin_amdgcn_sched_barrier(0)
; template <class Epi>
; __device__ __forceinline__ void gemm_phase(LAS unsigned char* lds, const Gemm g, const Epi& E) {
;     ...
;             PG8_WAIT_V(6); PG8_BAR; PG8_MMA(1, 1, At, B1); PG8_BAR;
;             PG8_LDB(B0, 1, 0); PG8_SCHED; PG8_LDA(At, 1, 0); PG8_STAGE(PG8_SA(0, 1), a2 + hstep, voffA);
;             PG8_WAIT_L(8); PG8_BAR; PG8_WAIT_L(0); PG8_MMA(0, 0, At, B0); PG8_BAR; PG8_SCHED;
;             PG8_LDB(B1, 1, 1); PG8_STAGE(PG8_SB(1, 0), b3, voffB);
;             PG8_BAR; PG8_WAIT_L(0); PG8_MMA(0, 1, At, B1); PG8_BAR;
;             PG8_LDA(At, 1, 1); PG8_STAGE(PG8_SA(1, 0), a3, voffA);
	s_add_u32 s48, s48, s26
	s_addc_u32 s49, s49, s27
	s_add_i32 s85, s86, s25
	v_lshl_add_u64 v[236:237], s[48:49], 0, v[132:133]
	s_mov_b32 m0, s85
	v_lshl_add_u64 v[238:239], s[48:49], 0, v[136:137]
	global_load_lds_dwordx4 v[236:237], off
	s_add_i32 m0, s85, 0x2000
	s_nop 0
	global_load_lds_dwordx4 v[238:239], off
	s_waitcnt vmcnt(6)
	s_barrier
	s_setprio 1
	v_mfma_f32_16x16x32_bf16 v[54:57], v[206:209], v[162:165], v[54:57]
	v_mfma_f32_16x16x32_bf16 v[50:53], v[220:223], v[162:165], v[50:53]
	v_mfma_f32_16x16x32_bf16 v[38:41], v[206:209], v[170:173], v[38:41]
	v_mfma_f32_16x16x32_bf16 v[34:37], v[220:223], v[170:173], v[34:37]
	v_mfma_f32_16x16x32_bf16 v[22:25], v[206:209], v[186:189], v[22:25]
	v_mfma_f32_16x16x32_bf16 v[18:21], v[220:223], v[186:189], v[18:21]
	v_mfma_f32_16x16x32_bf16 v[4:7], v[206:209], v[198:201], v[4:7]
	v_mfma_f32_16x16x32_bf16 v[0:3], v[220:223], v[198:201], v[0:3]
	v_mfma_f32_16x16x32_bf16 v[54:57], v[210:213], v[166:169], v[54:57]
	v_mfma_f32_16x16x32_bf16 v[50:53], v[224:227], v[166:169], v[50:53]
	v_mfma_f32_16x16x32_bf16 v[38:41], v[210:213], v[174:177], v[38:41]
	v_mfma_f32_16x16x32_bf16 v[34:37], v[224:227], v[174:177], v[34:37]
	v_mfma_f32_16x16x32_bf16 v[22:25], v[210:213], v[194:197], v[22:25]
	v_mfma_f32_16x16x32_bf16 v[18:21], v[224:227], v[194:197], v[18:21]
	v_mfma_f32_16x16x32_bf16 v[4:7], v[210:213], v[202:205], v[4:7]
	v_mfma_f32_16x16x32_bf16 v[0:3], v[224:227], v[202:205], v[0:3]
	s_setprio 0
	s_add_i32 s48, 0, 0x18000
	v_add_u32_e32 v149, s48, v147
	s_barrier
	ds_read_b128 v[142:145], v149
	ds_read_b128 v[150:153], v149 offset:1024
	ds_read_b128 v[154:157], v149 offset:2048
	ds_read_b128 v[158:161], v149 offset:3072
	s_add_u32 s46, s46, s26
	s_addc_u32 s47, s47, s27
	s_mov_b32 m0, s52
	v_lshl_add_u64 v[206:207], s[46:47], 0, v[130:131]
	ds_read_b128 v[162:165], v148 offset:32768
	ds_read_b128 v[166:169], v148 offset:33792
	ds_read_b128 v[170:173], v148 offset:34816
	ds_read_b128 v[174:177], v148 offset:35840
	ds_read_b128 v[186:189], v148 offset:36864
	ds_read_b128 v[194:197], v148 offset:37888
	ds_read_b128 v[198:201], v148 offset:38912
	ds_read_b128 v[202:205], v148 offset:39936
	global_load_lds_dwordx4 v[206:207], off
	v_lshl_add_u64 v[206:207], s[46:47], 0, v[134:135]
	s_mov_b32 m0, s53
	s_nop 0
	global_load_lds_dwordx4 v[206:207], off
	s_waitcnt lgkmcnt(8)
	s_barrier
	s_waitcnt lgkmcnt(0)
	s_setprio 1
	s_waitcnt lgkmcnt(0)
	v_mfma_f32_16x16x32_bf16 v[122:125], v[142:145], v[162:165], v[122:125]
	v_mfma_f32_16x16x32_bf16 v[126:129], v[154:157], v[162:165], v[126:129]
	v_mfma_f32_16x16x32_bf16 v[110:113], v[142:145], v[170:173], v[110:113]
	v_mfma_f32_16x16x32_bf16 v[106:109], v[154:157], v[170:173], v[106:109]
	v_mfma_f32_16x16x32_bf16 v[94:97], v[142:145], v[186:189], v[94:97]
	v_mfma_f32_16x16x32_bf16 v[90:93], v[154:157], v[186:189], v[90:93]
	v_mfma_f32_16x16x32_bf16 v[78:81], v[142:145], v[198:201], v[78:81]
	v_mfma_f32_16x16x32_bf16 v[74:77], v[154:157], v[198:201], v[74:77]
	v_mfma_f32_16x16x32_bf16 v[122:125], v[150:153], v[166:169], v[122:125]
	v_mfma_f32_16x16x32_bf16 v[126:129], v[158:161], v[166:169], v[126:129]
	v_mfma_f32_16x16x32_bf16 v[110:113], v[150:153], v[174:177], v[110:113]
	v_mfma_f32_16x16x32_bf16 v[106:109], v[158:161], v[174:177], v[106:109]
	v_mfma_f32_16x16x32_bf16 v[94:97], v[150:153], v[194:197], v[94:97]
	v_mfma_f32_16x16x32_bf16 v[90:93], v[158:161], v[194:197], v[90:93]
	v_mfma_f32_16x16x32_bf16 v[78:81], v[150:153], v[202:205], v[78:81]
	v_mfma_f32_16x16x32_bf16 v[74:77], v[158:161], v[202:205], v[74:77]
	s_setprio 0
	s_barrier
	s_add_i32 s46, 0, 0x1c000
	s_add_i32 s47, s48, s25
	v_add_u32_e32 v149, s46, v147
	v_lshl_add_u64 v[228:229], v[228:229], 0, s[20:21]
	s_mov_b32 m0, s47
	ds_read_b128 v[206:209], v149
	ds_read_b128 v[210:213], v149 offset:1024
	ds_read_b128 v[220:223], v149 offset:2048
	ds_read_b128 v[224:227], v149 offset:3072
	global_load_lds_dwordx4 v[228:229], off
	v_lshl_add_u64 v[228:229], v[230:231], 0, s[20:21]
	s_add_i32 m0, s47, 0x2000
	s_nop 0
	global_load_lds_dwordx4 v[228:229], off
	s_barrier
; #define PG8_STAGE(bufoff, gbase, voff) do { _Pragma("unroll") for (int _i = 0; _i < 2; ++_i) \
;         __builtin_amdgcn_global_load_lds((const unsigned*)((const char*)(gbase) + (voff)[_i]), (LAS unsigned*)(lds + (bufoff) + ldsw + _i * 8192), 16, 0, 0); } while (0)
; #define PG8_LDA(dst, b, h) do { _Pragma("unroll") for (int m = 0; m < 4; ++m) _Pragma("unroll") for (int k = 0; k < 2; ++k) dst[m][k] = *(const LAS bf16x8*)(lds + PG8_SA(b, h) + aoff + m * 2048 + k * 1024); } while (0)
; #define PG8_MMA(ai, bj, At, Bt) do { __builtin_amdgcn_s_setprio(1); _Pragma("unroll") for (int m = 0; m < 4; ++m) _Pragma("unroll") for (int n = 0; n < 2; ++n) _Pragma("unroll") for (int k = 0; k < 2; ++k) \
;         acc[ai][bj][m][n] = __builtin_amdgcn_mfma_f32_16x16x32_bf16(Bt[n][k], At[m][k], acc[ai][bj][m][n], 0, 0, 0); __builtin_amdgcn_s_setprio(0); } while (0)
; #define PG8_WAIT_V(n) asm volatile("s_waitcnt vmcnt(" #n ")" ::: "memory")
; #define PG8_WAIT_L(n) asm volatile("s_waitcnt lgkmcnt(" #n ")" ::: "memory")
; #define PG8_BAR __builtin_amdgcn_s_barrier()
; #define PG8_SCHED __builtin_amdgcn_sched_barrier(0)
; template <class Epi>
; __device__ __forceinline__ void gemm_phase(LAS unsigned char* lds, const Gemm g, const Epi& E) {
;     ...
;             PG8_BAR; PG8_WAIT_L(0); PG8_MMA(0, 1, At, B1); PG8_BAR;
;             PG8_LDA(At, 1, 1); PG8_STAGE(PG8_SA(1, 0), a3, voffA);
;             PG8_BAR; PG8_WAIT_L(0); PG8_MMA(1, 0, At, B0); PG8_BAR; PG8_SCHED;
;             PG8_STAGE(PG8_SB(1, 1), b3 + hstep, voffB);
;             PG8_WAIT_V(6); PG8_BAR; PG8_MMA(1, 1, At, B1); PG8_BAR;
	s_waitcnt lgkmcnt(0)
	s_setprio 1
	s_waitcnt lgkmcnt(0)
	v_mfma_f32_16x16x32_bf16 v[118:121], v[206:209], v[162:165], v[118:121]
	v_mfma_f32_16x16x32_bf16 v[114:117], v[220:223], v[162:165], v[114:117]
	v_mfma_f32_16x16x32_bf16 v[102:105], v[206:209], v[170:173], v[102:105]
	v_mfma_f32_16x16x32_bf16 v[98:101], v[220:223], v[170:173], v[98:101]
	v_mfma_f32_16x16x32_bf16 v[86:89], v[206:209], v[186:189], v[86:89]
	v_mfma_f32_16x16x32_bf16 v[82:85], v[220:223], v[186:189], v[82:85]
	v_mfma_f32_16x16x32_bf16 v[70:73], v[206:209], v[198:201], v[70:73]
	v_mfma_f32_16x16x32_bf16 v[66:69], v[220:223], v[198:201], v[66:69]
	v_mfma_f32_16x16x32_bf16 v[118:121], v[210:213], v[166:169], v[118:121]
	v_mfma_f32_16x16x32_bf16 v[114:117], v[224:227], v[166:169], v[114:117]
	v_mfma_f32_16x16x32_bf16 v[102:105], v[210:213], v[174:177], v[102:105]
	v_mfma_f32_16x16x32_bf16 v[98:101], v[224:227], v[174:177], v[98:101]
	v_mfma_f32_16x16x32_bf16 v[86:89], v[210:213], v[194:197], v[86:89]
	v_mfma_f32_16x16x32_bf16 v[82:85], v[224:227], v[194:197], v[82:85]
	v_mfma_f32_16x16x32_bf16 v[70:73], v[210:213], v[202:205], v[70:73]
	v_mfma_f32_16x16x32_bf16 v[66:69], v[224:227], v[202:205], v[66:69]
	s_setprio 0
	s_mov_b32 m0, s54
	v_lshl_add_u64 v[228:229], v[232:233], 0, s[20:21]
	s_barrier
	ds_read_b128 v[162:165], v148 offset:49152
	ds_read_b128 v[166:169], v148 offset:50176
	ds_read_b128 v[170:173], v148 offset:51200
	ds_read_b128 v[174:177], v148 offset:52224
	ds_read_b128 v[186:189], v148 offset:53248
	ds_read_b128 v[194:197], v148 offset:54272
	ds_read_b128 v[198:201], v148 offset:55296
	ds_read_b128 v[202:205], v148 offset:56320
	global_load_lds_dwordx4 v[228:229], off
	v_lshl_add_u64 v[228:229], v[234:235], 0, s[20:21]
	s_mov_b32 m0, s55
	s_nop 0
	global_load_lds_dwordx4 v[228:229], off
	s_barrier
	s_waitcnt lgkmcnt(0)
	s_setprio 1
	s_waitcnt lgkmcnt(0)
	v_mfma_f32_16x16x32_bf16 v[62:65], v[142:145], v[162:165], v[62:65]
	v_mfma_f32_16x16x32_bf16 v[58:61], v[154:157], v[162:165], v[58:61]
	v_mfma_f32_16x16x32_bf16 v[46:49], v[142:145], v[170:173], v[46:49]
	v_mfma_f32_16x16x32_bf16 v[42:45], v[154:157], v[170:173], v[42:45]
	v_mfma_f32_16x16x32_bf16 v[30:33], v[142:145], v[186:189], v[30:33]
	v_mfma_f32_16x16x32_bf16 v[26:29], v[154:157], v[186:189], v[26:29]
	v_mfma_f32_16x16x32_bf16 v[14:17], v[142:145], v[198:201], v[14:17]
	v_mfma_f32_16x16x32_bf16 v[8:11], v[154:157], v[198:201], v[8:11]
	v_mfma_f32_16x16x32_bf16 v[62:65], v[150:153], v[166:169], v[62:65]
	v_mfma_f32_16x16x32_bf16 v[58:61], v[158:161], v[166:169], v[58:61]
	v_mfma_f32_16x16x32_bf16 v[46:49], v[150:153], v[174:177], v[46:49]
	v_mfma_f32_16x16x32_bf16 v[42:45], v[158:161], v[174:177], v[42:45]
	v_mfma_f32_16x16x32_bf16 v[30:33], v[150:153], v[194:197], v[30:33]
	v_mfma_f32_16x16x32_bf16 v[26:29], v[158:161], v[194:197], v[26:29]
	v_mfma_f32_16x16x32_bf16 v[14:17], v[150:153], v[202:205], v[14:17]
	v_mfma_f32_16x16x32_bf16 v[8:11], v[158:161], v[202:205], v[8:11]
	s_setprio 0
	s_barrier
	s_add_i32 s46, s46, s25
	v_lshl_add_u64 v[142:143], v[236:237], 0, s[20:21]
	s_mov_b32 m0, s46
	s_nop 0
	global_load_lds_dwordx4 v[142:143], off
	v_lshl_add_u64 v[142:143], v[238:239], 0, s[20:21]
	s_add_i32 m0, s46, 0x2000
	s_nop 0
	global_load_lds_dwordx4 v[142:143], off
	s_waitcnt vmcnt(6)
	s_barrier
	s_setprio 1
	v_mfma_f32_16x16x32_bf16 v[54:57], v[206:209], v[162:165], v[54:57]
	v_mfma_f32_16x16x32_bf16 v[50:53], v[220:223], v[162:165], v[50:53]
	v_mfma_f32_16x16x32_bf16 v[38:41], v[206:209], v[170:173], v[38:41]
	v_mfma_f32_16x16x32_bf16 v[34:37], v[220:223], v[170:173], v[34:37]
	v_mfma_f32_16x16x32_bf16 v[22:25], v[206:209], v[186:189], v[22:25]
	v_mfma_f32_16x16x32_bf16 v[18:21], v[220:223], v[186:189], v[18:21]
	v_mfma_f32_16x16x32_bf16 v[4:7], v[206:209], v[198:201], v[4:7]
	v_mfma_f32_16x16x32_bf16 v[0:3], v[220:223], v[198:201], v[0:3]
	v_mfma_f32_16x16x32_bf16 v[54:57], v[210:213], v[166:169], v[54:57]
	v_mfma_f32_16x16x32_bf16 v[50:53], v[224:227], v[166:169], v[50:53]
	v_mfma_f32_16x16x32_bf16 v[38:41], v[210:213], v[174:177], v[38:41]
	v_mfma_f32_16x16x32_bf16 v[34:37], v[224:227], v[174:177], v[34:37]
	v_mfma_f32_16x16x32_bf16 v[22:25], v[210:213], v[194:197], v[22:25]
	v_mfma_f32_16x16x32_bf16 v[18:21], v[224:227], v[194:197], v[18:21]
	v_mfma_f32_16x16x32_bf16 v[4:7], v[210:213], v[202:205], v[4:7]
	v_mfma_f32_16x16x32_bf16 v[0:3], v[224:227], v[202:205], v[0:3]
	s_setprio 0
	s_add_u32 s44, s44, 0x100
	s_addc_u32 s45, s45, 0
	s_add_u32 s82, s82, 0x100
	s_addc_u32 s83, s83, 0
	s_cmp_ge_i32 s84, s2
	s_mov_b32 s46, s84
	s_barrier
	s_cbranch_scc0 .LBB0_1008
	s_nop 0
	s_nop 0
	s_nop 0
	s_nop 0
	s_nop 0
	s_nop 0
	s_nop 0
	s_nop 0
	s_nop 0
	s_nop 0
	s_nop 0
	s_nop 0
	s_nop 0
	s_nop 0
	s_nop 0
	s_nop 0
	s_nop 0
	s_nop 0
	s_nop 0
	s_nop 0
	s_nop 0
	s_nop 0
	s_nop 0
	s_nop 0
	s_nop 0
	s_nop 0
	s_nop 0
	s_nop 0
	s_nop 0
	s_nop 0
	s_nop 0
	s_nop 0
	s_nop 0
	s_nop 0
	s_nop 0
	s_nop 0
	s_nop 0
	s_nop 0
	s_nop 0
	s_nop 0
	s_nop 0
	s_nop 0
	s_nop 0
	s_nop 0
	s_nop 0
	s_nop 0
	s_nop 0
	s_nop 0
	s_nop 0
	s_nop 0
	s_nop 0
	s_nop 0
	s_nop 0
	s_nop 0
	s_nop 0
	v_readlane_b32 s48, v254, 63
	v_readlane_b32 s49, v243, 0
	s_branch .LBB0_995

; template <class Epi>
; __device__ __forceinline__ void gemm_phase(LAS unsigned char* lds, const Gemm g, const Epi& E) {
;     ...
;         const bool has_next = S.next(ui + 1, nxt);
;         const char* nA = has_next ? (const char*)g.A + (size_t)nxt.pm * tstep : cA; const char* nB = has_next ? (const char*)g.Bt + (size_t)nxt.pn * tstep : cB;
; #pragma unroll 1
;         for (int t = 0; t < nt; t += 2) {
;     ...
;         if (!has_next) break;
; #pragma unroll
;         for (int a = 0; a < 2; ++a)
; #pragma unroll
;             for (int b = 0; b < 2; ++b)
; #pragma unroll
;                 for (int m = 0; m < 4; ++m)
; #pragma unroll
;                     for (int n = 0; n < 2; ++n) acc[a][b][m][n] = (f32x4){0.f, 0.f, 0.f, 0.f};
;         cur = nxt; cA = nA; cB = nB; ++ui;
.LBB0_1032:
	v_mov_b32_e32 v125, 0
	s_andn2_b64 vcc, exec, s[42:43]
	v_mov_b32_e32 v124, v125
	v_mov_b32_e32 v123, v125
	v_mov_b32_e32 v122, v125
	v_mov_b32_e32 v129, v125
	v_mov_b32_e32 v128, v125
	v_mov_b32_e32 v127, v125
	v_mov_b32_e32 v126, v125
	v_mov_b32_e32 v113, v125
	v_mov_b32_e32 v112, v125
	v_mov_b32_e32 v111, v125
	v_mov_b32_e32 v110, v125
	v_mov_b32_e32 v109, v125
	v_mov_b32_e32 v108, v125
	v_mov_b32_e32 v107, v125
	v_mov_b32_e32 v106, v125
	v_mov_b32_e32 v97, v125
	v_mov_b32_e32 v96, v125
	v_mov_b32_e32 v95, v125
	v_mov_b32_e32 v94, v125
	v_mov_b32_e32 v93, v125
	v_mov_b32_e32 v92, v125
	v_mov_b32_e32 v91, v125
	v_mov_b32_e32 v90, v125
	v_mov_b32_e32 v81, v125
	v_mov_b32_e32 v80, v125
	v_mov_b32_e32 v79, v125
	v_mov_b32_e32 v78, v125
	v_mov_b32_e32 v77, v125
	v_mov_b32_e32 v76, v125
	v_mov_b32_e32 v75, v125
	v_mov_b32_e32 v74, v125
	v_mov_b32_e32 v121, v125
	v_mov_b32_e32 v120, v125
	v_mov_b32_e32 v119, v125
	v_mov_b32_e32 v118, v125
	v_mov_b32_e32 v117, v125
	v_mov_b32_e32 v116, v125
	v_mov_b32_e32 v115, v125
	v_mov_b32_e32 v114, v125
	v_mov_b32_e32 v105, v125
	v_mov_b32_e32 v104, v125
	v_mov_b32_e32 v103, v125
	v_mov_b32_e32 v102, v125
	v_mov_b32_e32 v101, v125
	v_mov_b32_e32 v100, v125
	v_mov_b32_e32 v99, v125
	v_mov_b32_e32 v98, v125
	v_mov_b32_e32 v89, v125
	v_mov_b32_e32 v88, v125
	v_mov_b32_e32 v87, v125
	v_mov_b32_e32 v86, v125
	v_mov_b32_e32 v85, v125
	v_mov_b32_e32 v84, v125
	v_mov_b32_e32 v83, v125
	v_mov_b32_e32 v82, v125
	v_mov_b32_e32 v73, v125
	v_mov_b32_e32 v72, v125
	v_mov_b32_e32 v71, v125
	v_mov_b32_e32 v70, v125
	v_mov_b32_e32 v69, v125
	v_mov_b32_e32 v68, v125
	v_mov_b32_e32 v67, v125
	v_mov_b32_e32 v66, v125
	v_mov_b32_e32 v65, v125
	v_mov_b32_e32 v64, v125
	v_mov_b32_e32 v63, v125
	v_mov_b32_e32 v62, v125
	v_mov_b32_e32 v61, v125
	v_mov_b32_e32 v60, v125
	v_mov_b32_e32 v59, v125
	v_mov_b32_e32 v58, v125
	v_mov_b32_e32 v49, v125
	v_mov_b32_e32 v48, v125
	v_mov_b32_e32 v47, v125
	v_mov_b32_e32 v46, v125
	v_mov_b32_e32 v45, v125
	v_mov_b32_e32 v44, v125
	v_mov_b32_e32 v43, v125
	v_mov_b32_e32 v42, v125
	v_mov_b32_e32 v33, v125
	v_mov_b32_e32 v32, v125
	v_mov_b32_e32 v31, v125
	v_mov_b32_e32 v30, v125
	v_mov_b32_e32 v29, v125
	v_mov_b32_e32 v28, v125
	v_mov_b32_e32 v27, v125
	v_mov_b32_e32 v26, v125
	v_mov_b32_e32 v17, v125
	v_mov_b32_e32 v16, v125
	v_mov_b32_e32 v15, v125
	v_mov_b32_e32 v14, v125
	v_mov_b32_e32 v11, v125
	v_mov_b32_e32 v10, v125
	v_mov_b32_e32 v9, v125
	v_mov_b32_e32 v8, v125
	v_mov_b32_e32 v57, v125
	v_mov_b32_e32 v56, v125
	v_mov_b32_e32 v55, v125
	v_mov_b32_e32 v54, v125
	v_mov_b32_e32 v53, v125
	v_mov_b32_e32 v52, v125
	v_mov_b32_e32 v51, v125
	v_mov_b32_e32 v50, v125
	v_mov_b32_e32 v41, v125
	v_mov_b32_e32 v40, v125
	v_mov_b32_e32 v39, v125
	v_mov_b32_e32 v38, v125
	v_mov_b32_e32 v37, v125
	v_mov_b32_e32 v36, v125
	v_mov_b32_e32 v35, v125
	v_mov_b32_e32 v34, v125
	v_mov_b32_e32 v25, v125
	v_mov_b32_e32 v24, v125
	v_mov_b32_e32 v23, v125
	v_mov_b32_e32 v22, v125
	v_mov_b32_e32 v21, v125
	v_mov_b32_e32 v20, v125
	v_mov_b32_e32 v19, v125
	v_mov_b32_e32 v18, v125
	v_mov_b32_e32 v7, v125
	v_mov_b32_e32 v6, v125
	v_mov_b32_e32 v5, v125
	v_mov_b32_e32 v4, v125
	v_mov_b32_e32 v3, v125
	v_mov_b32_e32 v2, v125
	v_mov_b32_e32 v1, v125
	v_mov_b32_e32 v0, v125
	s_cbranch_vccnz .LBB0_1021
	s_add_u32 s44, s44, 0x80
	s_addc_u32 s45, s45, 0
	s_add_u32 s82, s46, 0x100
	v_mov_b32_e32 v0, 0
	s_addc_u32 s83, s47, 0
	s_mov_b32 s46, 0
	v_mov_b32_e32 v1, v0
	v_mov_b32_e32 v2, v0
	v_mov_b32_e32 v3, v0
	v_mov_b32_e32 v4, v0
	v_mov_b32_e32 v5, v0
	v_mov_b32_e32 v6, v0
	v_mov_b32_e32 v7, v0
	v_mov_b32_e32 v18, v0
	v_mov_b32_e32 v19, v0
	v_mov_b32_e32 v20, v0
	v_mov_b32_e32 v21, v0
	v_mov_b32_e32 v22, v0
	v_mov_b32_e32 v23, v0
	v_mov_b32_e32 v24, v0
	v_mov_b32_e32 v25, v0
	v_mov_b32_e32 v34, v0
	v_mov_b32_e32 v35, v0
	v_mov_b32_e32 v36, v0
	v_mov_b32_e32 v37, v0
	v_mov_b32_e32 v38, v0
	v_mov_b32_e32 v39, v0
	v_mov_b32_e32 v40, v0
	v_mov_b32_e32 v41, v0
	v_mov_b32_e32 v50, v0
	v_mov_b32_e32 v51, v0
	v_mov_b32_e32 v52, v0
	v_mov_b32_e32 v53, v0
	v_mov_b32_e32 v54, v0
	v_mov_b32_e32 v55, v0
	v_mov_b32_e32 v56, v0
	v_mov_b32_e32 v57, v0
	v_mov_b32_e32 v8, v0
	v_mov_b32_e32 v9, v0
	v_mov_b32_e32 v10, v0
	v_mov_b32_e32 v11, v0
	v_mov_b32_e32 v14, v0
	v_mov_b32_e32 v15, v0
	v_mov_b32_e32 v16, v0
	v_mov_b32_e32 v17, v0
	v_mov_b32_e32 v26, v0
	v_mov_b32_e32 v27, v0
	v_mov_b32_e32 v28, v0
	v_mov_b32_e32 v29, v0
	v_mov_b32_e32 v30, v0
	v_mov_b32_e32 v31, v0
	v_mov_b32_e32 v32, v0
	v_mov_b32_e32 v33, v0
	v_mov_b32_e32 v42, v0
	v_mov_b32_e32 v43, v0
	v_mov_b32_e32 v44, v0
	v_mov_b32_e32 v45, v0
	v_mov_b32_e32 v46, v0
	v_mov_b32_e32 v47, v0
	v_mov_b32_e32 v48, v0
	v_mov_b32_e32 v49, v0
	v_mov_b32_e32 v58, v0
	v_mov_b32_e32 v59, v0
	v_mov_b32_e32 v60, v0
	v_mov_b32_e32 v61, v0
	v_mov_b32_e32 v62, v0
	v_mov_b32_e32 v63, v0
	v_mov_b32_e32 v64, v0
	v_mov_b32_e32 v65, v0
	v_mov_b32_e32 v66, v0
	v_mov_b32_e32 v67, v0
	v_mov_b32_e32 v68, v0
	v_mov_b32_e32 v69, v0
	v_mov_b32_e32 v70, v0
	v_mov_b32_e32 v71, v0
	v_mov_b32_e32 v72, v0
	v_mov_b32_e32 v73, v0
	v_mov_b32_e32 v82, v0
	v_mov_b32_e32 v83, v0
	v_mov_b32_e32 v84, v0
	v_mov_b32_e32 v85, v0
	v_mov_b32_e32 v86, v0
	v_mov_b32_e32 v87, v0
	v_mov_b32_e32 v88, v0
	v_mov_b32_e32 v89, v0
	v_mov_b32_e32 v98, v0
	v_mov_b32_e32 v99, v0
	v_mov_b32_e32 v100, v0
	v_mov_b32_e32 v101, v0
	v_mov_b32_e32 v102, v0
	v_mov_b32_e32 v103, v0
	v_mov_b32_e32 v104, v0
	v_mov_b32_e32 v105, v0
	v_mov_b32_e32 v114, v0
	v_mov_b32_e32 v115, v0
	v_mov_b32_e32 v116, v0
	v_mov_b32_e32 v117, v0
	v_mov_b32_e32 v118, v0
	v_mov_b32_e32 v119, v0
	v_mov_b32_e32 v120, v0
	v_mov_b32_e32 v121, v0
	v_mov_b32_e32 v74, v0
	v_mov_b32_e32 v75, v0
	v_mov_b32_e32 v76, v0
	v_mov_b32_e32 v77, v0
	v_mov_b32_e32 v78, v0
	v_mov_b32_e32 v79, v0
	v_mov_b32_e32 v80, v0
	v_mov_b32_e32 v81, v0
	v_mov_b32_e32 v90, v0
	v_mov_b32_e32 v91, v0
	v_mov_b32_e32 v92, v0
	v_mov_b32_e32 v93, v0
	v_mov_b32_e32 v94, v0
	v_mov_b32_e32 v95, v0
	v_mov_b32_e32 v96, v0
	v_mov_b32_e32 v97, v0
	v_mov_b32_e32 v106, v0
	v_mov_b32_e32 v107, v0
	v_mov_b32_e32 v108, v0
	v_mov_b32_e32 v109, v0
	v_mov_b32_e32 v110, v0
	v_mov_b32_e32 v111, v0
	v_mov_b32_e32 v112, v0
	v_mov_b32_e32 v113, v0
	v_mov_b32_e32 v126, v0
	v_mov_b32_e32 v127, v0
	v_mov_b32_e32 v128, v0
	v_mov_b32_e32 v129, v0
	v_mov_b32_e32 v122, v0
	v_mov_b32_e32 v123, v0
	v_mov_b32_e32 v124, v0
	v_mov_b32_e32 v125, v0
	s_nop 0
	s_nop 0
	s_nop 0
	s_nop 0
	s_nop 0
	s_nop 0
	s_nop 0
	s_nop 0
	s_nop 0
	s_nop 0
	s_nop 0
	s_nop 0
	s_nop 0
	s_nop 0
	s_nop 0
	s_nop 0
	s_nop 0
	s_nop 0
	s_nop 0
	s_nop 0
; #define PG8_STAGE(bufoff, gbase, voff) do { _Pragma("unroll") for (int _i = 0; _i < 2; ++_i) \
;         __builtin_amdgcn_global_load_lds((const unsigned*)((const char*)(gbase) + (voff)[_i]), (LAS unsigned*)(lds + (bufoff) + ldsw + _i * 8192), 16, 0, 0); } while (0)
; #define PG8_LDA(dst, b, h) do { _Pragma("unroll") for (int m = 0; m < 4; ++m) _Pragma("unroll") for (int k = 0; k < 2; ++k) dst[m][k] = *(const LAS bf16x8*)(lds + PG8_SA(b, h) + aoff + m * 2048 + k * 1024); } while (0)
; #define PG8_LDB(dst, b, h) do { _Pragma("unroll") for (int n = 0; n < 2; ++n) _Pragma("unroll") for (int k = 0; k < 2; ++k) dst[n][k] = *(const LAS bf16x8*)(lds + PG8_SB(b, h) + boff + n * 2048 + k * 1024); } while (0)
; #define PG8_MMA(ai, bj, At, Bt) do { __builtin_amdgcn_s_setprio(1); _Pragma("unroll") for (int m = 0; m < 4; ++m) _Pragma("unroll") for (int n = 0; n < 2; ++n) _Pragma("unroll") for (int k = 0; k < 2; ++k) \
;         acc[ai][bj][m][n] = __builtin_amdgcn_mfma_f32_16x16x32_bf16(Bt[n][k], At[m][k], acc[ai][bj][m][n], 0, 0, 0); __builtin_amdgcn_s_setprio(0); } while (0)
; #define PG8_WAIT_L(n) asm volatile("s_waitcnt lgkmcnt(" #n ")" ::: "memory")
; #define PG8_BAR __builtin_amdgcn_s_barrier()
; #define PG8_SCHED __builtin_amdgcn_sched_barrier(0)
; template <class Epi>
; __device__ __forceinline__ void gemm_phase(LAS unsigned char* lds, const Gemm g, const Epi& E) {
;     ...
;             PG8_LDB(B0, 0, 0); PG8_SCHED; PG8_LDA(At, 0, 0); PG8_STAGE(PG8_SA(1, 1), a1 + hstep, voffA);
;             PG8_WAIT_L(8); PG8_BAR; PG8_WAIT_L(0); PG8_MMA(0, 0, At, B0); PG8_BAR; PG8_SCHED;
;             PG8_LDB(B1, 0, 1); PG8_STAGE(PG8_SB(0, 0), b2, voffB);
;             PG8_BAR; PG8_WAIT_L(0); PG8_MMA(0, 1, At, B1); PG8_BAR;
;             PG8_LDA(At, 0, 1); PG8_STAGE(PG8_SA(0, 0), a2, voffA);
;             PG8_BAR; PG8_WAIT_L(0); PG8_MMA(1, 0, At, B0); PG8_BAR; PG8_SCHED;
;             PG8_STAGE(PG8_SB(0, 1), b2 + hstep, voffB);
.LBB0_1034:
	s_add_i32 s84, s46, 2
	s_add_u32 s48, s44, 0x80
	s_addc_u32 s47, s45, 0
	s_add_i32 s85, 0, 0x10000
	v_add_u32_e32 v154, s85, v157
	ds_read_b128 v[130:133], v154
	ds_read_b128 v[134:137], v154 offset:1024
	ds_read_b128 v[150:153], v154 offset:2048
	ds_read_b128 v[160:163], v154 offset:3072
	s_cmp_eq_u32 s58, s46
	s_cselect_b32 s46, s0, s48
	s_cselect_b32 s47, s1, s47
	s_cselect_b32 s49, s39, s83
	s_cselect_b32 s48, s38, s82
	v_lshl_add_u64 v[154:155], s[44:45], 0, v[146:147]
	s_add_i32 m0, s50, 0xc000
	ds_read_b128 v[164:167], v158
	ds_read_b128 v[168:171], v158 offset:1024
	ds_read_b128 v[172:175], v158 offset:2048
	ds_read_b128 v[186:189], v158 offset:3072
	ds_read_b128 v[194:197], v158 offset:4096
	ds_read_b128 v[198:201], v158 offset:5120
	ds_read_b128 v[202:205], v158 offset:6144
	ds_read_b128 v[206:209], v158 offset:7168
	global_load_lds_dwordx4 v[154:155], off
	v_lshl_add_u64 v[154:155], s[44:45], 0, v[148:149]
	s_add_i32 m0, s50, 0xe000
	s_nop 0
	global_load_lds_dwordx4 v[154:155], off
	s_waitcnt lgkmcnt(8)
	s_barrier
	s_waitcnt lgkmcnt(0)
	s_setprio 1
	s_waitcnt lgkmcnt(0)
	v_mfma_f32_16x16x32_bf16 v[122:125], v[130:133], v[164:167], v[122:125]
	v_mfma_f32_16x16x32_bf16 v[126:129], v[150:153], v[164:167], v[126:129]
	v_mfma_f32_16x16x32_bf16 v[110:113], v[130:133], v[172:175], v[110:113]
	v_mfma_f32_16x16x32_bf16 v[106:109], v[150:153], v[172:175], v[106:109]
	v_mfma_f32_16x16x32_bf16 v[94:97], v[130:133], v[194:197], v[94:97]
	v_mfma_f32_16x16x32_bf16 v[90:93], v[150:153], v[194:197], v[90:93]
	v_mfma_f32_16x16x32_bf16 v[78:81], v[130:133], v[202:205], v[78:81]
	v_mfma_f32_16x16x32_bf16 v[74:77], v[150:153], v[202:205], v[74:77]
	v_mfma_f32_16x16x32_bf16 v[122:125], v[134:137], v[168:171], v[122:125]
	v_mfma_f32_16x16x32_bf16 v[126:129], v[160:163], v[168:171], v[126:129]
	v_mfma_f32_16x16x32_bf16 v[110:113], v[134:137], v[186:189], v[110:113]
	v_mfma_f32_16x16x32_bf16 v[106:109], v[160:163], v[186:189], v[106:109]
	v_mfma_f32_16x16x32_bf16 v[94:97], v[134:137], v[198:201], v[94:97]
	v_mfma_f32_16x16x32_bf16 v[90:93], v[160:163], v[198:201], v[90:93]
	v_mfma_f32_16x16x32_bf16 v[78:81], v[134:137], v[206:209], v[78:81]
	v_mfma_f32_16x16x32_bf16 v[74:77], v[160:163], v[206:209], v[74:77]
	s_setprio 0
	s_barrier
	s_add_i32 s86, 0, 0x14000
	v_add_u32_e32 v154, s86, v157
	s_add_i32 s85, s85, s25
	ds_read_b128 v[210:213], v154
	ds_read_b128 v[220:223], v154 offset:1024
	ds_read_b128 v[224:227], v154 offset:2048
	ds_read_b128 v[228:231], v154 offset:3072
	v_lshl_add_u64 v[154:155], s[48:49], 0, v[140:141]
	s_mov_b32 m0, s85
	v_lshl_add_u64 v[176:177], s[48:49], 0, v[144:145]
	global_load_lds_dwordx4 v[154:155], off
	s_add_i32 m0, s85, 0x2000
	s_nop 0
	global_load_lds_dwordx4 v[176:177], off
	s_barrier
	s_waitcnt lgkmcnt(0)
	s_setprio 1
	s_waitcnt lgkmcnt(0)
	v_mfma_f32_16x16x32_bf16 v[118:121], v[210:213], v[164:167], v[118:121]
	v_mfma_f32_16x16x32_bf16 v[114:117], v[224:227], v[164:167], v[114:117]
	v_mfma_f32_16x16x32_bf16 v[102:105], v[210:213], v[172:175], v[102:105]
	v_mfma_f32_16x16x32_bf16 v[98:101], v[224:227], v[172:175], v[98:101]
	v_mfma_f32_16x16x32_bf16 v[86:89], v[210:213], v[194:197], v[86:89]
	v_mfma_f32_16x16x32_bf16 v[82:85], v[224:227], v[194:197], v[82:85]
	v_mfma_f32_16x16x32_bf16 v[70:73], v[210:213], v[202:205], v[70:73]
	v_mfma_f32_16x16x32_bf16 v[66:69], v[224:227], v[202:205], v[66:69]
	v_mfma_f32_16x16x32_bf16 v[118:121], v[220:223], v[168:171], v[118:121]
	v_mfma_f32_16x16x32_bf16 v[114:117], v[228:231], v[168:171], v[114:117]
	v_mfma_f32_16x16x32_bf16 v[102:105], v[220:223], v[186:189], v[102:105]
	v_mfma_f32_16x16x32_bf16 v[98:101], v[228:231], v[186:189], v[98:101]
	v_mfma_f32_16x16x32_bf16 v[86:89], v[220:223], v[198:201], v[86:89]
	v_mfma_f32_16x16x32_bf16 v[82:85], v[228:231], v[198:201], v[82:85]
	v_mfma_f32_16x16x32_bf16 v[70:73], v[220:223], v[206:209], v[70:73]
	v_mfma_f32_16x16x32_bf16 v[66:69], v[228:231], v[206:209], v[66:69]
	s_setprio 0
	s_mov_b32 m0, s50
	v_lshl_add_u64 v[232:233], s[46:47], 0, v[138:139]
	s_barrier
	ds_read_b128 v[164:167], v158 offset:16384
	ds_read_b128 v[168:171], v158 offset:17408
	ds_read_b128 v[172:175], v158 offset:18432
	ds_read_b128 v[186:189], v158 offset:19456
	ds_read_b128 v[194:197], v158 offset:20480
	ds_read_b128 v[198:201], v158 offset:21504
	ds_read_b128 v[202:205], v158 offset:22528
	ds_read_b128 v[206:209], v158 offset:23552
	global_load_lds_dwordx4 v[232:233], off
	v_lshl_add_u64 v[234:235], s[46:47], 0, v[142:143]
	s_mov_b32 m0, s51
	s_nop 0
	global_load_lds_dwordx4 v[234:235], off
	s_barrier
	s_waitcnt lgkmcnt(0)
	s_setprio 1
	s_waitcnt lgkmcnt(0)
	v_mfma_f32_16x16x32_bf16 v[62:65], v[130:133], v[164:167], v[62:65]
	v_mfma_f32_16x16x32_bf16 v[58:61], v[150:153], v[164:167], v[58:61]
	v_mfma_f32_16x16x32_bf16 v[46:49], v[130:133], v[172:175], v[46:49]
	v_mfma_f32_16x16x32_bf16 v[42:45], v[150:153], v[172:175], v[42:45]
	v_mfma_f32_16x16x32_bf16 v[30:33], v[130:133], v[194:197], v[30:33]
	v_mfma_f32_16x16x32_bf16 v[26:29], v[150:153], v[194:197], v[26:29]
	v_mfma_f32_16x16x32_bf16 v[14:17], v[130:133], v[202:205], v[14:17]
	v_mfma_f32_16x16x32_bf16 v[8:11], v[150:153], v[202:205], v[8:11]
	v_mfma_f32_16x16x32_bf16 v[62:65], v[134:137], v[168:171], v[62:65]
	v_mfma_f32_16x16x32_bf16 v[58:61], v[160:163], v[168:171], v[58:61]
	v_mfma_f32_16x16x32_bf16 v[46:49], v[134:137], v[186:189], v[46:49]
	v_mfma_f32_16x16x32_bf16 v[42:45], v[160:163], v[186:189], v[42:45]
	v_mfma_f32_16x16x32_bf16 v[30:33], v[134:137], v[198:201], v[30:33]
	v_mfma_f32_16x16x32_bf16 v[26:29], v[160:163], v[198:201], v[26:29]
	v_mfma_f32_16x16x32_bf16 v[14:17], v[134:137], v[206:209], v[14:17]
	v_mfma_f32_16x16x32_bf16 v[8:11], v[160:163], v[206:209], v[8:11]
	s_setprio 0
	s_barrier
; #define PG8_STAGE(bufoff, gbase, voff) do { _Pragma("unroll") for (int _i = 0; _i < 2; ++_i) \
;         __builtin_amdgcn_global_load_lds((const unsigned*)((const char*)(gbase) + (voff)[_i]), (LAS unsigned*)(lds + (bufoff) + ldsw + _i * 8192), 16, 0, 0); } while (0)
; #define PG8_LDA(dst, b, h) do { _Pragma("unroll") for (int m = 0; m < 4; ++m) _Pragma("unroll") for (int k = 0; k < 2; ++k) dst[m][k] = *(const LAS bf16x8*)(lds + PG8_SA(b, h) + aoff + m * 2048 + k * 1024); } while (0)
; #define PG8_LDB(dst, b, h) do { _Pragma("unroll") for (int n = 0; n < 2; ++n) _Pragma("unroll") for (int k = 0; k < 2; ++k) dst[n][k] = *(const LAS bf16x8*)(lds + PG8_SB(b, h) + boff + n * 2048 + k * 1024); } while (0)
; #define PG8_MMA(ai, bj, At, Bt) do { __builtin_amdgcn_s_setprio(1); _Pragma("unroll") for (int m = 0; m < 4; ++m) _Pragma("unroll") for (int n = 0; n < 2; ++n) _Pragma("unroll") for (int k = 0; k < 2; ++k) \
;         acc[ai][bj][m][n] = __builtin_amdgcn_mfma_f32_16x16x32_bf16(Bt[n][k], At[m][k], acc[ai][bj][m][n], 0, 0, 0); __builtin_amdgcn_s_setprio(0); } while (0)
; #define PG8_WAIT_V(n) asm volatile("s_waitcnt vmcnt(" #n ")" ::: "memory")
; #define PG8_WAIT_L(n) asm volatile("s_waitcnt lgkmcnt(" #n ")" ::: "memory")
; #define PG8_BAR __builtin_amdgcn_s_barrier()
; #define PG8_SCHED __builtin_amdgcn_sched_barrier(0)
; template <class Epi>
; __device__ __forceinline__ void gemm_phase(LAS unsigned char* lds, const Gemm g, const Epi& E) {
;     ...
;             PG8_STAGE(PG8_SB(0, 1), b2 + hstep, voffB);
;             PG8_WAIT_V(6); PG8_BAR; PG8_MMA(1, 1, At, B1); PG8_BAR;
;             PG8_LDB(B0, 1, 0); PG8_SCHED; PG8_LDA(At, 1, 0); PG8_STAGE(PG8_SA(0, 1), a2 + hstep, voffA);
;             PG8_WAIT_L(8); PG8_BAR; PG8_WAIT_L(0); PG8_MMA(0, 0, At, B0); PG8_BAR; PG8_SCHED;
;             PG8_LDB(B1, 1, 1); PG8_STAGE(PG8_SB(1, 0), b3, voffB);
;             PG8_BAR; PG8_WAIT_L(0); PG8_MMA(0, 1, At, B1); PG8_BAR;
;             PG8_LDA(At, 1, 1); PG8_STAGE(PG8_SA(1, 0), a3, voffA);
;             PG8_BAR; PG8_WAIT_L(0); PG8_MMA(1, 0, At, B0); PG8_BAR; PG8_SCHED;
	s_add_u32 s48, s48, s26
	s_addc_u32 s49, s49, s27
	s_add_i32 s85, s86, s25
	v_lshl_add_u64 v[236:237], s[48:49], 0, v[140:141]
	s_mov_b32 m0, s85
	v_lshl_add_u64 v[238:239], s[48:49], 0, v[144:145]
	global_load_lds_dwordx4 v[236:237], off
	s_add_i32 m0, s85, 0x2000
	s_nop 0
	global_load_lds_dwordx4 v[238:239], off
	s_waitcnt vmcnt(6)
	s_barrier
	s_setprio 1
	v_mfma_f32_16x16x32_bf16 v[54:57], v[210:213], v[164:167], v[54:57]
	v_mfma_f32_16x16x32_bf16 v[50:53], v[224:227], v[164:167], v[50:53]
	v_mfma_f32_16x16x32_bf16 v[38:41], v[210:213], v[172:175], v[38:41]
	v_mfma_f32_16x16x32_bf16 v[34:37], v[224:227], v[172:175], v[34:37]
	v_mfma_f32_16x16x32_bf16 v[22:25], v[210:213], v[194:197], v[22:25]
	v_mfma_f32_16x16x32_bf16 v[18:21], v[224:227], v[194:197], v[18:21]
	v_mfma_f32_16x16x32_bf16 v[4:7], v[210:213], v[202:205], v[4:7]
	v_mfma_f32_16x16x32_bf16 v[0:3], v[224:227], v[202:205], v[0:3]
	v_mfma_f32_16x16x32_bf16 v[54:57], v[220:223], v[168:171], v[54:57]
	v_mfma_f32_16x16x32_bf16 v[50:53], v[228:231], v[168:171], v[50:53]
	v_mfma_f32_16x16x32_bf16 v[38:41], v[220:223], v[186:189], v[38:41]
	v_mfma_f32_16x16x32_bf16 v[34:37], v[228:231], v[186:189], v[34:37]
	v_mfma_f32_16x16x32_bf16 v[22:25], v[220:223], v[198:201], v[22:25]
	v_mfma_f32_16x16x32_bf16 v[18:21], v[228:231], v[198:201], v[18:21]
	v_mfma_f32_16x16x32_bf16 v[4:7], v[220:223], v[206:209], v[4:7]
	v_mfma_f32_16x16x32_bf16 v[0:3], v[228:231], v[206:209], v[0:3]
	s_setprio 0
	s_add_i32 s48, 0, 0x18000
	v_add_u32_e32 v159, s48, v157
	s_barrier
	ds_read_b128 v[130:133], v159
	ds_read_b128 v[134:137], v159 offset:1024
	ds_read_b128 v[150:153], v159 offset:2048
	ds_read_b128 v[160:163], v159 offset:3072
	s_add_u32 s46, s46, s26
	s_addc_u32 s47, s47, s27
	s_mov_b32 m0, s52
	v_lshl_add_u64 v[210:211], s[46:47], 0, v[138:139]
	ds_read_b128 v[164:167], v158 offset:32768
	ds_read_b128 v[168:171], v158 offset:33792
	ds_read_b128 v[172:175], v158 offset:34816
	ds_read_b128 v[186:189], v158 offset:35840
	ds_read_b128 v[194:197], v158 offset:36864
	ds_read_b128 v[198:201], v158 offset:37888
	ds_read_b128 v[202:205], v158 offset:38912
	ds_read_b128 v[206:209], v158 offset:39936
	global_load_lds_dwordx4 v[210:211], off
	v_lshl_add_u64 v[210:211], s[46:47], 0, v[142:143]
	s_mov_b32 m0, s53
	s_nop 0
	global_load_lds_dwordx4 v[210:211], off
	s_waitcnt lgkmcnt(8)
	s_barrier
	s_waitcnt lgkmcnt(0)
	s_setprio 1
	s_waitcnt lgkmcnt(0)
	v_mfma_f32_16x16x32_bf16 v[122:125], v[130:133], v[164:167], v[122:125]
	v_mfma_f32_16x16x32_bf16 v[126:129], v[150:153], v[164:167], v[126:129]
	v_mfma_f32_16x16x32_bf16 v[110:113], v[130:133], v[172:175], v[110:113]
	v_mfma_f32_16x16x32_bf16 v[106:109], v[150:153], v[172:175], v[106:109]
	v_mfma_f32_16x16x32_bf16 v[94:97], v[130:133], v[194:197], v[94:97]
	v_mfma_f32_16x16x32_bf16 v[90:93], v[150:153], v[194:197], v[90:93]
	v_mfma_f32_16x16x32_bf16 v[78:81], v[130:133], v[202:205], v[78:81]
	v_mfma_f32_16x16x32_bf16 v[74:77], v[150:153], v[202:205], v[74:77]
	v_mfma_f32_16x16x32_bf16 v[122:125], v[134:137], v[168:171], v[122:125]
	v_mfma_f32_16x16x32_bf16 v[126:129], v[160:163], v[168:171], v[126:129]
	v_mfma_f32_16x16x32_bf16 v[110:113], v[134:137], v[186:189], v[110:113]
	v_mfma_f32_16x16x32_bf16 v[106:109], v[160:163], v[186:189], v[106:109]
	v_mfma_f32_16x16x32_bf16 v[94:97], v[134:137], v[198:201], v[94:97]
	v_mfma_f32_16x16x32_bf16 v[90:93], v[160:163], v[198:201], v[90:93]
	v_mfma_f32_16x16x32_bf16 v[78:81], v[134:137], v[206:209], v[78:81]
	v_mfma_f32_16x16x32_bf16 v[74:77], v[160:163], v[206:209], v[74:77]
	s_setprio 0
	s_barrier
	s_add_i32 s46, 0, 0x1c000
	s_add_i32 s47, s48, s25
	v_add_u32_e32 v159, s46, v157
	v_lshl_add_u64 v[154:155], v[154:155], 0, s[20:21]
	s_mov_b32 m0, s47
	ds_read_b128 v[210:213], v159
	ds_read_b128 v[220:223], v159 offset:1024
	ds_read_b128 v[224:227], v159 offset:2048
	ds_read_b128 v[228:231], v159 offset:3072
	global_load_lds_dwordx4 v[154:155], off
	v_lshl_add_u64 v[154:155], v[176:177], 0, s[20:21]
	s_add_i32 m0, s47, 0x2000
	s_nop 0
	global_load_lds_dwordx4 v[154:155], off
	s_barrier
; #define PG8_STAGE(bufoff, gbase, voff) do { _Pragma("unroll") for (int _i = 0; _i < 2; ++_i) \
;         __builtin_amdgcn_global_load_lds((const unsigned*)((const char*)(gbase) + (voff)[_i]), (LAS unsigned*)(lds + (bufoff) + ldsw + _i * 8192), 16, 0, 0); } while (0)
; #define PG8_MMA(ai, bj, At, Bt) do { __builtin_amdgcn_s_setprio(1); _Pragma("unroll") for (int m = 0; m < 4; ++m) _Pragma("unroll") for (int n = 0; n < 2; ++n) _Pragma("unroll") for (int k = 0; k < 2; ++k) \
;         acc[ai][bj][m][n] = __builtin_amdgcn_mfma_f32_16x16x32_bf16(Bt[n][k], At[m][k], acc[ai][bj][m][n], 0, 0, 0); __builtin_amdgcn_s_setprio(0); } while (0)
; #define PG8_WAIT_V(n) asm volatile("s_waitcnt vmcnt(" #n ")" ::: "memory")
; #define PG8_WAIT_L(n) asm volatile("s_waitcnt lgkmcnt(" #n ")" ::: "memory")
; #define PG8_BAR __builtin_amdgcn_s_barrier()
; #define PG8_SCHED __builtin_amdgcn_sched_barrier(0)
; template <class Epi>
; __device__ __forceinline__ void gemm_phase(LAS unsigned char* lds, const Gemm g, const Epi& E) {
;     ...
;             PG8_BAR; PG8_WAIT_L(0); PG8_MMA(1, 0, At, B0); PG8_BAR; PG8_SCHED;
;             PG8_STAGE(PG8_SB(1, 1), b3 + hstep, voffB);
;             PG8_WAIT_V(6); PG8_BAR; PG8_MMA(1, 1, At, B1); PG8_BAR;
;         }
	s_waitcnt lgkmcnt(0)
	s_setprio 1
	s_waitcnt lgkmcnt(0)
	v_mfma_f32_16x16x32_bf16 v[118:121], v[210:213], v[164:167], v[118:121]
	v_mfma_f32_16x16x32_bf16 v[114:117], v[224:227], v[164:167], v[114:117]
	v_mfma_f32_16x16x32_bf16 v[102:105], v[210:213], v[172:175], v[102:105]
	v_mfma_f32_16x16x32_bf16 v[98:101], v[224:227], v[172:175], v[98:101]
	v_mfma_f32_16x16x32_bf16 v[86:89], v[210:213], v[194:197], v[86:89]
	v_mfma_f32_16x16x32_bf16 v[82:85], v[224:227], v[194:197], v[82:85]
	v_mfma_f32_16x16x32_bf16 v[70:73], v[210:213], v[202:205], v[70:73]
	v_mfma_f32_16x16x32_bf16 v[66:69], v[224:227], v[202:205], v[66:69]
	v_mfma_f32_16x16x32_bf16 v[118:121], v[220:223], v[168:171], v[118:121]
	v_mfma_f32_16x16x32_bf16 v[114:117], v[228:231], v[168:171], v[114:117]
	v_mfma_f32_16x16x32_bf16 v[102:105], v[220:223], v[186:189], v[102:105]
	v_mfma_f32_16x16x32_bf16 v[98:101], v[228:231], v[186:189], v[98:101]
	v_mfma_f32_16x16x32_bf16 v[86:89], v[220:223], v[198:201], v[86:89]
	v_mfma_f32_16x16x32_bf16 v[82:85], v[228:231], v[198:201], v[82:85]
	v_mfma_f32_16x16x32_bf16 v[70:73], v[220:223], v[206:209], v[70:73]
	v_mfma_f32_16x16x32_bf16 v[66:69], v[228:231], v[206:209], v[66:69]
	s_setprio 0
	s_mov_b32 m0, s54
	v_lshl_add_u64 v[154:155], v[232:233], 0, s[20:21]
	s_barrier
	ds_read_b128 v[164:167], v158 offset:49152
	ds_read_b128 v[168:171], v158 offset:50176
	ds_read_b128 v[172:175], v158 offset:51200
	ds_read_b128 v[186:189], v158 offset:52224
	ds_read_b128 v[194:197], v158 offset:53248
	ds_read_b128 v[198:201], v158 offset:54272
	ds_read_b128 v[202:205], v158 offset:55296
	ds_read_b128 v[206:209], v158 offset:56320
	global_load_lds_dwordx4 v[154:155], off
	v_lshl_add_u64 v[154:155], v[234:235], 0, s[20:21]
	s_mov_b32 m0, s55
	s_nop 0
	global_load_lds_dwordx4 v[154:155], off
	s_barrier
	s_waitcnt lgkmcnt(0)
	s_setprio 1
	s_waitcnt lgkmcnt(0)
	v_mfma_f32_16x16x32_bf16 v[62:65], v[130:133], v[164:167], v[62:65]
	v_mfma_f32_16x16x32_bf16 v[58:61], v[150:153], v[164:167], v[58:61]
	v_mfma_f32_16x16x32_bf16 v[46:49], v[130:133], v[172:175], v[46:49]
	v_mfma_f32_16x16x32_bf16 v[42:45], v[150:153], v[172:175], v[42:45]
	v_mfma_f32_16x16x32_bf16 v[30:33], v[130:133], v[194:197], v[30:33]
	v_mfma_f32_16x16x32_bf16 v[26:29], v[150:153], v[194:197], v[26:29]
	v_mfma_f32_16x16x32_bf16 v[14:17], v[130:133], v[202:205], v[14:17]
	v_mfma_f32_16x16x32_bf16 v[8:11], v[150:153], v[202:205], v[8:11]
	v_mfma_f32_16x16x32_bf16 v[62:65], v[134:137], v[168:171], v[62:65]
	v_mfma_f32_16x16x32_bf16 v[58:61], v[160:163], v[168:171], v[58:61]
	v_mfma_f32_16x16x32_bf16 v[46:49], v[134:137], v[186:189], v[46:49]
	v_mfma_f32_16x16x32_bf16 v[42:45], v[160:163], v[186:189], v[42:45]
	v_mfma_f32_16x16x32_bf16 v[30:33], v[134:137], v[198:201], v[30:33]
	v_mfma_f32_16x16x32_bf16 v[26:29], v[160:163], v[198:201], v[26:29]
	v_mfma_f32_16x16x32_bf16 v[14:17], v[134:137], v[206:209], v[14:17]
	v_mfma_f32_16x16x32_bf16 v[8:11], v[160:163], v[206:209], v[8:11]
	s_setprio 0
	s_barrier
	s_add_i32 s46, s46, s25
	v_lshl_add_u64 v[130:131], v[236:237], 0, s[20:21]
	s_mov_b32 m0, s46
	s_nop 0
	global_load_lds_dwordx4 v[130:131], off
	v_lshl_add_u64 v[130:131], v[238:239], 0, s[20:21]
	s_add_i32 m0, s46, 0x2000
	s_nop 0
	global_load_lds_dwordx4 v[130:131], off
	s_waitcnt vmcnt(6)
	s_barrier
	s_setprio 1
	v_mfma_f32_16x16x32_bf16 v[54:57], v[210:213], v[164:167], v[54:57]
	v_mfma_f32_16x16x32_bf16 v[50:53], v[224:227], v[164:167], v[50:53]
	v_mfma_f32_16x16x32_bf16 v[38:41], v[210:213], v[172:175], v[38:41]
	v_mfma_f32_16x16x32_bf16 v[34:37], v[224:227], v[172:175], v[34:37]
	v_mfma_f32_16x16x32_bf16 v[22:25], v[210:213], v[194:197], v[22:25]
	v_mfma_f32_16x16x32_bf16 v[18:21], v[224:227], v[194:197], v[18:21]
	v_mfma_f32_16x16x32_bf16 v[4:7], v[210:213], v[202:205], v[4:7]
	v_mfma_f32_16x16x32_bf16 v[0:3], v[224:227], v[202:205], v[0:3]
	v_mfma_f32_16x16x32_bf16 v[54:57], v[220:223], v[168:171], v[54:57]
	v_mfma_f32_16x16x32_bf16 v[50:53], v[228:231], v[168:171], v[50:53]
	v_mfma_f32_16x16x32_bf16 v[38:41], v[220:223], v[186:189], v[38:41]
	v_mfma_f32_16x16x32_bf16 v[34:37], v[228:231], v[186:189], v[34:37]
	v_mfma_f32_16x16x32_bf16 v[22:25], v[220:223], v[198:201], v[22:25]
	v_mfma_f32_16x16x32_bf16 v[18:21], v[228:231], v[198:201], v[18:21]
	v_mfma_f32_16x16x32_bf16 v[4:7], v[220:223], v[206:209], v[4:7]
	v_mfma_f32_16x16x32_bf16 v[0:3], v[228:231], v[206:209], v[0:3]
	s_setprio 0
	s_add_u32 s44, s44, 0x100
	s_addc_u32 s45, s45, 0
	s_add_u32 s82, s82, 0x100
	s_addc_u32 s83, s83, 0
	s_cmp_ge_i32 s84, s2
	s_mov_b32 s46, s84
	s_barrier
	s_cbranch_scc0 .LBB0_1034
	s_nop 0
	s_nop 0
	s_nop 0
	s_nop 0
	s_nop 0
	s_nop 0
	s_nop 0
	s_nop 0
	s_nop 0
	s_nop 0
	s_nop 0
	s_nop 0
	s_nop 0
	s_nop 0
	s_nop 0
	s_nop 0
	s_nop 0
	s_nop 0
	s_nop 0
	s_nop 0
	s_nop 0
	s_nop 0
	s_nop 0
	s_nop 0
	s_nop 0
	s_nop 0
	s_nop 0
	s_nop 0
	s_nop 0
	s_nop 0
	s_nop 0
	s_nop 0
	s_nop 0
	s_nop 0
	s_nop 0
	s_nop 0
	s_nop 0
	s_nop 0
	s_nop 0
	s_nop 0
	s_nop 0
	s_nop 0
	s_nop 0
	s_nop 0
	v_readlane_b32 s48, v254, 63
	v_readlane_b32 s49, v243, 0
	s_branch .LBB0_1021

; template <class Epi>
; __device__ __forceinline__ void gemm_phase(LAS unsigned char* lds, const Gemm g, const Epi& E) {
;     ...
;         const bool has_next = S.next(ui + 1, nxt);
;         const char* nA = has_next ? (const char*)g.A + (size_t)nxt.pm * tstep : cA; const char* nB = has_next ? (const char*)g.Bt + (size_t)nxt.pn * tstep : cB;
; #pragma unroll 1
;         for (int t = 0; t < nt; t += 2) {
;     ...
;         if (!has_next) break;
; #pragma unroll
;         for (int a = 0; a < 2; ++a)
; #pragma unroll
;             for (int b = 0; b < 2; ++b)
; #pragma unroll
;                 for (int m = 0; m < 4; ++m)
; #pragma unroll
;                     for (int n = 0; n < 2; ++n) acc[a][b][m][n] = (f32x4){0.f, 0.f, 0.f, 0.f};
;         cur = nxt; cA = nA; cB = nB; ++ui;
.LBB0_1110:
	v_mov_b32_e32 v125, 0
	s_andn2_b64 vcc, exec, s[42:43]
	v_mov_b32_e32 v124, v125
	v_mov_b32_e32 v123, v125
	v_mov_b32_e32 v122, v125
	v_mov_b32_e32 v129, v125
	v_mov_b32_e32 v128, v125
	v_mov_b32_e32 v127, v125
	v_mov_b32_e32 v126, v125
	v_mov_b32_e32 v113, v125
	v_mov_b32_e32 v112, v125
	v_mov_b32_e32 v111, v125
	v_mov_b32_e32 v110, v125
	v_mov_b32_e32 v109, v125
	v_mov_b32_e32 v108, v125
	v_mov_b32_e32 v107, v125
	v_mov_b32_e32 v106, v125
	v_mov_b32_e32 v97, v125
	v_mov_b32_e32 v96, v125
	v_mov_b32_e32 v95, v125
	v_mov_b32_e32 v94, v125
	v_mov_b32_e32 v93, v125
	v_mov_b32_e32 v92, v125
	v_mov_b32_e32 v91, v125
	v_mov_b32_e32 v90, v125
	v_mov_b32_e32 v81, v125
	v_mov_b32_e32 v80, v125
	v_mov_b32_e32 v79, v125
	v_mov_b32_e32 v78, v125
	v_mov_b32_e32 v77, v125
	v_mov_b32_e32 v76, v125
	v_mov_b32_e32 v75, v125
	v_mov_b32_e32 v74, v125
	v_mov_b32_e32 v121, v125
	v_mov_b32_e32 v120, v125
	v_mov_b32_e32 v119, v125
	v_mov_b32_e32 v118, v125
	v_mov_b32_e32 v117, v125
	v_mov_b32_e32 v116, v125
	v_mov_b32_e32 v115, v125
	v_mov_b32_e32 v114, v125
	v_mov_b32_e32 v105, v125
	v_mov_b32_e32 v104, v125
	v_mov_b32_e32 v103, v125
	v_mov_b32_e32 v102, v125
	v_mov_b32_e32 v101, v125
	v_mov_b32_e32 v100, v125
	v_mov_b32_e32 v99, v125
	v_mov_b32_e32 v98, v125
	v_mov_b32_e32 v89, v125
	v_mov_b32_e32 v88, v125
	v_mov_b32_e32 v87, v125
	v_mov_b32_e32 v86, v125
	v_mov_b32_e32 v85, v125
	v_mov_b32_e32 v84, v125
	v_mov_b32_e32 v83, v125
	v_mov_b32_e32 v82, v125
	v_mov_b32_e32 v73, v125
	v_mov_b32_e32 v72, v125
	v_mov_b32_e32 v71, v125
	v_mov_b32_e32 v70, v125
	v_mov_b32_e32 v69, v125
	v_mov_b32_e32 v68, v125
	v_mov_b32_e32 v67, v125
	v_mov_b32_e32 v66, v125
	v_mov_b32_e32 v65, v125
	v_mov_b32_e32 v64, v125
	v_mov_b32_e32 v63, v125
	v_mov_b32_e32 v62, v125
	v_mov_b32_e32 v61, v125
	v_mov_b32_e32 v60, v125
	v_mov_b32_e32 v59, v125
	v_mov_b32_e32 v58, v125
	v_mov_b32_e32 v49, v125
	v_mov_b32_e32 v48, v125
	v_mov_b32_e32 v47, v125
	v_mov_b32_e32 v46, v125
	v_mov_b32_e32 v45, v125
	v_mov_b32_e32 v44, v125
	v_mov_b32_e32 v43, v125
	v_mov_b32_e32 v42, v125
	v_mov_b32_e32 v33, v125
	v_mov_b32_e32 v32, v125
	v_mov_b32_e32 v31, v125
	v_mov_b32_e32 v30, v125
	v_mov_b32_e32 v29, v125
	v_mov_b32_e32 v28, v125
	v_mov_b32_e32 v27, v125
	v_mov_b32_e32 v26, v125
	v_mov_b32_e32 v17, v125
	v_mov_b32_e32 v16, v125
	v_mov_b32_e32 v15, v125
	v_mov_b32_e32 v14, v125
	v_mov_b32_e32 v11, v125
	v_mov_b32_e32 v10, v125
	v_mov_b32_e32 v9, v125
	v_mov_b32_e32 v8, v125
	v_mov_b32_e32 v57, v125
	v_mov_b32_e32 v56, v125
	v_mov_b32_e32 v55, v125
	v_mov_b32_e32 v54, v125
	v_mov_b32_e32 v53, v125
	v_mov_b32_e32 v52, v125
	v_mov_b32_e32 v51, v125
	v_mov_b32_e32 v50, v125
	v_mov_b32_e32 v41, v125
	v_mov_b32_e32 v40, v125
	v_mov_b32_e32 v39, v125
	v_mov_b32_e32 v38, v125
	v_mov_b32_e32 v37, v125
	v_mov_b32_e32 v36, v125
	v_mov_b32_e32 v35, v125
	v_mov_b32_e32 v34, v125
	v_mov_b32_e32 v25, v125
	v_mov_b32_e32 v24, v125
	v_mov_b32_e32 v23, v125
	v_mov_b32_e32 v22, v125
	v_mov_b32_e32 v21, v125
	v_mov_b32_e32 v20, v125
	v_mov_b32_e32 v19, v125
	v_mov_b32_e32 v18, v125
	v_mov_b32_e32 v7, v125
	v_mov_b32_e32 v6, v125
	v_mov_b32_e32 v5, v125
	v_mov_b32_e32 v4, v125
	v_mov_b32_e32 v3, v125
	v_mov_b32_e32 v2, v125
	v_mov_b32_e32 v1, v125
	v_mov_b32_e32 v0, v125
	s_cbranch_vccnz .LBB0_1099
	s_add_u32 s44, s44, 0x80
	s_addc_u32 s45, s45, 0
	s_add_u32 s82, s46, 0x100
	v_mov_b32_e32 v0, 0
	s_addc_u32 s83, s47, 0
	s_mov_b32 s46, 0
	v_mov_b32_e32 v1, v0
	v_mov_b32_e32 v2, v0
	v_mov_b32_e32 v3, v0
	v_mov_b32_e32 v4, v0
	v_mov_b32_e32 v5, v0
	v_mov_b32_e32 v6, v0
	v_mov_b32_e32 v7, v0
	v_mov_b32_e32 v18, v0
	v_mov_b32_e32 v19, v0
	v_mov_b32_e32 v20, v0
	v_mov_b32_e32 v21, v0
	v_mov_b32_e32 v22, v0
	v_mov_b32_e32 v23, v0
	v_mov_b32_e32 v24, v0
	v_mov_b32_e32 v25, v0
	v_mov_b32_e32 v34, v0
	v_mov_b32_e32 v35, v0
	v_mov_b32_e32 v36, v0
	v_mov_b32_e32 v37, v0
	v_mov_b32_e32 v38, v0
	v_mov_b32_e32 v39, v0
	v_mov_b32_e32 v40, v0
	v_mov_b32_e32 v41, v0
	v_mov_b32_e32 v50, v0
	v_mov_b32_e32 v51, v0
	v_mov_b32_e32 v52, v0
	v_mov_b32_e32 v53, v0
	v_mov_b32_e32 v54, v0
	v_mov_b32_e32 v55, v0
	v_mov_b32_e32 v56, v0
	v_mov_b32_e32 v57, v0
	v_mov_b32_e32 v8, v0
	v_mov_b32_e32 v9, v0
	v_mov_b32_e32 v10, v0
	v_mov_b32_e32 v11, v0
	v_mov_b32_e32 v14, v0
	v_mov_b32_e32 v15, v0
	v_mov_b32_e32 v16, v0
	v_mov_b32_e32 v17, v0
	v_mov_b32_e32 v26, v0
	v_mov_b32_e32 v27, v0
	v_mov_b32_e32 v28, v0
	v_mov_b32_e32 v29, v0
	v_mov_b32_e32 v30, v0
	v_mov_b32_e32 v31, v0
	v_mov_b32_e32 v32, v0
	v_mov_b32_e32 v33, v0
	v_mov_b32_e32 v42, v0
	v_mov_b32_e32 v43, v0
	v_mov_b32_e32 v44, v0
	v_mov_b32_e32 v45, v0
	v_mov_b32_e32 v46, v0
	v_mov_b32_e32 v47, v0
	v_mov_b32_e32 v48, v0
	v_mov_b32_e32 v49, v0
	v_mov_b32_e32 v58, v0
	v_mov_b32_e32 v59, v0
	v_mov_b32_e32 v60, v0
	v_mov_b32_e32 v61, v0
	v_mov_b32_e32 v62, v0
	v_mov_b32_e32 v63, v0
	v_mov_b32_e32 v64, v0
	v_mov_b32_e32 v65, v0
	v_mov_b32_e32 v66, v0
	v_mov_b32_e32 v67, v0
	v_mov_b32_e32 v68, v0
	v_mov_b32_e32 v69, v0
	v_mov_b32_e32 v70, v0
	v_mov_b32_e32 v71, v0
	v_mov_b32_e32 v72, v0
	v_mov_b32_e32 v73, v0
	v_mov_b32_e32 v82, v0
	v_mov_b32_e32 v83, v0
	v_mov_b32_e32 v84, v0
	v_mov_b32_e32 v85, v0
	v_mov_b32_e32 v86, v0
	v_mov_b32_e32 v87, v0
	v_mov_b32_e32 v88, v0
	v_mov_b32_e32 v89, v0
	v_mov_b32_e32 v98, v0
	v_mov_b32_e32 v99, v0
	v_mov_b32_e32 v100, v0
	v_mov_b32_e32 v101, v0
	v_mov_b32_e32 v102, v0
	v_mov_b32_e32 v103, v0
	v_mov_b32_e32 v104, v0
	v_mov_b32_e32 v105, v0
	v_mov_b32_e32 v114, v0
	v_mov_b32_e32 v115, v0
	v_mov_b32_e32 v116, v0
	v_mov_b32_e32 v117, v0
	v_mov_b32_e32 v118, v0
	v_mov_b32_e32 v119, v0
	v_mov_b32_e32 v120, v0
	v_mov_b32_e32 v121, v0
	v_mov_b32_e32 v74, v0
	v_mov_b32_e32 v75, v0
	v_mov_b32_e32 v76, v0
	v_mov_b32_e32 v77, v0
	v_mov_b32_e32 v78, v0
	v_mov_b32_e32 v79, v0
	v_mov_b32_e32 v80, v0
	v_mov_b32_e32 v81, v0
	v_mov_b32_e32 v90, v0
	v_mov_b32_e32 v91, v0
	v_mov_b32_e32 v92, v0
	v_mov_b32_e32 v93, v0
	v_mov_b32_e32 v94, v0
	v_mov_b32_e32 v95, v0
	v_mov_b32_e32 v96, v0
	v_mov_b32_e32 v97, v0
	v_mov_b32_e32 v106, v0
	v_mov_b32_e32 v107, v0
	v_mov_b32_e32 v108, v0
	v_mov_b32_e32 v109, v0
	v_mov_b32_e32 v110, v0
	v_mov_b32_e32 v111, v0
	v_mov_b32_e32 v112, v0
	v_mov_b32_e32 v113, v0
	v_mov_b32_e32 v126, v0
	v_mov_b32_e32 v127, v0
	v_mov_b32_e32 v128, v0
	v_mov_b32_e32 v129, v0
	v_mov_b32_e32 v122, v0
	v_mov_b32_e32 v123, v0
	v_mov_b32_e32 v124, v0
	v_mov_b32_e32 v125, v0
	s_nop 0
	s_nop 0
	s_nop 0
	s_nop 0
	s_nop 0
	s_nop 0
	s_nop 0
	s_nop 0
	s_nop 0
	s_nop 0
	s_nop 0
	s_nop 0
	s_nop 0
	s_nop 0
	s_nop 0
	s_nop 0
	s_nop 0
	s_nop 0
	s_nop 0
	s_nop 0
	s_nop 0
	s_nop 0
; #define PG8_STAGE(bufoff, gbase, voff) do { _Pragma("unroll") for (int _i = 0; _i < 2; ++_i) \
;         __builtin_amdgcn_global_load_lds((const unsigned*)((const char*)(gbase) + (voff)[_i]), (LAS unsigned*)(lds + (bufoff) + ldsw + _i * 8192), 16, 0, 0); } while (0)
; #define PG8_LDA(dst, b, h) do { _Pragma("unroll") for (int m = 0; m < 4; ++m) _Pragma("unroll") for (int k = 0; k < 2; ++k) dst[m][k] = *(const LAS bf16x8*)(lds + PG8_SA(b, h) + aoff + m * 2048 + k * 1024); } while (0)
; #define PG8_LDB(dst, b, h) do { _Pragma("unroll") for (int n = 0; n < 2; ++n) _Pragma("unroll") for (int k = 0; k < 2; ++k) dst[n][k] = *(const LAS bf16x8*)(lds + PG8_SB(b, h) + boff + n * 2048 + k * 1024); } while (0)
; #define PG8_MMA(ai, bj, At, Bt) do { __builtin_amdgcn_s_setprio(1); _Pragma("unroll") for (int m = 0; m < 4; ++m) _Pragma("unroll") for (int n = 0; n < 2; ++n) _Pragma("unroll") for (int k = 0; k < 2; ++k) \
;         acc[ai][bj][m][n] = __builtin_amdgcn_mfma_f32_16x16x32_bf16(Bt[n][k], At[m][k], acc[ai][bj][m][n], 0, 0, 0); __builtin_amdgcn_s_setprio(0); } while (0)
; #define PG8_WAIT_L(n) asm volatile("s_waitcnt lgkmcnt(" #n ")" ::: "memory")
; #define PG8_BAR __builtin_amdgcn_s_barrier()
; #define PG8_SCHED __builtin_amdgcn_sched_barrier(0)
; template <class Epi>
; __device__ __forceinline__ void gemm_phase(LAS unsigned char* lds, const Gemm g, const Epi& E) {
;     ...
;             PG8_LDB(B0, 0, 0); PG8_SCHED; PG8_LDA(At, 0, 0); PG8_STAGE(PG8_SA(1, 1), a1 + hstep, voffA);
;             PG8_WAIT_L(8); PG8_BAR; PG8_WAIT_L(0); PG8_MMA(0, 0, At, B0); PG8_BAR; PG8_SCHED;
;             PG8_LDB(B1, 0, 1); PG8_STAGE(PG8_SB(0, 0), b2, voffB);
;             PG8_BAR; PG8_WAIT_L(0); PG8_MMA(0, 1, At, B1); PG8_BAR;
;             PG8_LDA(At, 0, 1); PG8_STAGE(PG8_SA(0, 0), a2, voffA);
;             PG8_BAR; PG8_WAIT_L(0); PG8_MMA(1, 0, At, B0); PG8_BAR; PG8_SCHED;
;             PG8_STAGE(PG8_SB(0, 1), b2 + hstep, voffB);
.LBB0_1112:
	s_add_i32 s84, s46, 2
	s_add_u32 s48, s44, 0x80
	s_addc_u32 s47, s45, 0
	s_add_i32 s85, 0, 0x10000
	v_add_u32_e32 v145, s85, v143
	ds_read_b128 v[146:149], v145
	ds_read_b128 v[150:153], v145 offset:1024
	ds_read_b128 v[154:157], v145 offset:2048
	ds_read_b128 v[158:161], v145 offset:3072
	s_cmp_eq_u32 s58, s46
	s_cselect_b32 s46, s0, s48
	s_cselect_b32 s47, s1, s47
	s_cselect_b32 s49, s39, s83
	s_cselect_b32 s48, s38, s82
	v_lshl_add_u64 v[206:207], s[44:45], 0, v[138:139]
	s_add_i32 m0, s50, 0xc000
	ds_read_b128 v[162:165], v144
	ds_read_b128 v[166:169], v144 offset:1024
	ds_read_b128 v[170:173], v144 offset:2048
	ds_read_b128 v[174:177], v144 offset:3072
	ds_read_b128 v[186:189], v144 offset:4096
	ds_read_b128 v[194:197], v144 offset:5120
	ds_read_b128 v[198:201], v144 offset:6144
	ds_read_b128 v[202:205], v144 offset:7168
	global_load_lds_dwordx4 v[206:207], off
	v_lshl_add_u64 v[206:207], s[44:45], 0, v[140:141]
	s_add_i32 m0, s50, 0xe000
	s_nop 0
	global_load_lds_dwordx4 v[206:207], off
	s_waitcnt lgkmcnt(8)
	s_barrier
	s_waitcnt lgkmcnt(0)
	s_setprio 1
	s_waitcnt lgkmcnt(0)
	v_mfma_f32_16x16x32_bf16 v[122:125], v[146:149], v[162:165], v[122:125]
	v_mfma_f32_16x16x32_bf16 v[126:129], v[154:157], v[162:165], v[126:129]
	v_mfma_f32_16x16x32_bf16 v[110:113], v[146:149], v[170:173], v[110:113]
	v_mfma_f32_16x16x32_bf16 v[106:109], v[154:157], v[170:173], v[106:109]
	v_mfma_f32_16x16x32_bf16 v[94:97], v[146:149], v[186:189], v[94:97]
	v_mfma_f32_16x16x32_bf16 v[90:93], v[154:157], v[186:189], v[90:93]
	v_mfma_f32_16x16x32_bf16 v[78:81], v[146:149], v[198:201], v[78:81]
	v_mfma_f32_16x16x32_bf16 v[74:77], v[154:157], v[198:201], v[74:77]
	v_mfma_f32_16x16x32_bf16 v[122:125], v[150:153], v[166:169], v[122:125]
	v_mfma_f32_16x16x32_bf16 v[126:129], v[158:161], v[166:169], v[126:129]
	v_mfma_f32_16x16x32_bf16 v[110:113], v[150:153], v[174:177], v[110:113]
	v_mfma_f32_16x16x32_bf16 v[106:109], v[158:161], v[174:177], v[106:109]
	v_mfma_f32_16x16x32_bf16 v[94:97], v[150:153], v[194:197], v[94:97]
	v_mfma_f32_16x16x32_bf16 v[90:93], v[158:161], v[194:197], v[90:93]
	v_mfma_f32_16x16x32_bf16 v[78:81], v[150:153], v[202:205], v[78:81]
	v_mfma_f32_16x16x32_bf16 v[74:77], v[158:161], v[202:205], v[74:77]
	s_setprio 0
	s_barrier
	s_add_i32 s86, 0, 0x14000
	s_add_i32 s85, s85, s25
	v_add_u32_e32 v145, s86, v143
	v_lshl_add_u64 v[228:229], s[48:49], 0, v[132:133]
	s_mov_b32 m0, s85
	ds_read_b128 v[206:209], v145
	ds_read_b128 v[210:213], v145 offset:1024
	ds_read_b128 v[220:223], v145 offset:2048
	ds_read_b128 v[224:227], v145 offset:3072
	global_load_lds_dwordx4 v[228:229], off
	v_lshl_add_u64 v[230:231], s[48:49], 0, v[136:137]
	s_add_i32 m0, s85, 0x2000
	s_nop 0
	global_load_lds_dwordx4 v[230:231], off
	s_barrier
	s_waitcnt lgkmcnt(0)
	s_setprio 1
	s_waitcnt lgkmcnt(0)
	v_mfma_f32_16x16x32_bf16 v[118:121], v[206:209], v[162:165], v[118:121]
	v_mfma_f32_16x16x32_bf16 v[114:117], v[220:223], v[162:165], v[114:117]
	v_mfma_f32_16x16x32_bf16 v[102:105], v[206:209], v[170:173], v[102:105]
	v_mfma_f32_16x16x32_bf16 v[98:101], v[220:223], v[170:173], v[98:101]
	v_mfma_f32_16x16x32_bf16 v[86:89], v[206:209], v[186:189], v[86:89]
	v_mfma_f32_16x16x32_bf16 v[82:85], v[220:223], v[186:189], v[82:85]
	v_mfma_f32_16x16x32_bf16 v[70:73], v[206:209], v[198:201], v[70:73]
	v_mfma_f32_16x16x32_bf16 v[66:69], v[220:223], v[198:201], v[66:69]
	v_mfma_f32_16x16x32_bf16 v[118:121], v[210:213], v[166:169], v[118:121]
	v_mfma_f32_16x16x32_bf16 v[114:117], v[224:227], v[166:169], v[114:117]
	v_mfma_f32_16x16x32_bf16 v[102:105], v[210:213], v[174:177], v[102:105]
	v_mfma_f32_16x16x32_bf16 v[98:101], v[224:227], v[174:177], v[98:101]
	v_mfma_f32_16x16x32_bf16 v[86:89], v[210:213], v[194:197], v[86:89]
	v_mfma_f32_16x16x32_bf16 v[82:85], v[224:227], v[194:197], v[82:85]
	v_mfma_f32_16x16x32_bf16 v[70:73], v[210:213], v[202:205], v[70:73]
	v_mfma_f32_16x16x32_bf16 v[66:69], v[224:227], v[202:205], v[66:69]
	s_setprio 0
	s_mov_b32 m0, s50
	v_lshl_add_u64 v[232:233], s[46:47], 0, v[130:131]
	s_barrier
	ds_read_b128 v[162:165], v144 offset:16384
	ds_read_b128 v[166:169], v144 offset:17408
	ds_read_b128 v[170:173], v144 offset:18432
	ds_read_b128 v[174:177], v144 offset:19456
	ds_read_b128 v[186:189], v144 offset:20480
	ds_read_b128 v[194:197], v144 offset:21504
	ds_read_b128 v[198:201], v144 offset:22528
	ds_read_b128 v[202:205], v144 offset:23552
	global_load_lds_dwordx4 v[232:233], off
	v_lshl_add_u64 v[234:235], s[46:47], 0, v[134:135]
	s_mov_b32 m0, s51
	s_nop 0
	global_load_lds_dwordx4 v[234:235], off
	s_barrier
	s_waitcnt lgkmcnt(0)
	s_setprio 1
	s_waitcnt lgkmcnt(0)
	v_mfma_f32_16x16x32_bf16 v[62:65], v[146:149], v[162:165], v[62:65]
	v_mfma_f32_16x16x32_bf16 v[58:61], v[154:157], v[162:165], v[58:61]
	v_mfma_f32_16x16x32_bf16 v[46:49], v[146:149], v[170:173], v[46:49]
	v_mfma_f32_16x16x32_bf16 v[42:45], v[154:157], v[170:173], v[42:45]
	v_mfma_f32_16x16x32_bf16 v[30:33], v[146:149], v[186:189], v[30:33]
	v_mfma_f32_16x16x32_bf16 v[26:29], v[154:157], v[186:189], v[26:29]
	v_mfma_f32_16x16x32_bf16 v[14:17], v[146:149], v[198:201], v[14:17]
	v_mfma_f32_16x16x32_bf16 v[8:11], v[154:157], v[198:201], v[8:11]
	v_mfma_f32_16x16x32_bf16 v[62:65], v[150:153], v[166:169], v[62:65]
	v_mfma_f32_16x16x32_bf16 v[58:61], v[158:161], v[166:169], v[58:61]
	v_mfma_f32_16x16x32_bf16 v[46:49], v[150:153], v[174:177], v[46:49]
	v_mfma_f32_16x16x32_bf16 v[42:45], v[158:161], v[174:177], v[42:45]
	v_mfma_f32_16x16x32_bf16 v[30:33], v[150:153], v[194:197], v[30:33]
	v_mfma_f32_16x16x32_bf16 v[26:29], v[158:161], v[194:197], v[26:29]
	v_mfma_f32_16x16x32_bf16 v[14:17], v[150:153], v[202:205], v[14:17]
	v_mfma_f32_16x16x32_bf16 v[8:11], v[158:161], v[202:205], v[8:11]
	s_setprio 0
	s_barrier
; #define PG8_STAGE(bufoff, gbase, voff) do { _Pragma("unroll") for (int _i = 0; _i < 2; ++_i) \
;         __builtin_amdgcn_global_load_lds((const unsigned*)((const char*)(gbase) + (voff)[_i]), (LAS unsigned*)(lds + (bufoff) + ldsw + _i * 8192), 16, 0, 0); } while (0)
; #define PG8_LDA(dst, b, h) do { _Pragma("unroll") for (int m = 0; m < 4; ++m) _Pragma("unroll") for (int k = 0; k < 2; ++k) dst[m][k] = *(const LAS bf16x8*)(lds + PG8_SA(b, h) + aoff + m * 2048 + k * 1024); } while (0)
; #define PG8_LDB(dst, b, h) do { _Pragma("unroll") for (int n = 0; n < 2; ++n) _Pragma("unroll") for (int k = 0; k < 2; ++k) dst[n][k] = *(const LAS bf16x8*)(lds + PG8_SB(b, h) + boff + n * 2048 + k * 1024); } while (0)
; #define PG8_MMA(ai, bj, At, Bt) do { __builtin_amdgcn_s_setprio(1); _Pragma("unroll") for (int m = 0; m < 4; ++m) _Pragma("unroll") for (int n = 0; n < 2; ++n) _Pragma("unroll") for (int k = 0; k < 2; ++k) \
;         acc[ai][bj][m][n] = __builtin_amdgcn_mfma_f32_16x16x32_bf16(Bt[n][k], At[m][k], acc[ai][bj][m][n], 0, 0, 0); __builtin_amdgcn_s_setprio(0); } while (0)
; #define PG8_WAIT_V(n) asm volatile("s_waitcnt vmcnt(" #n ")" ::: "memory")
; #define PG8_WAIT_L(n) asm volatile("s_waitcnt lgkmcnt(" #n ")" ::: "memory")
; #define PG8_BAR __builtin_amdgcn_s_barrier()
; #define PG8_SCHED __builtin_amdgcn_sched_barrier(0)
; template <class Epi>
; __device__ __forceinline__ void gemm_phase(LAS unsigned char* lds, const Gemm g, const Epi& E) {
;     ...
;             PG8_STAGE(PG8_SB(0, 1), b2 + hstep, voffB);
;             PG8_WAIT_V(6); PG8_BAR; PG8_MMA(1, 1, At, B1); PG8_BAR;
;             PG8_LDB(B0, 1, 0); PG8_SCHED; PG8_LDA(At, 1, 0); PG8_STAGE(PG8_SA(0, 1), a2 + hstep, voffA);
;             PG8_WAIT_L(8); PG8_BAR; PG8_WAIT_L(0); PG8_MMA(0, 0, At, B0); PG8_BAR; PG8_SCHED;
;             PG8_LDB(B1, 1, 1); PG8_STAGE(PG8_SB(1, 0), b3, voffB);
;             PG8_BAR; PG8_WAIT_L(0); PG8_MMA(0, 1, At, B1); PG8_BAR;
;             PG8_LDA(At, 1, 1); PG8_STAGE(PG8_SA(1, 0), a3, voffA);
;             PG8_BAR; PG8_WAIT_L(0); PG8_MMA(1, 0, At, B0); PG8_BAR; PG8_SCHED;
	s_add_u32 s48, s48, s26
	s_addc_u32 s49, s49, s27
	s_add_i32 s85, s86, s25
	v_lshl_add_u64 v[236:237], s[48:49], 0, v[132:133]
	s_mov_b32 m0, s85
	v_lshl_add_u64 v[238:239], s[48:49], 0, v[136:137]
	global_load_lds_dwordx4 v[236:237], off
	s_add_i32 m0, s85, 0x2000
	s_nop 0
	global_load_lds_dwordx4 v[238:239], off
	s_waitcnt vmcnt(6)
	s_barrier
	s_setprio 1
	v_mfma_f32_16x16x32_bf16 v[54:57], v[206:209], v[162:165], v[54:57]
	v_mfma_f32_16x16x32_bf16 v[50:53], v[220:223], v[162:165], v[50:53]
	v_mfma_f32_16x16x32_bf16 v[38:41], v[206:209], v[170:173], v[38:41]
	v_mfma_f32_16x16x32_bf16 v[34:37], v[220:223], v[170:173], v[34:37]
	v_mfma_f32_16x16x32_bf16 v[22:25], v[206:209], v[186:189], v[22:25]
	v_mfma_f32_16x16x32_bf16 v[18:21], v[220:223], v[186:189], v[18:21]
	v_mfma_f32_16x16x32_bf16 v[4:7], v[206:209], v[198:201], v[4:7]
	v_mfma_f32_16x16x32_bf16 v[0:3], v[220:223], v[198:201], v[0:3]
	v_mfma_f32_16x16x32_bf16 v[54:57], v[210:213], v[166:169], v[54:57]
	v_mfma_f32_16x16x32_bf16 v[50:53], v[224:227], v[166:169], v[50:53]
	v_mfma_f32_16x16x32_bf16 v[38:41], v[210:213], v[174:177], v[38:41]
	v_mfma_f32_16x16x32_bf16 v[34:37], v[224:227], v[174:177], v[34:37]
	v_mfma_f32_16x16x32_bf16 v[22:25], v[210:213], v[194:197], v[22:25]
	v_mfma_f32_16x16x32_bf16 v[18:21], v[224:227], v[194:197], v[18:21]
	v_mfma_f32_16x16x32_bf16 v[4:7], v[210:213], v[202:205], v[4:7]
	v_mfma_f32_16x16x32_bf16 v[0:3], v[224:227], v[202:205], v[0:3]
	s_setprio 0
	s_add_i32 s48, 0, 0x18000
	v_add_u32_e32 v145, s48, v143
	s_barrier
	ds_read_b128 v[146:149], v145
	ds_read_b128 v[150:153], v145 offset:1024
	ds_read_b128 v[154:157], v145 offset:2048
	ds_read_b128 v[158:161], v145 offset:3072
	s_add_u32 s46, s46, s26
	s_addc_u32 s47, s47, s27
	s_mov_b32 m0, s52
	v_lshl_add_u64 v[206:207], s[46:47], 0, v[130:131]
	ds_read_b128 v[162:165], v144 offset:32768
	ds_read_b128 v[166:169], v144 offset:33792
	ds_read_b128 v[170:173], v144 offset:34816
	ds_read_b128 v[174:177], v144 offset:35840
	ds_read_b128 v[186:189], v144 offset:36864
	ds_read_b128 v[194:197], v144 offset:37888
	ds_read_b128 v[198:201], v144 offset:38912
	ds_read_b128 v[202:205], v144 offset:39936
	global_load_lds_dwordx4 v[206:207], off
	v_lshl_add_u64 v[206:207], s[46:47], 0, v[134:135]
	s_mov_b32 m0, s53
	s_nop 0
	global_load_lds_dwordx4 v[206:207], off
	s_waitcnt lgkmcnt(8)
	s_barrier
	s_waitcnt lgkmcnt(0)
	s_setprio 1
	s_waitcnt lgkmcnt(0)
	v_mfma_f32_16x16x32_bf16 v[122:125], v[146:149], v[162:165], v[122:125]
	v_mfma_f32_16x16x32_bf16 v[126:129], v[154:157], v[162:165], v[126:129]
	v_mfma_f32_16x16x32_bf16 v[110:113], v[146:149], v[170:173], v[110:113]
	v_mfma_f32_16x16x32_bf16 v[106:109], v[154:157], v[170:173], v[106:109]
	v_mfma_f32_16x16x32_bf16 v[94:97], v[146:149], v[186:189], v[94:97]
	v_mfma_f32_16x16x32_bf16 v[90:93], v[154:157], v[186:189], v[90:93]
	v_mfma_f32_16x16x32_bf16 v[78:81], v[146:149], v[198:201], v[78:81]
	v_mfma_f32_16x16x32_bf16 v[74:77], v[154:157], v[198:201], v[74:77]
	v_mfma_f32_16x16x32_bf16 v[122:125], v[150:153], v[166:169], v[122:125]
	v_mfma_f32_16x16x32_bf16 v[126:129], v[158:161], v[166:169], v[126:129]
	v_mfma_f32_16x16x32_bf16 v[110:113], v[150:153], v[174:177], v[110:113]
	v_mfma_f32_16x16x32_bf16 v[106:109], v[158:161], v[174:177], v[106:109]
	v_mfma_f32_16x16x32_bf16 v[94:97], v[150:153], v[194:197], v[94:97]
	v_mfma_f32_16x16x32_bf16 v[90:93], v[158:161], v[194:197], v[90:93]
	v_mfma_f32_16x16x32_bf16 v[78:81], v[150:153], v[202:205], v[78:81]
	v_mfma_f32_16x16x32_bf16 v[74:77], v[158:161], v[202:205], v[74:77]
	s_setprio 0
	s_barrier
	s_add_i32 s46, 0, 0x1c000
	s_add_i32 s47, s48, s25
	v_add_u32_e32 v145, s46, v143
	v_lshl_add_u64 v[228:229], v[228:229], 0, s[20:21]
	s_mov_b32 m0, s47
	ds_read_b128 v[206:209], v145
	ds_read_b128 v[210:213], v145 offset:1024
	ds_read_b128 v[220:223], v145 offset:2048
	ds_read_b128 v[224:227], v145 offset:3072
	global_load_lds_dwordx4 v[228:229], off
	v_lshl_add_u64 v[228:229], v[230:231], 0, s[20:21]
	s_add_i32 m0, s47, 0x2000
	s_nop 0
	global_load_lds_dwordx4 v[228:229], off
	s_barrier
; #define PG8_STAGE(bufoff, gbase, voff) do { _Pragma("unroll") for (int _i = 0; _i < 2; ++_i) \
;         __builtin_amdgcn_global_load_lds((const unsigned*)((const char*)(gbase) + (voff)[_i]), (LAS unsigned*)(lds + (bufoff) + ldsw + _i * 8192), 16, 0, 0); } while (0)
; #define PG8_MMA(ai, bj, At, Bt) do { __builtin_amdgcn_s_setprio(1); _Pragma("unroll") for (int m = 0; m < 4; ++m) _Pragma("unroll") for (int n = 0; n < 2; ++n) _Pragma("unroll") for (int k = 0; k < 2; ++k) \
;         acc[ai][bj][m][n] = __builtin_amdgcn_mfma_f32_16x16x32_bf16(Bt[n][k], At[m][k], acc[ai][bj][m][n], 0, 0, 0); __builtin_amdgcn_s_setprio(0); } while (0)
; #define PG8_WAIT_V(n) asm volatile("s_waitcnt vmcnt(" #n ")" ::: "memory")
; #define PG8_WAIT_L(n) asm volatile("s_waitcnt lgkmcnt(" #n ")" ::: "memory")
; #define PG8_BAR __builtin_amdgcn_s_barrier()
; #define PG8_SCHED __builtin_amdgcn_sched_barrier(0)
; template <class Epi>
; __device__ __forceinline__ void gemm_phase(LAS unsigned char* lds, const Gemm g, const Epi& E) {
;     ...
;             PG8_BAR; PG8_WAIT_L(0); PG8_MMA(1, 0, At, B0); PG8_BAR; PG8_SCHED;
;             PG8_STAGE(PG8_SB(1, 1), b3 + hstep, voffB);
;             PG8_WAIT_V(6); PG8_BAR; PG8_MMA(1, 1, At, B1); PG8_BAR;
;         }
	s_waitcnt lgkmcnt(0)
	s_setprio 1
	s_waitcnt lgkmcnt(0)
	v_mfma_f32_16x16x32_bf16 v[118:121], v[206:209], v[162:165], v[118:121]
	v_mfma_f32_16x16x32_bf16 v[114:117], v[220:223], v[162:165], v[114:117]
	v_mfma_f32_16x16x32_bf16 v[102:105], v[206:209], v[170:173], v[102:105]
	v_mfma_f32_16x16x32_bf16 v[98:101], v[220:223], v[170:173], v[98:101]
	v_mfma_f32_16x16x32_bf16 v[86:89], v[206:209], v[186:189], v[86:89]
	v_mfma_f32_16x16x32_bf16 v[82:85], v[220:223], v[186:189], v[82:85]
	v_mfma_f32_16x16x32_bf16 v[70:73], v[206:209], v[198:201], v[70:73]
	v_mfma_f32_16x16x32_bf16 v[66:69], v[220:223], v[198:201], v[66:69]
	v_mfma_f32_16x16x32_bf16 v[118:121], v[210:213], v[166:169], v[118:121]
	v_mfma_f32_16x16x32_bf16 v[114:117], v[224:227], v[166:169], v[114:117]
	v_mfma_f32_16x16x32_bf16 v[102:105], v[210:213], v[174:177], v[102:105]
	v_mfma_f32_16x16x32_bf16 v[98:101], v[224:227], v[174:177], v[98:101]
	v_mfma_f32_16x16x32_bf16 v[86:89], v[210:213], v[194:197], v[86:89]
	v_mfma_f32_16x16x32_bf16 v[82:85], v[224:227], v[194:197], v[82:85]
	v_mfma_f32_16x16x32_bf16 v[70:73], v[210:213], v[202:205], v[70:73]
	v_mfma_f32_16x16x32_bf16 v[66:69], v[224:227], v[202:205], v[66:69]
	s_setprio 0
	s_mov_b32 m0, s54
	v_lshl_add_u64 v[228:229], v[232:233], 0, s[20:21]
	s_barrier
	ds_read_b128 v[162:165], v144 offset:49152
	ds_read_b128 v[166:169], v144 offset:50176
	ds_read_b128 v[170:173], v144 offset:51200
	ds_read_b128 v[174:177], v144 offset:52224
	ds_read_b128 v[186:189], v144 offset:53248
	ds_read_b128 v[194:197], v144 offset:54272
	ds_read_b128 v[198:201], v144 offset:55296
	ds_read_b128 v[202:205], v144 offset:56320
	global_load_lds_dwordx4 v[228:229], off
	v_lshl_add_u64 v[228:229], v[234:235], 0, s[20:21]
	s_mov_b32 m0, s55
	s_nop 0
	global_load_lds_dwordx4 v[228:229], off
	s_barrier
	s_waitcnt lgkmcnt(0)
	s_setprio 1
	s_waitcnt lgkmcnt(0)
	v_mfma_f32_16x16x32_bf16 v[62:65], v[146:149], v[162:165], v[62:65]
	v_mfma_f32_16x16x32_bf16 v[58:61], v[154:157], v[162:165], v[58:61]
	v_mfma_f32_16x16x32_bf16 v[46:49], v[146:149], v[170:173], v[46:49]
	v_mfma_f32_16x16x32_bf16 v[42:45], v[154:157], v[170:173], v[42:45]
	v_mfma_f32_16x16x32_bf16 v[30:33], v[146:149], v[186:189], v[30:33]
	v_mfma_f32_16x16x32_bf16 v[26:29], v[154:157], v[186:189], v[26:29]
	v_mfma_f32_16x16x32_bf16 v[14:17], v[146:149], v[198:201], v[14:17]
	v_mfma_f32_16x16x32_bf16 v[8:11], v[154:157], v[198:201], v[8:11]
	v_mfma_f32_16x16x32_bf16 v[62:65], v[150:153], v[166:169], v[62:65]
	v_mfma_f32_16x16x32_bf16 v[58:61], v[158:161], v[166:169], v[58:61]
	v_mfma_f32_16x16x32_bf16 v[46:49], v[150:153], v[174:177], v[46:49]
	v_mfma_f32_16x16x32_bf16 v[42:45], v[158:161], v[174:177], v[42:45]
	v_mfma_f32_16x16x32_bf16 v[30:33], v[150:153], v[194:197], v[30:33]
	v_mfma_f32_16x16x32_bf16 v[26:29], v[158:161], v[194:197], v[26:29]
	v_mfma_f32_16x16x32_bf16 v[14:17], v[150:153], v[202:205], v[14:17]
	v_mfma_f32_16x16x32_bf16 v[8:11], v[158:161], v[202:205], v[8:11]
	s_setprio 0
	s_barrier
	s_add_i32 s46, s46, s25
	v_lshl_add_u64 v[146:147], v[236:237], 0, s[20:21]
	s_mov_b32 m0, s46
	s_nop 0
	global_load_lds_dwordx4 v[146:147], off
	v_lshl_add_u64 v[146:147], v[238:239], 0, s[20:21]
	s_add_i32 m0, s46, 0x2000
	s_nop 0
	global_load_lds_dwordx4 v[146:147], off
	s_waitcnt vmcnt(6)
	s_barrier
	s_setprio 1
	v_mfma_f32_16x16x32_bf16 v[54:57], v[206:209], v[162:165], v[54:57]
	v_mfma_f32_16x16x32_bf16 v[50:53], v[220:223], v[162:165], v[50:53]
	v_mfma_f32_16x16x32_bf16 v[38:41], v[206:209], v[170:173], v[38:41]
	v_mfma_f32_16x16x32_bf16 v[34:37], v[220:223], v[170:173], v[34:37]
	v_mfma_f32_16x16x32_bf16 v[22:25], v[206:209], v[186:189], v[22:25]
	v_mfma_f32_16x16x32_bf16 v[18:21], v[220:223], v[186:189], v[18:21]
	v_mfma_f32_16x16x32_bf16 v[4:7], v[206:209], v[198:201], v[4:7]
	v_mfma_f32_16x16x32_bf16 v[0:3], v[220:223], v[198:201], v[0:3]
	v_mfma_f32_16x16x32_bf16 v[54:57], v[210:213], v[166:169], v[54:57]
	v_mfma_f32_16x16x32_bf16 v[50:53], v[224:227], v[166:169], v[50:53]
	v_mfma_f32_16x16x32_bf16 v[38:41], v[210:213], v[174:177], v[38:41]
	v_mfma_f32_16x16x32_bf16 v[34:37], v[224:227], v[174:177], v[34:37]
	v_mfma_f32_16x16x32_bf16 v[22:25], v[210:213], v[194:197], v[22:25]
	v_mfma_f32_16x16x32_bf16 v[18:21], v[224:227], v[194:197], v[18:21]
	v_mfma_f32_16x16x32_bf16 v[4:7], v[210:213], v[202:205], v[4:7]
	v_mfma_f32_16x16x32_bf16 v[0:3], v[224:227], v[202:205], v[0:3]
	s_setprio 0
	s_add_u32 s44, s44, 0x100
	s_addc_u32 s45, s45, 0
	s_add_u32 s82, s82, 0x100
	s_addc_u32 s83, s83, 0
	s_cmp_ge_i32 s84, s2
	s_mov_b32 s46, s84
	s_barrier
	s_cbranch_scc0 .LBB0_1112
	s_nop 0
	s_nop 0
	s_nop 0
	s_nop 0
	s_nop 0
	s_nop 0
	s_nop 0
	s_nop 0
	s_nop 0
	s_nop 0
	s_nop 0
	s_nop 0
	s_nop 0
	s_nop 0
	s_nop 0
	s_nop 0
	s_nop 0
	s_nop 0
	s_nop 0
	s_nop 0
	s_nop 0
	s_nop 0
	s_nop 0
	s_nop 0
	s_nop 0
	s_nop 0
	s_nop 0
	s_nop 0
	s_nop 0
	s_nop 0
	s_nop 0
	s_nop 0
	s_nop 0
	s_nop 0
	s_nop 0
	s_nop 0
	s_nop 0
	s_nop 0
	s_nop 0
	s_nop 0
	s_nop 0
	s_nop 0
	v_readlane_b32 s48, v254, 63
	v_readlane_b32 s49, v243, 0
	s_branch .LBB0_1099
